# speedup vs baseline: 1.0136x; 1.0016x over previous
.LBB0_213:
	s_mov_b64 s[38:39], s[54:55]
	ds_read_b128 v[148:151], v153
	ds_read_b128 v[158:161], v153 offset:1024
	ds_read_b128 v[162:165], v153 offset:2048
	ds_read_b128 v[166:169], v153 offset:3072
	ds_read_b128 v[170:173], v155
	ds_read_b128 v[174:177], v155 offset:1024
	ds_read_b128 v[182:185], v155 offset:2048
	ds_read_b128 v[186:189], v155 offset:3072
	s_add_u32 s17, s6, s38
	s_addc_u32 s25, s7, s39
	s_add_u32 s40, s17, 0x100
	s_addc_u32 s41, s25, 0
	s_add_u32 s38, s36, s38
	s_addc_u32 s39, s37, s39
	s_add_u32 s38, s38, 0x100
	s_addc_u32 s39, s39, 0
	s_cmp_eq_u32 s70, s3
	s_cselect_b32 s61, s31, s41
	s_cselect_b32 s60, s30, s40
	s_cselect_b32 s59, s35, s39
	s_cselect_b32 s58, s34, s38
	s_add_u32 s38, s17, 0x80080
	s_addc_u32 s39, s25, 0
	v_lshl_add_u64 v[140:141], s[38:39], 0, v[128:129]
	s_add_i32 m0, s19, 0xc000
	ds_read_b128 v[190:193], v157
	ds_read_b128 v[194:197], v157 offset:1024
	ds_read_b128 v[198:201], v157 offset:2048
	ds_read_b128 v[202:205], v157 offset:3072
	ds_read_b128 v[206:209], v157 offset:4096
	ds_read_b128 v[210:213], v157 offset:5120
	ds_read_b128 v[214:217], v157 offset:6144
	ds_read_b128 v[218:221], v157 offset:7168
	global_load_lds_dwordx4 v[140:141], off
	v_lshl_add_u64 v[140:141], s[38:39], 0, v[132:133]
	s_add_i32 m0, s19, 0xe000
	s_nop 0
	global_load_lds_dwordx4 v[140:141], off
	s_waitcnt vmcnt(8)
	s_waitcnt lgkmcnt(0)
	s_barrier
	s_setprio 1
	v_mfma_f32_16x16x32_bf16 v[124:127], v[148:151], v[190:193], v[124:127]
	v_mfma_f32_16x16x32_bf16 v[120:123], v[162:165], v[190:193], v[120:123]
	v_mfma_f32_16x16x32_bf16 v[108:111], v[148:151], v[198:201], v[108:111]
	v_mfma_f32_16x16x32_bf16 v[104:107], v[162:165], v[198:201], v[104:107]
	v_mfma_f32_16x16x32_bf16 v[92:95], v[148:151], v[206:209], v[92:95]
	v_mfma_f32_16x16x32_bf16 v[88:91], v[162:165], v[206:209], v[88:91]
	v_mfma_f32_16x16x32_bf16 v[76:79], v[148:151], v[214:217], v[76:79]
	v_mfma_f32_16x16x32_bf16 v[72:75], v[162:165], v[214:217], v[72:75]
	v_mfma_f32_16x16x32_bf16 v[124:127], v[158:161], v[194:197], v[124:127]
	v_mfma_f32_16x16x32_bf16 v[120:123], v[166:169], v[194:197], v[120:123]
	v_mfma_f32_16x16x32_bf16 v[108:111], v[158:161], v[202:205], v[108:111]
	v_mfma_f32_16x16x32_bf16 v[104:107], v[166:169], v[202:205], v[104:107]
	v_mfma_f32_16x16x32_bf16 v[92:95], v[158:161], v[210:213], v[92:95]
	v_mfma_f32_16x16x32_bf16 v[88:91], v[166:169], v[210:213], v[88:91]
	v_mfma_f32_16x16x32_bf16 v[76:79], v[158:161], v[218:221], v[76:79]
	v_mfma_f32_16x16x32_bf16 v[72:75], v[166:169], v[218:221], v[72:75]
	s_setprio 0
	s_setprio 1
	v_mfma_f32_16x16x32_bf16 v[116:119], v[170:173], v[190:193], v[116:119]
	v_mfma_f32_16x16x32_bf16 v[112:115], v[182:185], v[190:193], v[112:115]
	v_mfma_f32_16x16x32_bf16 v[100:103], v[170:173], v[198:201], v[100:103]
	v_mfma_f32_16x16x32_bf16 v[96:99], v[182:185], v[198:201], v[96:99]
	v_mfma_f32_16x16x32_bf16 v[84:87], v[170:173], v[206:209], v[84:87]
	v_mfma_f32_16x16x32_bf16 v[80:83], v[182:185], v[206:209], v[80:83]
	v_mfma_f32_16x16x32_bf16 v[68:71], v[170:173], v[214:217], v[68:71]
	v_mfma_f32_16x16x32_bf16 v[64:67], v[182:185], v[214:217], v[64:67]
	v_mfma_f32_16x16x32_bf16 v[116:119], v[174:177], v[194:197], v[116:119]
	v_mfma_f32_16x16x32_bf16 v[112:115], v[186:189], v[194:197], v[112:115]
	v_mfma_f32_16x16x32_bf16 v[100:103], v[174:177], v[202:205], v[100:103]
	v_mfma_f32_16x16x32_bf16 v[96:99], v[186:189], v[202:205], v[96:99]
	v_mfma_f32_16x16x32_bf16 v[84:87], v[174:177], v[210:213], v[84:87]
	v_mfma_f32_16x16x32_bf16 v[80:83], v[186:189], v[210:213], v[80:83]
	v_mfma_f32_16x16x32_bf16 v[68:71], v[174:177], v[218:221], v[68:71]
	v_mfma_f32_16x16x32_bf16 v[64:67], v[186:189], v[218:221], v[64:67]
	s_setprio 0
	s_barrier
	s_add_i32 s17, s71, s18
	v_lshl_add_u64 v[140:141], s[58:59], 0, v[130:131]
	s_mov_b32 m0, s17
	ds_read_b128 v[190:193], v157 offset:16384
	ds_read_b128 v[194:197], v157 offset:17408
	ds_read_b128 v[198:201], v157 offset:18432
	ds_read_b128 v[202:205], v157 offset:19456
	ds_read_b128 v[206:209], v157 offset:20480
	ds_read_b128 v[210:213], v157 offset:21504
	ds_read_b128 v[214:217], v157 offset:22528
	ds_read_b128 v[218:221], v157 offset:23552
	global_load_lds_dwordx4 v[140:141], off
	s_add_i32 m0, s17, 0x2000
	s_add_u32 s38, s58, 0x80000
	v_lshl_add_u64 v[178:179], s[58:59], 0, v[134:135]
	s_addc_u32 s39, s59, 0
	s_add_i32 s17, s72, s18
	global_load_lds_dwordx4 v[178:179], off
	v_lshl_add_u64 v[222:223], s[38:39], 0, v[130:131]
	s_mov_b32 m0, s17
	v_lshl_add_u64 v[224:225], s[60:61], 0, v[132:133]
	global_load_lds_dwordx4 v[222:223], off
	v_lshl_add_u64 v[222:223], s[38:39], 0, v[134:135]
	s_add_i32 m0, s17, 0x2000
	s_nop 0
	global_load_lds_dwordx4 v[222:223], off
	v_lshl_add_u64 v[222:223], s[60:61], 0, v[128:129]
	s_mov_b32 m0, s19
	s_nop 0
	global_load_lds_dwordx4 v[222:223], off
	s_mov_b32 m0, s56
	s_nop 0
	global_load_lds_dwordx4 v[224:225], off
	s_waitcnt vmcnt(8)
	s_waitcnt lgkmcnt(0)
	s_barrier
	s_setprio 1
	v_mfma_f32_16x16x32_bf16 v[60:63], v[148:151], v[190:193], v[60:63]
	v_mfma_f32_16x16x32_bf16 v[56:59], v[162:165], v[190:193], v[56:59]
	v_mfma_f32_16x16x32_bf16 v[44:47], v[148:151], v[198:201], v[44:47]
	v_mfma_f32_16x16x32_bf16 v[40:43], v[162:165], v[198:201], v[40:43]
	v_mfma_f32_16x16x32_bf16 v[28:31], v[148:151], v[206:209], v[28:31]
	v_mfma_f32_16x16x32_bf16 v[24:27], v[162:165], v[206:209], v[24:27]
	v_mfma_f32_16x16x32_bf16 v[12:15], v[148:151], v[214:217], v[12:15]
	v_mfma_f32_16x16x32_bf16 v[8:11], v[162:165], v[214:217], v[8:11]
	v_mfma_f32_16x16x32_bf16 v[60:63], v[158:161], v[194:197], v[60:63]
	v_mfma_f32_16x16x32_bf16 v[56:59], v[166:169], v[194:197], v[56:59]
	v_mfma_f32_16x16x32_bf16 v[44:47], v[158:161], v[202:205], v[44:47]
	v_mfma_f32_16x16x32_bf16 v[40:43], v[166:169], v[202:205], v[40:43]
	v_mfma_f32_16x16x32_bf16 v[28:31], v[158:161], v[210:213], v[28:31]
	v_mfma_f32_16x16x32_bf16 v[24:27], v[166:169], v[210:213], v[24:27]
	v_mfma_f32_16x16x32_bf16 v[12:15], v[158:161], v[218:221], v[12:15]
	v_mfma_f32_16x16x32_bf16 v[8:11], v[166:169], v[218:221], v[8:11]
	s_setprio 0
	s_setprio 1
	v_mfma_f32_16x16x32_bf16 v[52:55], v[170:173], v[190:193], v[52:55]
	v_mfma_f32_16x16x32_bf16 v[48:51], v[182:185], v[190:193], v[48:51]
	v_mfma_f32_16x16x32_bf16 v[36:39], v[170:173], v[198:201], v[36:39]
	v_mfma_f32_16x16x32_bf16 v[32:35], v[182:185], v[198:201], v[32:35]
	v_mfma_f32_16x16x32_bf16 v[20:23], v[170:173], v[206:209], v[20:23]
	v_mfma_f32_16x16x32_bf16 v[16:19], v[182:185], v[206:209], v[16:19]
	v_mfma_f32_16x16x32_bf16 v[4:7], v[170:173], v[214:217], v[4:7]
	v_mfma_f32_16x16x32_bf16 v[0:3], v[182:185], v[214:217], v[0:3]
	v_mfma_f32_16x16x32_bf16 v[52:55], v[174:177], v[194:197], v[52:55]
	v_mfma_f32_16x16x32_bf16 v[48:51], v[186:189], v[194:197], v[48:51]
	v_mfma_f32_16x16x32_bf16 v[36:39], v[174:177], v[202:205], v[36:39]
	v_mfma_f32_16x16x32_bf16 v[32:35], v[186:189], v[202:205], v[32:35]
	v_mfma_f32_16x16x32_bf16 v[20:23], v[174:177], v[210:213], v[20:23]
	v_mfma_f32_16x16x32_bf16 v[16:19], v[186:189], v[210:213], v[16:19]
	v_mfma_f32_16x16x32_bf16 v[4:7], v[174:177], v[218:221], v[4:7]
	v_mfma_f32_16x16x32_bf16 v[0:3], v[186:189], v[218:221], v[0:3]
	s_setprio 0
	s_barrier
	s_add_i32 s17, 0, 0x18000
	v_add_u32_e32 v142, s17, v147
	s_add_i32 s25, 0, 0x1c000
	ds_read_b128 v[148:151], v142
	ds_read_b128 v[158:161], v142 offset:1024
	ds_read_b128 v[162:165], v142 offset:2048
	ds_read_b128 v[166:169], v142 offset:3072
	v_add_u32_e32 v142, s25, v147
	ds_read_b128 v[170:173], v142
	ds_read_b128 v[174:177], v142 offset:1024
	ds_read_b128 v[182:185], v142 offset:2048
	ds_read_b128 v[186:189], v142 offset:3072
	s_add_u32 s38, s60, 0x80000
	s_addc_u32 s39, s61, 0
	s_mov_b32 m0, s57
	v_lshl_add_u64 v[226:227], s[38:39], 0, v[128:129]
	ds_read_b128 v[190:193], v157 offset:32768
	ds_read_b128 v[194:197], v157 offset:33792
	ds_read_b128 v[198:201], v157 offset:34816
	ds_read_b128 v[202:205], v157 offset:35840
	ds_read_b128 v[206:209], v157 offset:36864
	ds_read_b128 v[210:213], v157 offset:37888
	ds_read_b128 v[214:217], v157 offset:38912
	ds_read_b128 v[218:221], v157 offset:39936
	global_load_lds_dwordx4 v[226:227], off
	v_lshl_add_u64 v[226:227], s[38:39], 0, v[132:133]
	s_mov_b32 m0, s62
	s_nop 0
	global_load_lds_dwordx4 v[226:227], off
	s_waitcnt vmcnt(8)
	s_waitcnt lgkmcnt(0)
	s_barrier
	s_setprio 1
	v_mfma_f32_16x16x32_bf16 v[124:127], v[148:151], v[190:193], v[124:127]
	v_mfma_f32_16x16x32_bf16 v[120:123], v[162:165], v[190:193], v[120:123]
	v_mfma_f32_16x16x32_bf16 v[108:111], v[148:151], v[198:201], v[108:111]
	v_mfma_f32_16x16x32_bf16 v[104:107], v[162:165], v[198:201], v[104:107]
	v_mfma_f32_16x16x32_bf16 v[92:95], v[148:151], v[206:209], v[92:95]
	v_mfma_f32_16x16x32_bf16 v[88:91], v[162:165], v[206:209], v[88:91]
	v_mfma_f32_16x16x32_bf16 v[76:79], v[148:151], v[214:217], v[76:79]
	v_mfma_f32_16x16x32_bf16 v[72:75], v[162:165], v[214:217], v[72:75]
	v_mfma_f32_16x16x32_bf16 v[124:127], v[158:161], v[194:197], v[124:127]
	v_mfma_f32_16x16x32_bf16 v[120:123], v[166:169], v[194:197], v[120:123]
	v_mfma_f32_16x16x32_bf16 v[108:111], v[158:161], v[202:205], v[108:111]
	v_mfma_f32_16x16x32_bf16 v[104:107], v[166:169], v[202:205], v[104:107]
	v_mfma_f32_16x16x32_bf16 v[92:95], v[158:161], v[210:213], v[92:95]
	v_mfma_f32_16x16x32_bf16 v[88:91], v[166:169], v[210:213], v[88:91]
	v_mfma_f32_16x16x32_bf16 v[76:79], v[158:161], v[218:221], v[76:79]
	v_mfma_f32_16x16x32_bf16 v[72:75], v[166:169], v[218:221], v[72:75]
	s_setprio 0
	s_setprio 1
	v_mfma_f32_16x16x32_bf16 v[116:119], v[170:173], v[190:193], v[116:119]
	v_mfma_f32_16x16x32_bf16 v[112:115], v[182:185], v[190:193], v[112:115]
	v_mfma_f32_16x16x32_bf16 v[100:103], v[170:173], v[198:201], v[100:103]
	v_mfma_f32_16x16x32_bf16 v[96:99], v[182:185], v[198:201], v[96:99]
	v_mfma_f32_16x16x32_bf16 v[84:87], v[170:173], v[206:209], v[84:87]
	v_mfma_f32_16x16x32_bf16 v[80:83], v[182:185], v[206:209], v[80:83]
	v_mfma_f32_16x16x32_bf16 v[68:71], v[170:173], v[214:217], v[68:71]
	v_mfma_f32_16x16x32_bf16 v[64:67], v[182:185], v[214:217], v[64:67]
	v_mfma_f32_16x16x32_bf16 v[116:119], v[174:177], v[194:197], v[116:119]
	v_mfma_f32_16x16x32_bf16 v[112:115], v[186:189], v[194:197], v[112:115]
	v_mfma_f32_16x16x32_bf16 v[100:103], v[174:177], v[202:205], v[100:103]
	v_mfma_f32_16x16x32_bf16 v[96:99], v[186:189], v[202:205], v[96:99]
	v_mfma_f32_16x16x32_bf16 v[84:87], v[174:177], v[210:213], v[84:87]
	v_mfma_f32_16x16x32_bf16 v[80:83], v[186:189], v[210:213], v[80:83]
	v_mfma_f32_16x16x32_bf16 v[68:71], v[174:177], v[218:221], v[68:71]
	v_mfma_f32_16x16x32_bf16 v[64:67], v[186:189], v[218:221], v[64:67]
	s_setprio 0
	s_barrier
	s_add_i32 s17, s17, s18
	v_lshl_add_u64 v[140:141], v[140:141], 0, s[12:13]
	s_mov_b32 m0, s17
	ds_read_b128 v[190:193], v157 offset:49152
	ds_read_b128 v[194:197], v157 offset:50176
	ds_read_b128 v[198:201], v157 offset:51200
	ds_read_b128 v[202:205], v157 offset:52224
	ds_read_b128 v[206:209], v157 offset:53248
	ds_read_b128 v[210:213], v157 offset:54272
	ds_read_b128 v[214:217], v157 offset:55296
	ds_read_b128 v[218:221], v157 offset:56320
	global_load_lds_dwordx4 v[140:141], off
	s_add_i32 m0, s17, 0x2000
	s_add_u32 s38, s58, 0x80080
	v_lshl_add_u64 v[140:141], v[178:179], 0, s[12:13]
	s_addc_u32 s39, s59, 0
	s_add_i32 s17, s25, s18
	global_load_lds_dwordx4 v[140:141], off
	v_lshl_add_u64 v[140:141], s[38:39], 0, v[130:131]
	s_mov_b32 m0, s17
	s_nop 0
	global_load_lds_dwordx4 v[140:141], off
	v_lshl_add_u64 v[140:141], s[38:39], 0, v[134:135]
	s_add_i32 m0, s17, 0x2000
	s_nop 0
	global_load_lds_dwordx4 v[140:141], off
	v_lshl_add_u64 v[140:141], v[222:223], 0, s[12:13]
	s_mov_b32 m0, s65
	s_nop 0
	global_load_lds_dwordx4 v[140:141], off
	v_lshl_add_u64 v[140:141], v[224:225], 0, s[12:13]
	s_mov_b32 m0, s68
	s_nop 0
	global_load_lds_dwordx4 v[140:141], off
	s_waitcnt vmcnt(8)
	s_waitcnt lgkmcnt(0)
	s_barrier
	s_setprio 1
	v_mfma_f32_16x16x32_bf16 v[60:63], v[148:151], v[190:193], v[60:63]
	v_mfma_f32_16x16x32_bf16 v[56:59], v[162:165], v[190:193], v[56:59]
	v_mfma_f32_16x16x32_bf16 v[44:47], v[148:151], v[198:201], v[44:47]
	v_mfma_f32_16x16x32_bf16 v[40:43], v[162:165], v[198:201], v[40:43]
	v_mfma_f32_16x16x32_bf16 v[28:31], v[148:151], v[206:209], v[28:31]
	v_mfma_f32_16x16x32_bf16 v[24:27], v[162:165], v[206:209], v[24:27]
	v_mfma_f32_16x16x32_bf16 v[12:15], v[148:151], v[214:217], v[12:15]
	v_mfma_f32_16x16x32_bf16 v[8:11], v[162:165], v[214:217], v[8:11]
	v_mfma_f32_16x16x32_bf16 v[60:63], v[158:161], v[194:197], v[60:63]
	v_mfma_f32_16x16x32_bf16 v[56:59], v[166:169], v[194:197], v[56:59]
	v_mfma_f32_16x16x32_bf16 v[44:47], v[158:161], v[202:205], v[44:47]
	v_mfma_f32_16x16x32_bf16 v[40:43], v[166:169], v[202:205], v[40:43]
	v_mfma_f32_16x16x32_bf16 v[28:31], v[158:161], v[210:213], v[28:31]
	v_mfma_f32_16x16x32_bf16 v[24:27], v[166:169], v[210:213], v[24:27]
	v_mfma_f32_16x16x32_bf16 v[12:15], v[158:161], v[218:221], v[12:15]
	v_mfma_f32_16x16x32_bf16 v[8:11], v[166:169], v[218:221], v[8:11]
	s_setprio 0
	s_setprio 1
	v_mfma_f32_16x16x32_bf16 v[52:55], v[170:173], v[190:193], v[52:55]
	v_mfma_f32_16x16x32_bf16 v[48:51], v[182:185], v[190:193], v[48:51]
	v_mfma_f32_16x16x32_bf16 v[36:39], v[170:173], v[198:201], v[36:39]
	v_mfma_f32_16x16x32_bf16 v[32:35], v[182:185], v[198:201], v[32:35]
	v_mfma_f32_16x16x32_bf16 v[20:23], v[170:173], v[206:209], v[20:23]
	v_mfma_f32_16x16x32_bf16 v[16:19], v[182:185], v[206:209], v[16:19]
	v_mfma_f32_16x16x32_bf16 v[4:7], v[170:173], v[214:217], v[4:7]
	v_mfma_f32_16x16x32_bf16 v[0:3], v[182:185], v[214:217], v[0:3]
	v_mfma_f32_16x16x32_bf16 v[52:55], v[174:177], v[194:197], v[52:55]
	v_mfma_f32_16x16x32_bf16 v[48:51], v[186:189], v[194:197], v[48:51]
	v_mfma_f32_16x16x32_bf16 v[36:39], v[174:177], v[202:205], v[36:39]
	v_mfma_f32_16x16x32_bf16 v[32:35], v[186:189], v[202:205], v[32:35]
	v_mfma_f32_16x16x32_bf16 v[20:23], v[174:177], v[210:213], v[20:23]
	v_mfma_f32_16x16x32_bf16 v[16:19], v[186:189], v[210:213], v[16:19]
	v_mfma_f32_16x16x32_bf16 v[4:7], v[174:177], v[218:221], v[4:7]
	v_mfma_f32_16x16x32_bf16 v[0:3], v[186:189], v[218:221], v[0:3]
	s_setprio 0
	s_barrier
	s_add_i32 s3, s3, 2
	s_add_u32 s54, s54, 0x100
	s_addc_u32 s55, s55, 0
	s_cmp_ge_i32 s3, s63
	s_cbranch_scc0 .LBB0_213

.LBB0_628:
	s_mov_b64 s[4:5], s[36:37]
	ds_read_b128 v[80:83], v199
	ds_read_b128 v[92:95], v199 offset:1024
	ds_read_b128 v[96:99], v199 offset:2048
	ds_read_b128 v[104:107], v199 offset:3072
	ds_read_b128 v[108:111], v200
	ds_read_b128 v[116:119], v200 offset:1024
	ds_read_b128 v[120:123], v200 offset:2048
	ds_read_b128 v[124:127], v200 offset:3072
	s_add_u32 s7, s12, s4
	s_addc_u32 s28, s13, s5
	s_add_u32 s29, s7, 0x100
	s_addc_u32 s31, s28, 0
	s_add_u32 s4, s16, s4
	s_addc_u32 s5, s17, s5
	s_add_u32 s4, s4, 0x100
	s_addc_u32 s5, s5, 0
	s_cmp_eq_u32 s72, s3
	s_cselect_b32 s65, s61, s31
	s_cselect_b32 s64, s60, s29
	s_cselect_b32 s55, s63, s5
	s_cselect_b32 s54, s62, s4
	s_add_u32 s4, s7, 0x80080
	s_addc_u32 s5, s28, 0
	v_lshl_add_u64 v[194:195], s[4:5], 0, v[182:183]
	s_add_i32 m0, s19, 0xc000
	ds_read_b128 v[160:163], v201
	ds_read_b128 v[164:167], v201 offset:1024
	ds_read_b128 v[168:171], v201 offset:2048
	ds_read_b128 v[172:175], v201 offset:3072
	ds_read_b128 v[176:179], v201 offset:4096
	ds_read_b128 v[190:193], v201 offset:5120
	ds_read_b128 v[202:205], v201 offset:6144
	ds_read_b128 v[206:209], v201 offset:7168
	global_load_lds_dwordx4 v[194:195], off
	v_lshl_add_u64 v[194:195], s[4:5], 0, v[184:185]
	s_add_i32 m0, s19, 0xe000
	s_nop 0
	global_load_lds_dwordx4 v[194:195], off
	s_waitcnt vmcnt(8)
	s_waitcnt lgkmcnt(0)
	s_barrier
	s_setprio 1
	v_mfma_f32_16x16x32_bf16 v[156:159], v[80:83], v[160:163], v[156:159]
	v_mfma_f32_16x16x32_bf16 v[152:155], v[96:99], v[160:163], v[152:155]
	v_mfma_f32_16x16x32_bf16 v[140:143], v[80:83], v[168:171], v[140:143]
	v_mfma_f32_16x16x32_bf16 v[136:139], v[96:99], v[168:171], v[136:139]
	v_mfma_f32_16x16x32_bf16 v[112:115], v[80:83], v[176:179], v[112:115]
	v_mfma_f32_16x16x32_bf16 v[100:103], v[96:99], v[176:179], v[100:103]
	v_mfma_f32_16x16x32_bf16 v[76:79], v[80:83], v[202:205], v[76:79]
	v_mfma_f32_16x16x32_bf16 v[72:75], v[96:99], v[202:205], v[72:75]
	v_mfma_f32_16x16x32_bf16 v[156:159], v[92:95], v[164:167], v[156:159]
	v_mfma_f32_16x16x32_bf16 v[152:155], v[104:107], v[164:167], v[152:155]
	v_mfma_f32_16x16x32_bf16 v[140:143], v[92:95], v[172:175], v[140:143]
	v_mfma_f32_16x16x32_bf16 v[136:139], v[104:107], v[172:175], v[136:139]
	v_mfma_f32_16x16x32_bf16 v[112:115], v[92:95], v[190:193], v[112:115]
	v_mfma_f32_16x16x32_bf16 v[100:103], v[104:107], v[190:193], v[100:103]
	v_mfma_f32_16x16x32_bf16 v[76:79], v[92:95], v[206:209], v[76:79]
	v_mfma_f32_16x16x32_bf16 v[72:75], v[104:107], v[206:209], v[72:75]
	s_setprio 0
	s_setprio 1
	v_mfma_f32_16x16x32_bf16 v[148:151], v[108:111], v[160:163], v[148:151]
	v_mfma_f32_16x16x32_bf16 v[144:147], v[120:123], v[160:163], v[144:147]
	v_mfma_f32_16x16x32_bf16 v[132:135], v[108:111], v[168:171], v[132:135]
	v_mfma_f32_16x16x32_bf16 v[128:131], v[120:123], v[168:171], v[128:131]
	v_mfma_f32_16x16x32_bf16 v[88:91], v[108:111], v[176:179], v[88:91]
	v_mfma_f32_16x16x32_bf16 v[84:87], v[120:123], v[176:179], v[84:87]
	v_mfma_f32_16x16x32_bf16 v[68:71], v[108:111], v[202:205], v[68:71]
	v_mfma_f32_16x16x32_bf16 v[64:67], v[120:123], v[202:205], v[64:67]
	v_mfma_f32_16x16x32_bf16 v[148:151], v[116:119], v[164:167], v[148:151]
	v_mfma_f32_16x16x32_bf16 v[144:147], v[124:127], v[164:167], v[144:147]
	v_mfma_f32_16x16x32_bf16 v[132:135], v[116:119], v[172:175], v[132:135]
	v_mfma_f32_16x16x32_bf16 v[128:131], v[124:127], v[172:175], v[128:131]
	v_mfma_f32_16x16x32_bf16 v[88:91], v[116:119], v[190:193], v[88:91]
	v_mfma_f32_16x16x32_bf16 v[84:87], v[124:127], v[190:193], v[84:87]
	v_mfma_f32_16x16x32_bf16 v[68:71], v[116:119], v[206:209], v[68:71]
	v_mfma_f32_16x16x32_bf16 v[64:67], v[124:127], v[206:209], v[64:67]
	s_setprio 0
	s_barrier
	s_add_i32 s4, s73, s18
	v_lshl_add_u64 v[194:195], s[54:55], 0, v[182:183]
	s_mov_b32 m0, s4
	ds_read_b128 v[160:163], v201 offset:16384
	ds_read_b128 v[164:167], v201 offset:17408
	ds_read_b128 v[168:171], v201 offset:18432
	ds_read_b128 v[172:175], v201 offset:19456
	ds_read_b128 v[176:179], v201 offset:20480
	ds_read_b128 v[190:193], v201 offset:21504
	ds_read_b128 v[202:205], v201 offset:22528
	ds_read_b128 v[206:209], v201 offset:23552
	global_load_lds_dwordx4 v[194:195], off
	s_add_i32 m0, s4, 0x2000
	s_add_u32 s4, s54, 0x80000
	v_lshl_add_u64 v[210:211], s[54:55], 0, v[184:185]
	s_addc_u32 s5, s55, 0
	s_add_i32 s7, s74, s18
	global_load_lds_dwordx4 v[210:211], off
	v_lshl_add_u64 v[212:213], s[4:5], 0, v[182:183]
	s_mov_b32 m0, s7
	v_lshl_add_u64 v[214:215], s[64:65], 0, v[184:185]
	global_load_lds_dwordx4 v[212:213], off
	v_lshl_add_u64 v[212:213], s[4:5], 0, v[184:185]
	s_add_i32 m0, s7, 0x2000
	s_nop 0
	global_load_lds_dwordx4 v[212:213], off
	v_lshl_add_u64 v[212:213], s[64:65], 0, v[182:183]
	s_mov_b32 m0, s19
	s_nop 0
	global_load_lds_dwordx4 v[212:213], off
	s_mov_b32 m0, s56
	s_nop 0
	global_load_lds_dwordx4 v[214:215], off
	s_waitcnt vmcnt(8)
	s_waitcnt lgkmcnt(0)
	s_barrier
	s_setprio 1
	v_mfma_f32_16x16x32_bf16 v[60:63], v[80:83], v[160:163], v[60:63]
	v_mfma_f32_16x16x32_bf16 v[56:59], v[96:99], v[160:163], v[56:59]
	v_mfma_f32_16x16x32_bf16 v[44:47], v[80:83], v[168:171], v[44:47]
	v_mfma_f32_16x16x32_bf16 v[40:43], v[96:99], v[168:171], v[40:43]
	v_mfma_f32_16x16x32_bf16 v[28:31], v[80:83], v[176:179], v[28:31]
	v_mfma_f32_16x16x32_bf16 v[24:27], v[96:99], v[176:179], v[24:27]
	v_mfma_f32_16x16x32_bf16 v[12:15], v[80:83], v[202:205], v[12:15]
	v_mfma_f32_16x16x32_bf16 v[8:11], v[96:99], v[202:205], v[8:11]
	v_mfma_f32_16x16x32_bf16 v[60:63], v[92:95], v[164:167], v[60:63]
	v_mfma_f32_16x16x32_bf16 v[56:59], v[104:107], v[164:167], v[56:59]
	v_mfma_f32_16x16x32_bf16 v[44:47], v[92:95], v[172:175], v[44:47]
	v_mfma_f32_16x16x32_bf16 v[40:43], v[104:107], v[172:175], v[40:43]
	v_mfma_f32_16x16x32_bf16 v[28:31], v[92:95], v[190:193], v[28:31]
	v_mfma_f32_16x16x32_bf16 v[24:27], v[104:107], v[190:193], v[24:27]
	v_mfma_f32_16x16x32_bf16 v[12:15], v[92:95], v[206:209], v[12:15]
	v_mfma_f32_16x16x32_bf16 v[8:11], v[104:107], v[206:209], v[8:11]
	s_setprio 0
	s_setprio 1
	v_mfma_f32_16x16x32_bf16 v[52:55], v[108:111], v[160:163], v[52:55]
	v_mfma_f32_16x16x32_bf16 v[48:51], v[120:123], v[160:163], v[48:51]
	v_mfma_f32_16x16x32_bf16 v[36:39], v[108:111], v[168:171], v[36:39]
	v_mfma_f32_16x16x32_bf16 v[32:35], v[120:123], v[168:171], v[32:35]
	v_mfma_f32_16x16x32_bf16 v[20:23], v[108:111], v[176:179], v[20:23]
	v_mfma_f32_16x16x32_bf16 v[16:19], v[120:123], v[176:179], v[16:19]
	v_mfma_f32_16x16x32_bf16 v[4:7], v[108:111], v[202:205], v[4:7]
	v_mfma_f32_16x16x32_bf16 v[0:3], v[120:123], v[202:205], v[0:3]
	v_mfma_f32_16x16x32_bf16 v[52:55], v[116:119], v[164:167], v[52:55]
	v_mfma_f32_16x16x32_bf16 v[48:51], v[124:127], v[164:167], v[48:51]
	v_mfma_f32_16x16x32_bf16 v[36:39], v[116:119], v[172:175], v[36:39]
	v_mfma_f32_16x16x32_bf16 v[32:35], v[124:127], v[172:175], v[32:35]
	v_mfma_f32_16x16x32_bf16 v[20:23], v[116:119], v[190:193], v[20:23]
	v_mfma_f32_16x16x32_bf16 v[16:19], v[124:127], v[190:193], v[16:19]
	v_mfma_f32_16x16x32_bf16 v[4:7], v[116:119], v[206:209], v[4:7]
	v_mfma_f32_16x16x32_bf16 v[0:3], v[124:127], v[206:209], v[0:3]
	s_setprio 0
	s_barrier
	s_add_i32 s7, 0, 0x18000
	s_add_i32 s28, 0, 0x1c000
	v_add_u32_e32 v104, s7, v198
	v_add_u32_e32 v124, s28, v198
	ds_read_b128 v[80:83], v104
	ds_read_b128 v[92:95], v104 offset:1024
	ds_read_b128 v[96:99], v104 offset:2048
	ds_read_b128 v[104:107], v104 offset:3072
	ds_read_b128 v[108:111], v124
	ds_read_b128 v[116:119], v124 offset:1024
	ds_read_b128 v[120:123], v124 offset:2048
	ds_read_b128 v[124:127], v124 offset:3072
	s_add_u32 s4, s64, 0x80000
	s_addc_u32 s5, s65, 0
	s_mov_b32 m0, s57
	v_lshl_add_u64 v[216:217], s[4:5], 0, v[182:183]
	ds_read_b128 v[160:163], v201 offset:32768
	ds_read_b128 v[164:167], v201 offset:33792
	ds_read_b128 v[168:171], v201 offset:34816
	ds_read_b128 v[172:175], v201 offset:35840
	ds_read_b128 v[176:179], v201 offset:36864
	ds_read_b128 v[190:193], v201 offset:37888
	ds_read_b128 v[202:205], v201 offset:38912
	ds_read_b128 v[206:209], v201 offset:39936
	global_load_lds_dwordx4 v[216:217], off
	v_lshl_add_u64 v[216:217], s[4:5], 0, v[184:185]
	s_mov_b32 m0, s66
	s_nop 0
	global_load_lds_dwordx4 v[216:217], off
	s_waitcnt vmcnt(8)
	s_waitcnt lgkmcnt(0)
	s_barrier
	s_setprio 1
	v_mfma_f32_16x16x32_bf16 v[156:159], v[80:83], v[160:163], v[156:159]
	v_mfma_f32_16x16x32_bf16 v[152:155], v[96:99], v[160:163], v[152:155]
	v_mfma_f32_16x16x32_bf16 v[140:143], v[80:83], v[168:171], v[140:143]
	v_mfma_f32_16x16x32_bf16 v[136:139], v[96:99], v[168:171], v[136:139]
	v_mfma_f32_16x16x32_bf16 v[112:115], v[80:83], v[176:179], v[112:115]
	v_mfma_f32_16x16x32_bf16 v[100:103], v[96:99], v[176:179], v[100:103]
	v_mfma_f32_16x16x32_bf16 v[76:79], v[80:83], v[202:205], v[76:79]
	v_mfma_f32_16x16x32_bf16 v[72:75], v[96:99], v[202:205], v[72:75]
	v_mfma_f32_16x16x32_bf16 v[156:159], v[92:95], v[164:167], v[156:159]
	v_mfma_f32_16x16x32_bf16 v[152:155], v[104:107], v[164:167], v[152:155]
	v_mfma_f32_16x16x32_bf16 v[140:143], v[92:95], v[172:175], v[140:143]
	v_mfma_f32_16x16x32_bf16 v[136:139], v[104:107], v[172:175], v[136:139]
	v_mfma_f32_16x16x32_bf16 v[112:115], v[92:95], v[190:193], v[112:115]
	v_mfma_f32_16x16x32_bf16 v[100:103], v[104:107], v[190:193], v[100:103]
	v_mfma_f32_16x16x32_bf16 v[76:79], v[92:95], v[206:209], v[76:79]
	v_mfma_f32_16x16x32_bf16 v[72:75], v[104:107], v[206:209], v[72:75]
	s_setprio 0
	s_setprio 1
	v_mfma_f32_16x16x32_bf16 v[148:151], v[108:111], v[160:163], v[148:151]
	v_mfma_f32_16x16x32_bf16 v[144:147], v[120:123], v[160:163], v[144:147]
	v_mfma_f32_16x16x32_bf16 v[132:135], v[108:111], v[168:171], v[132:135]
	v_mfma_f32_16x16x32_bf16 v[128:131], v[120:123], v[168:171], v[128:131]
	v_mfma_f32_16x16x32_bf16 v[88:91], v[108:111], v[176:179], v[88:91]
	v_mfma_f32_16x16x32_bf16 v[84:87], v[120:123], v[176:179], v[84:87]
	v_mfma_f32_16x16x32_bf16 v[68:71], v[108:111], v[202:205], v[68:71]
	v_mfma_f32_16x16x32_bf16 v[64:67], v[120:123], v[202:205], v[64:67]
	v_mfma_f32_16x16x32_bf16 v[148:151], v[116:119], v[164:167], v[148:151]
	v_mfma_f32_16x16x32_bf16 v[144:147], v[124:127], v[164:167], v[144:147]
	v_mfma_f32_16x16x32_bf16 v[132:135], v[116:119], v[172:175], v[132:135]
	v_mfma_f32_16x16x32_bf16 v[128:131], v[124:127], v[172:175], v[128:131]
	v_mfma_f32_16x16x32_bf16 v[88:91], v[116:119], v[190:193], v[88:91]
	v_mfma_f32_16x16x32_bf16 v[84:87], v[124:127], v[190:193], v[84:87]
	v_mfma_f32_16x16x32_bf16 v[68:71], v[116:119], v[206:209], v[68:71]
	v_mfma_f32_16x16x32_bf16 v[64:67], v[124:127], v[206:209], v[64:67]
	s_setprio 0
	s_barrier
	s_add_i32 s4, s7, s18
	v_lshl_add_u64 v[194:195], v[194:195], 0, s[14:15]
	s_mov_b32 m0, s4
	ds_read_b128 v[160:163], v201 offset:49152
	ds_read_b128 v[164:167], v201 offset:50176
	ds_read_b128 v[168:171], v201 offset:51200
	ds_read_b128 v[172:175], v201 offset:52224
	ds_read_b128 v[176:179], v201 offset:53248
	ds_read_b128 v[190:193], v201 offset:54272
	ds_read_b128 v[202:205], v201 offset:55296
	ds_read_b128 v[206:209], v201 offset:56320
	global_load_lds_dwordx4 v[194:195], off
	s_add_i32 m0, s4, 0x2000
	s_add_u32 s4, s54, 0x80080
	v_lshl_add_u64 v[194:195], v[210:211], 0, s[14:15]
	s_addc_u32 s5, s55, 0
	s_add_i32 s7, s28, s18
	global_load_lds_dwordx4 v[194:195], off
	v_lshl_add_u64 v[194:195], s[4:5], 0, v[182:183]
	s_mov_b32 m0, s7
	s_nop 0
	global_load_lds_dwordx4 v[194:195], off
	v_lshl_add_u64 v[194:195], s[4:5], 0, v[184:185]
	s_add_i32 m0, s7, 0x2000
	s_nop 0
	global_load_lds_dwordx4 v[194:195], off
	v_lshl_add_u64 v[194:195], v[212:213], 0, s[14:15]
	s_mov_b32 m0, s70
	s_nop 0
	global_load_lds_dwordx4 v[194:195], off
	v_lshl_add_u64 v[194:195], v[214:215], 0, s[14:15]
	s_mov_b32 m0, s71
	s_nop 0
	global_load_lds_dwordx4 v[194:195], off
	s_waitcnt vmcnt(8)
	s_waitcnt lgkmcnt(0)
	s_barrier
	s_setprio 1
	v_mfma_f32_16x16x32_bf16 v[60:63], v[80:83], v[160:163], v[60:63]
	v_mfma_f32_16x16x32_bf16 v[56:59], v[96:99], v[160:163], v[56:59]
	v_mfma_f32_16x16x32_bf16 v[44:47], v[80:83], v[168:171], v[44:47]
	v_mfma_f32_16x16x32_bf16 v[40:43], v[96:99], v[168:171], v[40:43]
	v_mfma_f32_16x16x32_bf16 v[28:31], v[80:83], v[176:179], v[28:31]
	v_mfma_f32_16x16x32_bf16 v[24:27], v[96:99], v[176:179], v[24:27]
	v_mfma_f32_16x16x32_bf16 v[12:15], v[80:83], v[202:205], v[12:15]
	v_mfma_f32_16x16x32_bf16 v[8:11], v[96:99], v[202:205], v[8:11]
	v_mfma_f32_16x16x32_bf16 v[60:63], v[92:95], v[164:167], v[60:63]
	v_mfma_f32_16x16x32_bf16 v[56:59], v[104:107], v[164:167], v[56:59]
	v_mfma_f32_16x16x32_bf16 v[44:47], v[92:95], v[172:175], v[44:47]
	v_mfma_f32_16x16x32_bf16 v[40:43], v[104:107], v[172:175], v[40:43]
	v_mfma_f32_16x16x32_bf16 v[28:31], v[92:95], v[190:193], v[28:31]
	v_mfma_f32_16x16x32_bf16 v[24:27], v[104:107], v[190:193], v[24:27]
	v_mfma_f32_16x16x32_bf16 v[12:15], v[92:95], v[206:209], v[12:15]
	v_mfma_f32_16x16x32_bf16 v[8:11], v[104:107], v[206:209], v[8:11]
	s_setprio 0
	s_setprio 1
	v_mfma_f32_16x16x32_bf16 v[52:55], v[108:111], v[160:163], v[52:55]
	v_mfma_f32_16x16x32_bf16 v[48:51], v[120:123], v[160:163], v[48:51]
	v_mfma_f32_16x16x32_bf16 v[36:39], v[108:111], v[168:171], v[36:39]
	v_mfma_f32_16x16x32_bf16 v[32:35], v[120:123], v[168:171], v[32:35]
	v_mfma_f32_16x16x32_bf16 v[20:23], v[108:111], v[176:179], v[20:23]
	v_mfma_f32_16x16x32_bf16 v[16:19], v[120:123], v[176:179], v[16:19]
	v_mfma_f32_16x16x32_bf16 v[4:7], v[108:111], v[202:205], v[4:7]
	v_mfma_f32_16x16x32_bf16 v[0:3], v[120:123], v[202:205], v[0:3]
	v_mfma_f32_16x16x32_bf16 v[52:55], v[116:119], v[164:167], v[52:55]
	v_mfma_f32_16x16x32_bf16 v[48:51], v[124:127], v[164:167], v[48:51]
	v_mfma_f32_16x16x32_bf16 v[36:39], v[116:119], v[172:175], v[36:39]
	v_mfma_f32_16x16x32_bf16 v[32:35], v[124:127], v[172:175], v[32:35]
	v_mfma_f32_16x16x32_bf16 v[20:23], v[116:119], v[190:193], v[20:23]
	v_mfma_f32_16x16x32_bf16 v[16:19], v[124:127], v[190:193], v[16:19]
	v_mfma_f32_16x16x32_bf16 v[4:7], v[116:119], v[206:209], v[4:7]
	v_mfma_f32_16x16x32_bf16 v[0:3], v[124:127], v[206:209], v[0:3]
	s_setprio 0
	s_barrier
	s_add_i32 s3, s3, 2
	s_add_u32 s36, s36, 0x100
	s_addc_u32 s37, s37, 0
	s_cmp_ge_i32 s3, s67
	s_cbranch_scc0 .LBB0_628

.LBB0_667:
	s_mov_b64 s[24:25], s[16:17]
	ds_read_b128 v[140:143], v134
	ds_read_b128 v[144:147], v134 offset:1024
	ds_read_b128 v[148:151], v134 offset:2048
	ds_read_b128 v[152:155], v134 offset:3072
	ds_read_b128 v[156:159], v135
	ds_read_b128 v[160:163], v135 offset:1024
	ds_read_b128 v[164:167], v135 offset:2048
	ds_read_b128 v[168:171], v135 offset:3072
	s_add_u32 s38, s0, s24
	s_addc_u32 s39, s1, s25
	s_add_u32 s26, s38, 0x100
	s_addc_u32 s27, s39, 0
	s_add_u32 s24, s2, s24
	s_addc_u32 s25, s3, s25
	s_add_u32 s24, s24, 0x100
	s_addc_u32 s25, s25, 0
	s_cmp_eq_u32 s31, s34
	s_cselect_b32 s27, s13, s27
	s_cselect_b32 s26, s12, s26
	s_cselect_b32 s25, s15, s25
	s_cselect_b32 s24, s14, s24
	s_add_u32 s38, s38, 0x80080
	s_addc_u32 s39, s39, 0
	s_mov_b32 m0, s35
	v_lshl_add_u64 v[206:207], s[38:39], 0, v[128:129]
	ds_read_b128 v[172:175], v136
	ds_read_b128 v[176:179], v136 offset:1024
	ds_read_b128 v[182:185], v136 offset:2048
	ds_read_b128 v[186:189], v136 offset:3072
	ds_read_b128 v[190:193], v136 offset:4096
	ds_read_b128 v[194:197], v136 offset:5120
	ds_read_b128 v[198:201], v136 offset:6144
	ds_read_b128 v[202:205], v136 offset:7168
	global_load_lds_dwordx4 v[206:207], off
	v_lshl_add_u64 v[206:207], s[38:39], 0, v[130:131]
	s_mov_b32 m0, s36
	s_nop 0
	global_load_lds_dwordx4 v[206:207], off
	s_waitcnt vmcnt(8)
	s_waitcnt lgkmcnt(0)
	s_barrier
	s_setprio 1
	v_mfma_f32_16x16x32_bf16 v[124:127], v[140:143], v[172:175], v[124:127]
	v_mfma_f32_16x16x32_bf16 v[120:123], v[148:151], v[172:175], v[120:123]
	v_mfma_f32_16x16x32_bf16 v[108:111], v[140:143], v[182:185], v[108:111]
	v_mfma_f32_16x16x32_bf16 v[104:107], v[148:151], v[182:185], v[104:107]
	v_mfma_f32_16x16x32_bf16 v[92:95], v[140:143], v[190:193], v[92:95]
	v_mfma_f32_16x16x32_bf16 v[88:91], v[148:151], v[190:193], v[88:91]
	v_mfma_f32_16x16x32_bf16 v[76:79], v[140:143], v[198:201], v[76:79]
	v_mfma_f32_16x16x32_bf16 v[72:75], v[148:151], v[198:201], v[72:75]
	v_mfma_f32_16x16x32_bf16 v[124:127], v[144:147], v[176:179], v[124:127]
	v_mfma_f32_16x16x32_bf16 v[120:123], v[152:155], v[176:179], v[120:123]
	v_mfma_f32_16x16x32_bf16 v[108:111], v[144:147], v[186:189], v[108:111]
	v_mfma_f32_16x16x32_bf16 v[104:107], v[152:155], v[186:189], v[104:107]
	v_mfma_f32_16x16x32_bf16 v[92:95], v[144:147], v[194:197], v[92:95]
	v_mfma_f32_16x16x32_bf16 v[88:91], v[152:155], v[194:197], v[88:91]
	v_mfma_f32_16x16x32_bf16 v[76:79], v[144:147], v[202:205], v[76:79]
	v_mfma_f32_16x16x32_bf16 v[72:75], v[152:155], v[202:205], v[72:75]
	s_setprio 0
	s_setprio 1
	v_mfma_f32_16x16x32_bf16 v[116:119], v[156:159], v[172:175], v[116:119]
	v_mfma_f32_16x16x32_bf16 v[112:115], v[164:167], v[172:175], v[112:115]
	v_mfma_f32_16x16x32_bf16 v[100:103], v[156:159], v[182:185], v[100:103]
	v_mfma_f32_16x16x32_bf16 v[96:99], v[164:167], v[182:185], v[96:99]
	v_mfma_f32_16x16x32_bf16 v[84:87], v[156:159], v[190:193], v[84:87]
	v_mfma_f32_16x16x32_bf16 v[80:83], v[164:167], v[190:193], v[80:83]
	v_mfma_f32_16x16x32_bf16 v[68:71], v[156:159], v[198:201], v[68:71]
	v_mfma_f32_16x16x32_bf16 v[64:67], v[164:167], v[198:201], v[64:67]
	v_mfma_f32_16x16x32_bf16 v[116:119], v[160:163], v[176:179], v[116:119]
	v_mfma_f32_16x16x32_bf16 v[112:115], v[168:171], v[176:179], v[112:115]
	v_mfma_f32_16x16x32_bf16 v[100:103], v[160:163], v[186:189], v[100:103]
	v_mfma_f32_16x16x32_bf16 v[96:99], v[168:171], v[186:189], v[96:99]
	v_mfma_f32_16x16x32_bf16 v[84:87], v[160:163], v[194:197], v[84:87]
	v_mfma_f32_16x16x32_bf16 v[80:83], v[168:171], v[194:197], v[80:83]
	v_mfma_f32_16x16x32_bf16 v[68:71], v[160:163], v[202:205], v[68:71]
	v_mfma_f32_16x16x32_bf16 v[64:67], v[168:171], v[202:205], v[64:67]
	s_setprio 0
	s_barrier
	s_mov_b32 m0, s37
	v_lshl_add_u64 v[206:207], s[24:25], 0, v[128:129]
	s_add_u32 s38, s24, 0x80000
	ds_read_b128 v[172:175], v136 offset:16384
	ds_read_b128 v[176:179], v136 offset:17408
	ds_read_b128 v[182:185], v136 offset:18432
	ds_read_b128 v[186:189], v136 offset:19456
	ds_read_b128 v[190:193], v136 offset:20480
	ds_read_b128 v[194:197], v136 offset:21504
	ds_read_b128 v[198:201], v136 offset:22528
	ds_read_b128 v[202:205], v136 offset:23552
	global_load_lds_dwordx4 v[206:207], off
	v_lshl_add_u64 v[208:209], s[24:25], 0, v[130:131]
	s_mov_b32 m0, s52
	s_addc_u32 s39, s25, 0
	global_load_lds_dwordx4 v[208:209], off
	v_lshl_add_u64 v[210:211], s[38:39], 0, v[128:129]
	s_mov_b32 m0, s53
	v_lshl_add_u64 v[212:213], s[26:27], 0, v[130:131]
	global_load_lds_dwordx4 v[210:211], off
	v_lshl_add_u64 v[210:211], s[38:39], 0, v[130:131]
	s_mov_b32 m0, s54
	s_nop 0
	global_load_lds_dwordx4 v[210:211], off
	v_lshl_add_u64 v[210:211], s[26:27], 0, v[128:129]
	s_mov_b32 m0, s9
	s_nop 0
	global_load_lds_dwordx4 v[210:211], off
	s_mov_b32 m0, s18
	s_nop 0
	global_load_lds_dwordx4 v[212:213], off
	s_waitcnt vmcnt(8)
	s_waitcnt lgkmcnt(0)
	s_barrier
	s_setprio 1
	v_mfma_f32_16x16x32_bf16 v[60:63], v[140:143], v[172:175], v[60:63]
	v_mfma_f32_16x16x32_bf16 v[56:59], v[148:151], v[172:175], v[56:59]
	v_mfma_f32_16x16x32_bf16 v[44:47], v[140:143], v[182:185], v[44:47]
	v_mfma_f32_16x16x32_bf16 v[40:43], v[148:151], v[182:185], v[40:43]
	v_mfma_f32_16x16x32_bf16 v[28:31], v[140:143], v[190:193], v[28:31]
	v_mfma_f32_16x16x32_bf16 v[24:27], v[148:151], v[190:193], v[24:27]
	v_mfma_f32_16x16x32_bf16 v[12:15], v[140:143], v[198:201], v[12:15]
	v_mfma_f32_16x16x32_bf16 v[8:11], v[148:151], v[198:201], v[8:11]
	v_mfma_f32_16x16x32_bf16 v[60:63], v[144:147], v[176:179], v[60:63]
	v_mfma_f32_16x16x32_bf16 v[56:59], v[152:155], v[176:179], v[56:59]
	v_mfma_f32_16x16x32_bf16 v[44:47], v[144:147], v[186:189], v[44:47]
	v_mfma_f32_16x16x32_bf16 v[40:43], v[152:155], v[186:189], v[40:43]
	v_mfma_f32_16x16x32_bf16 v[28:31], v[144:147], v[194:197], v[28:31]
	v_mfma_f32_16x16x32_bf16 v[24:27], v[152:155], v[194:197], v[24:27]
	v_mfma_f32_16x16x32_bf16 v[12:15], v[144:147], v[202:205], v[12:15]
	v_mfma_f32_16x16x32_bf16 v[8:11], v[152:155], v[202:205], v[8:11]
	s_setprio 0
	s_setprio 1
	v_mfma_f32_16x16x32_bf16 v[52:55], v[156:159], v[172:175], v[52:55]
	v_mfma_f32_16x16x32_bf16 v[48:51], v[164:167], v[172:175], v[48:51]
	v_mfma_f32_16x16x32_bf16 v[36:39], v[156:159], v[182:185], v[36:39]
	v_mfma_f32_16x16x32_bf16 v[32:35], v[164:167], v[182:185], v[32:35]
	v_mfma_f32_16x16x32_bf16 v[20:23], v[156:159], v[190:193], v[20:23]
	v_mfma_f32_16x16x32_bf16 v[16:19], v[164:167], v[190:193], v[16:19]
	v_mfma_f32_16x16x32_bf16 v[4:7], v[156:159], v[198:201], v[4:7]
	v_mfma_f32_16x16x32_bf16 v[0:3], v[164:167], v[198:201], v[0:3]
	v_mfma_f32_16x16x32_bf16 v[52:55], v[160:163], v[176:179], v[52:55]
	v_mfma_f32_16x16x32_bf16 v[48:51], v[168:171], v[176:179], v[48:51]
	v_mfma_f32_16x16x32_bf16 v[36:39], v[160:163], v[186:189], v[36:39]
	v_mfma_f32_16x16x32_bf16 v[32:35], v[168:171], v[186:189], v[32:35]
	v_mfma_f32_16x16x32_bf16 v[20:23], v[160:163], v[194:197], v[20:23]
	v_mfma_f32_16x16x32_bf16 v[16:19], v[168:171], v[194:197], v[16:19]
	v_mfma_f32_16x16x32_bf16 v[4:7], v[160:163], v[202:205], v[4:7]
	v_mfma_f32_16x16x32_bf16 v[0:3], v[168:171], v[202:205], v[0:3]
	s_setprio 0
	s_barrier
	ds_read_b128 v[140:143], v137
	ds_read_b128 v[144:147], v137 offset:1024
	ds_read_b128 v[148:151], v137 offset:2048
	ds_read_b128 v[152:155], v137 offset:3072
	ds_read_b128 v[156:159], v138
	ds_read_b128 v[160:163], v138 offset:1024
	ds_read_b128 v[164:167], v138 offset:2048
	ds_read_b128 v[168:171], v138 offset:3072
	s_add_u32 s26, s26, 0x80000
	s_addc_u32 s27, s27, 0
	s_mov_b32 m0, s19
	v_lshl_add_u64 v[214:215], s[26:27], 0, v[128:129]
	ds_read_b128 v[172:175], v136 offset:32768
	ds_read_b128 v[176:179], v136 offset:33792
	ds_read_b128 v[182:185], v136 offset:34816
	ds_read_b128 v[186:189], v136 offset:35840
	ds_read_b128 v[190:193], v136 offset:36864
	ds_read_b128 v[194:197], v136 offset:37888
	ds_read_b128 v[198:201], v136 offset:38912
	ds_read_b128 v[202:205], v136 offset:39936
	global_load_lds_dwordx4 v[214:215], off
	v_lshl_add_u64 v[214:215], s[26:27], 0, v[130:131]
	s_mov_b32 m0, s23
	s_nop 0
	global_load_lds_dwordx4 v[214:215], off
	s_waitcnt vmcnt(8)
	s_waitcnt lgkmcnt(0)
	s_barrier
	s_setprio 1
	v_mfma_f32_16x16x32_bf16 v[124:127], v[140:143], v[172:175], v[124:127]
	v_mfma_f32_16x16x32_bf16 v[120:123], v[148:151], v[172:175], v[120:123]
	v_mfma_f32_16x16x32_bf16 v[108:111], v[140:143], v[182:185], v[108:111]
	v_mfma_f32_16x16x32_bf16 v[104:107], v[148:151], v[182:185], v[104:107]
	v_mfma_f32_16x16x32_bf16 v[92:95], v[140:143], v[190:193], v[92:95]
	v_mfma_f32_16x16x32_bf16 v[88:91], v[148:151], v[190:193], v[88:91]
	v_mfma_f32_16x16x32_bf16 v[76:79], v[140:143], v[198:201], v[76:79]
	v_mfma_f32_16x16x32_bf16 v[72:75], v[148:151], v[198:201], v[72:75]
	v_mfma_f32_16x16x32_bf16 v[124:127], v[144:147], v[176:179], v[124:127]
	v_mfma_f32_16x16x32_bf16 v[120:123], v[152:155], v[176:179], v[120:123]
	v_mfma_f32_16x16x32_bf16 v[108:111], v[144:147], v[186:189], v[108:111]
	v_mfma_f32_16x16x32_bf16 v[104:107], v[152:155], v[186:189], v[104:107]
	v_mfma_f32_16x16x32_bf16 v[92:95], v[144:147], v[194:197], v[92:95]
	v_mfma_f32_16x16x32_bf16 v[88:91], v[152:155], v[194:197], v[88:91]
	v_mfma_f32_16x16x32_bf16 v[76:79], v[144:147], v[202:205], v[76:79]
	v_mfma_f32_16x16x32_bf16 v[72:75], v[152:155], v[202:205], v[72:75]
	s_setprio 0
	s_setprio 1
	v_mfma_f32_16x16x32_bf16 v[116:119], v[156:159], v[172:175], v[116:119]
	v_mfma_f32_16x16x32_bf16 v[112:115], v[164:167], v[172:175], v[112:115]
	v_mfma_f32_16x16x32_bf16 v[100:103], v[156:159], v[182:185], v[100:103]
	v_mfma_f32_16x16x32_bf16 v[96:99], v[164:167], v[182:185], v[96:99]
	v_mfma_f32_16x16x32_bf16 v[84:87], v[156:159], v[190:193], v[84:87]
	v_mfma_f32_16x16x32_bf16 v[80:83], v[164:167], v[190:193], v[80:83]
	v_mfma_f32_16x16x32_bf16 v[68:71], v[156:159], v[198:201], v[68:71]
	v_mfma_f32_16x16x32_bf16 v[64:67], v[164:167], v[198:201], v[64:67]
	v_mfma_f32_16x16x32_bf16 v[116:119], v[160:163], v[176:179], v[116:119]
	v_mfma_f32_16x16x32_bf16 v[112:115], v[168:171], v[176:179], v[112:115]
	v_mfma_f32_16x16x32_bf16 v[100:103], v[160:163], v[186:189], v[100:103]
	v_mfma_f32_16x16x32_bf16 v[96:99], v[168:171], v[186:189], v[96:99]
	v_mfma_f32_16x16x32_bf16 v[84:87], v[160:163], v[194:197], v[84:87]
	v_mfma_f32_16x16x32_bf16 v[80:83], v[168:171], v[194:197], v[80:83]
	v_mfma_f32_16x16x32_bf16 v[68:71], v[160:163], v[202:205], v[68:71]
	v_mfma_f32_16x16x32_bf16 v[64:67], v[168:171], v[202:205], v[64:67]
	s_setprio 0
	s_barrier
	s_mov_b32 m0, s55
	v_lshl_add_u64 v[206:207], v[206:207], 0, s[10:11]
	s_add_u32 s24, s24, 0x80080
	ds_read_b128 v[172:175], v136 offset:49152
	ds_read_b128 v[176:179], v136 offset:50176
	ds_read_b128 v[182:185], v136 offset:51200
	ds_read_b128 v[186:189], v136 offset:52224
	ds_read_b128 v[190:193], v136 offset:53248
	ds_read_b128 v[194:197], v136 offset:54272
	ds_read_b128 v[198:201], v136 offset:55296
	ds_read_b128 v[202:205], v136 offset:56320
	global_load_lds_dwordx4 v[206:207], off
	v_lshl_add_u64 v[206:207], v[208:209], 0, s[10:11]
	s_mov_b32 m0, s56
	s_addc_u32 s25, s25, 0
	global_load_lds_dwordx4 v[206:207], off
	v_lshl_add_u64 v[206:207], s[24:25], 0, v[128:129]
	s_mov_b32 m0, s57
	s_nop 0
	global_load_lds_dwordx4 v[206:207], off
	v_lshl_add_u64 v[206:207], s[24:25], 0, v[130:131]
	s_mov_b32 m0, s58
	s_nop 0
	global_load_lds_dwordx4 v[206:207], off
	v_lshl_add_u64 v[206:207], v[210:211], 0, s[10:11]
	s_mov_b32 m0, s28
	s_nop 0
	global_load_lds_dwordx4 v[206:207], off
	v_lshl_add_u64 v[206:207], v[212:213], 0, s[10:11]
	s_mov_b32 m0, s29
	s_nop 0
	global_load_lds_dwordx4 v[206:207], off
	s_waitcnt vmcnt(8)
	s_waitcnt lgkmcnt(0)
	s_barrier
	s_setprio 1
	v_mfma_f32_16x16x32_bf16 v[60:63], v[140:143], v[172:175], v[60:63]
	v_mfma_f32_16x16x32_bf16 v[56:59], v[148:151], v[172:175], v[56:59]
	v_mfma_f32_16x16x32_bf16 v[44:47], v[140:143], v[182:185], v[44:47]
	v_mfma_f32_16x16x32_bf16 v[40:43], v[148:151], v[182:185], v[40:43]
	v_mfma_f32_16x16x32_bf16 v[28:31], v[140:143], v[190:193], v[28:31]
	v_mfma_f32_16x16x32_bf16 v[24:27], v[148:151], v[190:193], v[24:27]
	v_mfma_f32_16x16x32_bf16 v[12:15], v[140:143], v[198:201], v[12:15]
	v_mfma_f32_16x16x32_bf16 v[8:11], v[148:151], v[198:201], v[8:11]
	v_mfma_f32_16x16x32_bf16 v[60:63], v[144:147], v[176:179], v[60:63]
	v_mfma_f32_16x16x32_bf16 v[56:59], v[152:155], v[176:179], v[56:59]
	v_mfma_f32_16x16x32_bf16 v[44:47], v[144:147], v[186:189], v[44:47]
	v_mfma_f32_16x16x32_bf16 v[40:43], v[152:155], v[186:189], v[40:43]
	v_mfma_f32_16x16x32_bf16 v[28:31], v[144:147], v[194:197], v[28:31]
	v_mfma_f32_16x16x32_bf16 v[24:27], v[152:155], v[194:197], v[24:27]
	v_mfma_f32_16x16x32_bf16 v[12:15], v[144:147], v[202:205], v[12:15]
	v_mfma_f32_16x16x32_bf16 v[8:11], v[152:155], v[202:205], v[8:11]
	s_setprio 0
	s_setprio 1
	v_mfma_f32_16x16x32_bf16 v[52:55], v[156:159], v[172:175], v[52:55]
	v_mfma_f32_16x16x32_bf16 v[48:51], v[164:167], v[172:175], v[48:51]
	v_mfma_f32_16x16x32_bf16 v[36:39], v[156:159], v[182:185], v[36:39]
	v_mfma_f32_16x16x32_bf16 v[32:35], v[164:167], v[182:185], v[32:35]
	v_mfma_f32_16x16x32_bf16 v[20:23], v[156:159], v[190:193], v[20:23]
	v_mfma_f32_16x16x32_bf16 v[16:19], v[164:167], v[190:193], v[16:19]
	v_mfma_f32_16x16x32_bf16 v[4:7], v[156:159], v[198:201], v[4:7]
	v_mfma_f32_16x16x32_bf16 v[0:3], v[164:167], v[198:201], v[0:3]
	v_mfma_f32_16x16x32_bf16 v[52:55], v[160:163], v[176:179], v[52:55]
	v_mfma_f32_16x16x32_bf16 v[48:51], v[168:171], v[176:179], v[48:51]
	v_mfma_f32_16x16x32_bf16 v[36:39], v[160:163], v[186:189], v[36:39]
	v_mfma_f32_16x16x32_bf16 v[32:35], v[168:171], v[186:189], v[32:35]
	v_mfma_f32_16x16x32_bf16 v[20:23], v[160:163], v[194:197], v[20:23]
	v_mfma_f32_16x16x32_bf16 v[16:19], v[168:171], v[194:197], v[16:19]
	v_mfma_f32_16x16x32_bf16 v[4:7], v[160:163], v[202:205], v[4:7]
	v_mfma_f32_16x16x32_bf16 v[0:3], v[168:171], v[202:205], v[0:3]
	s_setprio 0
	s_barrier
	s_add_i32 s34, s34, 2
	s_add_u32 s16, s16, 0x100
	s_addc_u32 s17, s17, 0
	s_cmp_ge_i32 s34, s30
	s_cbranch_scc0 .LBB0_667
	v_mov_b32_e32 v129, v127

.LBB0_878:
	s_mov_b64 s[6:7], s[54:55]
	ds_read_b128 v[140:143], v147
	ds_read_b128 v[150:153], v147 offset:1024
	ds_read_b128 v[154:157], v147 offset:2048
	ds_read_b128 v[158:161], v147 offset:3072
	ds_read_b128 v[162:165], v148
	ds_read_b128 v[166:169], v148 offset:1024
	ds_read_b128 v[170:173], v148 offset:2048
	ds_read_b128 v[174:177], v148 offset:3072
	s_add_u32 s5, s16, s6
	s_addc_u32 s8, s17, s7
	s_add_u32 s9, s5, 0x100
	s_addc_u32 s28, s8, 0
	s_add_u32 s6, s36, s6
	s_addc_u32 s7, s37, s7
	s_add_u32 s6, s6, 0x100
	s_addc_u32 s7, s7, 0
	s_cmp_eq_u32 s75, s4
	s_cselect_b32 s71, s65, s28
	s_cselect_b32 s70, s64, s9
	s_cselect_b32 s69, s67, s7
	s_cselect_b32 s68, s66, s6
	s_add_u32 s6, s5, 0x80080
	s_addc_u32 s7, s8, 0
	v_lshl_add_u64 v[178:179], s[6:7], 0, v[134:135]
	s_add_i32 m0, s23, 0xc000
	ds_read_b128 v[182:185], v149
	ds_read_b128 v[186:189], v149 offset:1024
	ds_read_b128 v[190:193], v149 offset:2048
	ds_read_b128 v[194:197], v149 offset:3072
	ds_read_b128 v[198:201], v149 offset:4096
	ds_read_b128 v[202:205], v149 offset:5120
	ds_read_b128 v[206:209], v149 offset:6144
	ds_read_b128 v[210:213], v149 offset:7168
	global_load_lds_dwordx4 v[178:179], off
	v_lshl_add_u64 v[178:179], s[6:7], 0, v[130:131]
	s_add_i32 m0, s23, 0xe000
	s_nop 0
	global_load_lds_dwordx4 v[178:179], off
	s_waitcnt vmcnt(8)
	s_waitcnt lgkmcnt(0)
	s_barrier
	s_setprio 1
	v_mfma_f32_16x16x32_bf16 v[120:123], v[140:143], v[182:185], v[120:123]
	v_mfma_f32_16x16x32_bf16 v[116:119], v[154:157], v[182:185], v[116:119]
	v_mfma_f32_16x16x32_bf16 v[108:111], v[140:143], v[190:193], v[108:111]
	v_mfma_f32_16x16x32_bf16 v[100:103], v[154:157], v[190:193], v[100:103]
	v_mfma_f32_16x16x32_bf16 v[92:95], v[140:143], v[198:201], v[92:95]
	v_mfma_f32_16x16x32_bf16 v[84:87], v[154:157], v[198:201], v[84:87]
	v_mfma_f32_16x16x32_bf16 v[76:79], v[140:143], v[206:209], v[76:79]
	v_mfma_f32_16x16x32_bf16 v[68:71], v[154:157], v[206:209], v[68:71]
	v_mfma_f32_16x16x32_bf16 v[120:123], v[150:153], v[186:189], v[120:123]
	v_mfma_f32_16x16x32_bf16 v[116:119], v[158:161], v[186:189], v[116:119]
	v_mfma_f32_16x16x32_bf16 v[108:111], v[150:153], v[194:197], v[108:111]
	v_mfma_f32_16x16x32_bf16 v[100:103], v[158:161], v[194:197], v[100:103]
	v_mfma_f32_16x16x32_bf16 v[92:95], v[150:153], v[202:205], v[92:95]
	v_mfma_f32_16x16x32_bf16 v[84:87], v[158:161], v[202:205], v[84:87]
	v_mfma_f32_16x16x32_bf16 v[76:79], v[150:153], v[210:213], v[76:79]
	v_mfma_f32_16x16x32_bf16 v[68:71], v[158:161], v[210:213], v[68:71]
	s_setprio 0
	s_setprio 1
	v_mfma_f32_16x16x32_bf16 v[124:127], v[162:165], v[182:185], v[124:127]
	v_mfma_f32_16x16x32_bf16 v[112:115], v[170:173], v[182:185], v[112:115]
	v_mfma_f32_16x16x32_bf16 v[104:107], v[162:165], v[190:193], v[104:107]
	v_mfma_f32_16x16x32_bf16 v[96:99], v[170:173], v[190:193], v[96:99]
	v_mfma_f32_16x16x32_bf16 v[88:91], v[162:165], v[198:201], v[88:91]
	v_mfma_f32_16x16x32_bf16 v[80:83], v[170:173], v[198:201], v[80:83]
	v_mfma_f32_16x16x32_bf16 v[72:75], v[162:165], v[206:209], v[72:75]
	v_mfma_f32_16x16x32_bf16 v[64:67], v[170:173], v[206:209], v[64:67]
	v_mfma_f32_16x16x32_bf16 v[124:127], v[166:169], v[186:189], v[124:127]
	v_mfma_f32_16x16x32_bf16 v[112:115], v[174:177], v[186:189], v[112:115]
	v_mfma_f32_16x16x32_bf16 v[104:107], v[166:169], v[194:197], v[104:107]
	v_mfma_f32_16x16x32_bf16 v[96:99], v[174:177], v[194:197], v[96:99]
	v_mfma_f32_16x16x32_bf16 v[88:91], v[166:169], v[202:205], v[88:91]
	v_mfma_f32_16x16x32_bf16 v[80:83], v[174:177], v[202:205], v[80:83]
	v_mfma_f32_16x16x32_bf16 v[72:75], v[166:169], v[210:213], v[72:75]
	v_mfma_f32_16x16x32_bf16 v[64:67], v[174:177], v[210:213], v[64:67]
	s_setprio 0
	s_barrier
	s_add_i32 s5, s76, s18
	v_lshl_add_u64 v[178:179], s[68:69], 0, v[132:133]
	s_mov_b32 m0, s5
	ds_read_b128 v[182:185], v149 offset:16384
	ds_read_b128 v[186:189], v149 offset:17408
	ds_read_b128 v[190:193], v149 offset:18432
	ds_read_b128 v[194:197], v149 offset:19456
	ds_read_b128 v[198:201], v149 offset:20480
	ds_read_b128 v[202:205], v149 offset:21504
	ds_read_b128 v[206:209], v149 offset:22528
	ds_read_b128 v[210:213], v149 offset:23552
	global_load_lds_dwordx4 v[178:179], off
	s_add_i32 m0, s5, 0x2000
	s_add_u32 s6, s68, 0x80000
	v_lshl_add_u64 v[214:215], s[68:69], 0, v[128:129]
	s_addc_u32 s7, s69, 0
	s_add_i32 s5, s77, s18
	global_load_lds_dwordx4 v[214:215], off
	v_lshl_add_u64 v[216:217], s[6:7], 0, v[132:133]
	s_mov_b32 m0, s5
	v_lshl_add_u64 v[218:219], s[70:71], 0, v[130:131]
	global_load_lds_dwordx4 v[216:217], off
	v_lshl_add_u64 v[216:217], s[6:7], 0, v[128:129]
	s_add_i32 m0, s5, 0x2000
	s_nop 0
	global_load_lds_dwordx4 v[216:217], off
	v_lshl_add_u64 v[216:217], s[70:71], 0, v[134:135]
	s_mov_b32 m0, s23
	s_nop 0
	global_load_lds_dwordx4 v[216:217], off
	s_mov_b32 m0, s30
	s_nop 0
	global_load_lds_dwordx4 v[218:219], off
	s_waitcnt vmcnt(8)
	s_waitcnt lgkmcnt(0)
	s_barrier
	s_setprio 1
	v_mfma_f32_16x16x32_bf16 v[60:63], v[140:143], v[182:185], v[60:63]
	v_mfma_f32_16x16x32_bf16 v[52:55], v[154:157], v[182:185], v[52:55]
	v_mfma_f32_16x16x32_bf16 v[44:47], v[140:143], v[190:193], v[44:47]
	v_mfma_f32_16x16x32_bf16 v[36:39], v[154:157], v[190:193], v[36:39]
	v_mfma_f32_16x16x32_bf16 v[28:31], v[140:143], v[198:201], v[28:31]
	v_mfma_f32_16x16x32_bf16 v[20:23], v[154:157], v[198:201], v[20:23]
	v_mfma_f32_16x16x32_bf16 v[12:15], v[140:143], v[206:209], v[12:15]
	v_mfma_f32_16x16x32_bf16 v[4:7], v[154:157], v[206:209], v[4:7]
	v_mfma_f32_16x16x32_bf16 v[60:63], v[150:153], v[186:189], v[60:63]
	v_mfma_f32_16x16x32_bf16 v[52:55], v[158:161], v[186:189], v[52:55]
	v_mfma_f32_16x16x32_bf16 v[44:47], v[150:153], v[194:197], v[44:47]
	v_mfma_f32_16x16x32_bf16 v[36:39], v[158:161], v[194:197], v[36:39]
	v_mfma_f32_16x16x32_bf16 v[28:31], v[150:153], v[202:205], v[28:31]
	v_mfma_f32_16x16x32_bf16 v[20:23], v[158:161], v[202:205], v[20:23]
	v_mfma_f32_16x16x32_bf16 v[12:15], v[150:153], v[210:213], v[12:15]
	v_mfma_f32_16x16x32_bf16 v[4:7], v[158:161], v[210:213], v[4:7]
	s_setprio 0
	s_setprio 1
	v_mfma_f32_16x16x32_bf16 v[56:59], v[162:165], v[182:185], v[56:59]
	v_mfma_f32_16x16x32_bf16 v[48:51], v[170:173], v[182:185], v[48:51]
	v_mfma_f32_16x16x32_bf16 v[40:43], v[162:165], v[190:193], v[40:43]
	v_mfma_f32_16x16x32_bf16 v[32:35], v[170:173], v[190:193], v[32:35]
	v_mfma_f32_16x16x32_bf16 v[24:27], v[162:165], v[198:201], v[24:27]
	v_mfma_f32_16x16x32_bf16 v[16:19], v[170:173], v[198:201], v[16:19]
	v_mfma_f32_16x16x32_bf16 v[8:11], v[162:165], v[206:209], v[8:11]
	v_mfma_f32_16x16x32_bf16 v[0:3], v[170:173], v[206:209], v[0:3]
	v_mfma_f32_16x16x32_bf16 v[56:59], v[166:169], v[186:189], v[56:59]
	v_mfma_f32_16x16x32_bf16 v[48:51], v[174:177], v[186:189], v[48:51]
	v_mfma_f32_16x16x32_bf16 v[40:43], v[166:169], v[194:197], v[40:43]
	v_mfma_f32_16x16x32_bf16 v[32:35], v[174:177], v[194:197], v[32:35]
	v_mfma_f32_16x16x32_bf16 v[24:27], v[166:169], v[202:205], v[24:27]
	v_mfma_f32_16x16x32_bf16 v[16:19], v[174:177], v[202:205], v[16:19]
	v_mfma_f32_16x16x32_bf16 v[8:11], v[166:169], v[210:213], v[8:11]
	v_mfma_f32_16x16x32_bf16 v[0:3], v[174:177], v[210:213], v[0:3]
	s_setprio 0
	s_barrier
	s_add_i32 s5, 0, 0x18000
	s_add_i32 s8, 0, 0x1c000
	v_add_u32_e32 v158, s5, v146
	v_add_u32_e32 v174, s8, v146
	ds_read_b128 v[140:143], v158
	ds_read_b128 v[150:153], v158 offset:1024
	ds_read_b128 v[154:157], v158 offset:2048
	ds_read_b128 v[158:161], v158 offset:3072
	ds_read_b128 v[162:165], v174
	ds_read_b128 v[166:169], v174 offset:1024
	ds_read_b128 v[170:173], v174 offset:2048
	ds_read_b128 v[174:177], v174 offset:3072
	s_add_u32 s6, s70, 0x80000
	s_addc_u32 s7, s71, 0
	s_mov_b32 m0, s31
	v_lshl_add_u64 v[220:221], s[6:7], 0, v[134:135]
	ds_read_b128 v[182:185], v149 offset:32768
	ds_read_b128 v[186:189], v149 offset:33792
	ds_read_b128 v[190:193], v149 offset:34816
	ds_read_b128 v[194:197], v149 offset:35840
	ds_read_b128 v[198:201], v149 offset:36864
	ds_read_b128 v[202:205], v149 offset:37888
	ds_read_b128 v[206:209], v149 offset:38912
	ds_read_b128 v[210:213], v149 offset:39936
	global_load_lds_dwordx4 v[220:221], off
	v_lshl_add_u64 v[220:221], s[6:7], 0, v[130:131]
	s_mov_b32 m0, s56
	s_nop 0
	global_load_lds_dwordx4 v[220:221], off
	s_waitcnt vmcnt(8)
	s_waitcnt lgkmcnt(0)
	s_barrier
	s_setprio 1
	v_mfma_f32_16x16x32_bf16 v[120:123], v[140:143], v[182:185], v[120:123]
	v_mfma_f32_16x16x32_bf16 v[116:119], v[154:157], v[182:185], v[116:119]
	v_mfma_f32_16x16x32_bf16 v[108:111], v[140:143], v[190:193], v[108:111]
	v_mfma_f32_16x16x32_bf16 v[100:103], v[154:157], v[190:193], v[100:103]
	v_mfma_f32_16x16x32_bf16 v[92:95], v[140:143], v[198:201], v[92:95]
	v_mfma_f32_16x16x32_bf16 v[84:87], v[154:157], v[198:201], v[84:87]
	v_mfma_f32_16x16x32_bf16 v[76:79], v[140:143], v[206:209], v[76:79]
	v_mfma_f32_16x16x32_bf16 v[68:71], v[154:157], v[206:209], v[68:71]
	v_mfma_f32_16x16x32_bf16 v[120:123], v[150:153], v[186:189], v[120:123]
	v_mfma_f32_16x16x32_bf16 v[116:119], v[158:161], v[186:189], v[116:119]
	v_mfma_f32_16x16x32_bf16 v[108:111], v[150:153], v[194:197], v[108:111]
	v_mfma_f32_16x16x32_bf16 v[100:103], v[158:161], v[194:197], v[100:103]
	v_mfma_f32_16x16x32_bf16 v[92:95], v[150:153], v[202:205], v[92:95]
	v_mfma_f32_16x16x32_bf16 v[84:87], v[158:161], v[202:205], v[84:87]
	v_mfma_f32_16x16x32_bf16 v[76:79], v[150:153], v[210:213], v[76:79]
	v_mfma_f32_16x16x32_bf16 v[68:71], v[158:161], v[210:213], v[68:71]
	s_setprio 0
	s_setprio 1
	v_mfma_f32_16x16x32_bf16 v[124:127], v[162:165], v[182:185], v[124:127]
	v_mfma_f32_16x16x32_bf16 v[112:115], v[170:173], v[182:185], v[112:115]
	v_mfma_f32_16x16x32_bf16 v[104:107], v[162:165], v[190:193], v[104:107]
	v_mfma_f32_16x16x32_bf16 v[96:99], v[170:173], v[190:193], v[96:99]
	v_mfma_f32_16x16x32_bf16 v[88:91], v[162:165], v[198:201], v[88:91]
	v_mfma_f32_16x16x32_bf16 v[80:83], v[170:173], v[198:201], v[80:83]
	v_mfma_f32_16x16x32_bf16 v[72:75], v[162:165], v[206:209], v[72:75]
	v_mfma_f32_16x16x32_bf16 v[64:67], v[170:173], v[206:209], v[64:67]
	v_mfma_f32_16x16x32_bf16 v[124:127], v[166:169], v[186:189], v[124:127]
	v_mfma_f32_16x16x32_bf16 v[112:115], v[174:177], v[186:189], v[112:115]
	v_mfma_f32_16x16x32_bf16 v[104:107], v[166:169], v[194:197], v[104:107]
	v_mfma_f32_16x16x32_bf16 v[96:99], v[174:177], v[194:197], v[96:99]
	v_mfma_f32_16x16x32_bf16 v[88:91], v[166:169], v[202:205], v[88:91]
	v_mfma_f32_16x16x32_bf16 v[80:83], v[174:177], v[202:205], v[80:83]
	v_mfma_f32_16x16x32_bf16 v[72:75], v[166:169], v[210:213], v[72:75]
	v_mfma_f32_16x16x32_bf16 v[64:67], v[174:177], v[210:213], v[64:67]
	s_setprio 0
	s_barrier
	s_add_i32 s5, s5, s18
	v_lshl_add_u64 v[178:179], v[178:179], 0, s[34:35]
	s_mov_b32 m0, s5
	ds_read_b128 v[182:185], v149 offset:49152
	ds_read_b128 v[186:189], v149 offset:50176
	ds_read_b128 v[190:193], v149 offset:51200
	ds_read_b128 v[194:197], v149 offset:52224
	ds_read_b128 v[198:201], v149 offset:53248
	ds_read_b128 v[202:205], v149 offset:54272
	ds_read_b128 v[206:209], v149 offset:55296
	ds_read_b128 v[210:213], v149 offset:56320
	global_load_lds_dwordx4 v[178:179], off
	s_add_i32 m0, s5, 0x2000
	s_add_u32 s6, s68, 0x80080
	v_lshl_add_u64 v[178:179], v[214:215], 0, s[34:35]
	s_addc_u32 s7, s69, 0
	s_add_i32 s5, s8, s18
	global_load_lds_dwordx4 v[178:179], off
	v_lshl_add_u64 v[178:179], s[6:7], 0, v[132:133]
	s_mov_b32 m0, s5
	s_nop 0
	global_load_lds_dwordx4 v[178:179], off
	v_lshl_add_u64 v[178:179], s[6:7], 0, v[128:129]
	s_add_i32 m0, s5, 0x2000
	s_nop 0
	global_load_lds_dwordx4 v[178:179], off
	v_lshl_add_u64 v[178:179], v[216:217], 0, s[34:35]
	s_mov_b32 m0, s73
	s_nop 0
	global_load_lds_dwordx4 v[178:179], off
	v_lshl_add_u64 v[178:179], v[218:219], 0, s[34:35]
	s_mov_b32 m0, s74
	s_nop 0
	global_load_lds_dwordx4 v[178:179], off
	s_waitcnt vmcnt(8)
	s_waitcnt lgkmcnt(0)
	s_barrier
	s_setprio 1
	v_mfma_f32_16x16x32_bf16 v[60:63], v[140:143], v[182:185], v[60:63]
	v_mfma_f32_16x16x32_bf16 v[52:55], v[154:157], v[182:185], v[52:55]
	v_mfma_f32_16x16x32_bf16 v[44:47], v[140:143], v[190:193], v[44:47]
	v_mfma_f32_16x16x32_bf16 v[36:39], v[154:157], v[190:193], v[36:39]
	v_mfma_f32_16x16x32_bf16 v[28:31], v[140:143], v[198:201], v[28:31]
	v_mfma_f32_16x16x32_bf16 v[20:23], v[154:157], v[198:201], v[20:23]
	v_mfma_f32_16x16x32_bf16 v[12:15], v[140:143], v[206:209], v[12:15]
	v_mfma_f32_16x16x32_bf16 v[4:7], v[154:157], v[206:209], v[4:7]
	v_mfma_f32_16x16x32_bf16 v[60:63], v[150:153], v[186:189], v[60:63]
	v_mfma_f32_16x16x32_bf16 v[52:55], v[158:161], v[186:189], v[52:55]
	v_mfma_f32_16x16x32_bf16 v[44:47], v[150:153], v[194:197], v[44:47]
	v_mfma_f32_16x16x32_bf16 v[36:39], v[158:161], v[194:197], v[36:39]
	v_mfma_f32_16x16x32_bf16 v[28:31], v[150:153], v[202:205], v[28:31]
	v_mfma_f32_16x16x32_bf16 v[20:23], v[158:161], v[202:205], v[20:23]
	v_mfma_f32_16x16x32_bf16 v[12:15], v[150:153], v[210:213], v[12:15]
	v_mfma_f32_16x16x32_bf16 v[4:7], v[158:161], v[210:213], v[4:7]
	s_setprio 0
	s_setprio 1
	v_mfma_f32_16x16x32_bf16 v[56:59], v[162:165], v[182:185], v[56:59]
	v_mfma_f32_16x16x32_bf16 v[48:51], v[170:173], v[182:185], v[48:51]
	v_mfma_f32_16x16x32_bf16 v[40:43], v[162:165], v[190:193], v[40:43]
	v_mfma_f32_16x16x32_bf16 v[32:35], v[170:173], v[190:193], v[32:35]
	v_mfma_f32_16x16x32_bf16 v[24:27], v[162:165], v[198:201], v[24:27]
	v_mfma_f32_16x16x32_bf16 v[16:19], v[170:173], v[198:201], v[16:19]
	v_mfma_f32_16x16x32_bf16 v[8:11], v[162:165], v[206:209], v[8:11]
	v_mfma_f32_16x16x32_bf16 v[0:3], v[170:173], v[206:209], v[0:3]
	v_mfma_f32_16x16x32_bf16 v[56:59], v[166:169], v[186:189], v[56:59]
	v_mfma_f32_16x16x32_bf16 v[48:51], v[174:177], v[186:189], v[48:51]
	v_mfma_f32_16x16x32_bf16 v[40:43], v[166:169], v[194:197], v[40:43]
	v_mfma_f32_16x16x32_bf16 v[32:35], v[174:177], v[194:197], v[32:35]
	v_mfma_f32_16x16x32_bf16 v[24:27], v[166:169], v[202:205], v[24:27]
	v_mfma_f32_16x16x32_bf16 v[16:19], v[174:177], v[202:205], v[16:19]
	v_mfma_f32_16x16x32_bf16 v[8:11], v[166:169], v[210:213], v[8:11]
	v_mfma_f32_16x16x32_bf16 v[0:3], v[174:177], v[210:213], v[0:3]
	s_setprio 0
	s_barrier
	s_add_i32 s4, s4, 2
	s_add_u32 s54, s54, 0x100
	s_addc_u32 s55, s55, 0
	s_cmp_ge_i32 s4, s57
	s_cbranch_scc0 .LBB0_878

.Lcoldzero_d0:
	v_mov_b32_e32 v161, 0
	v_mov_b32_e32 v160, 0
	v_mov_b32_e32 v163, 0
	v_mov_b32_e32 v162, 0
	v_mov_b32_e32 v159, 0
	v_mov_b32_e32 v158, 0
	v_mov_b32_e32 v157, 0
	v_mov_b32_e32 v156, 0
	v_mov_b32_e32 v139, 0
	v_mov_b32_e32 v138, 0
	v_mov_b32_e32 v141, 0
	v_mov_b32_e32 v140, 0
	v_mov_b32_e32 v143, 0
	v_mov_b32_e32 v142, 0
	v_mov_b32_e32 v145, 0
	v_mov_b32_e32 v144, 0
	v_mov_b32_e32 v121, 0
	v_mov_b32_e32 v120, 0
	v_mov_b32_e32 v119, 0
	v_mov_b32_e32 v118, 0
	v_mov_b32_e32 v117, 0
	v_mov_b32_e32 v116, 0
	v_mov_b32_e32 v115, 0
	v_mov_b32_e32 v114, 0
	v_mov_b32_e32 v97, 0
	v_mov_b32_e32 v96, 0
	v_mov_b32_e32 v99, 0
	v_mov_b32_e32 v98, 0
	v_mov_b32_e32 v101, 0
	v_mov_b32_e32 v100, 0
	v_mov_b32_e32 v103, 0
	v_mov_b32_e32 v102, 0
	v_mov_b32_e32 v171, 0
	v_mov_b32_e32 v170, 0
	v_mov_b32_e32 v169, 0
	v_mov_b32_e32 v168, 0
	v_mov_b32_e32 v167, 0
	v_mov_b32_e32 v166, 0
	v_mov_b32_e32 v165, 0
	v_mov_b32_e32 v164, 0
	v_mov_b32_e32 v147, 0
	v_mov_b32_e32 v146, 0
	v_mov_b32_e32 v149, 0
	v_mov_b32_e32 v148, 0
	v_mov_b32_e32 v151, 0
	v_mov_b32_e32 v150, 0
	v_mov_b32_e32 v153, 0
	v_mov_b32_e32 v152, 0
	v_mov_b32_e32 v137, 0
	v_mov_b32_e32 v136, 0
	v_mov_b32_e32 v127, 0
	v_mov_b32_e32 v126, 0
	v_mov_b32_e32 v125, 0
	v_mov_b32_e32 v124, 0
	v_mov_b32_e32 v123, 0
	v_mov_b32_e32 v122, 0
	v_mov_b32_e32 v105, 0
	v_mov_b32_e32 v104, 0
	v_mov_b32_e32 v107, 0
	v_mov_b32_e32 v106, 0
	v_mov_b32_e32 v109, 0
	v_mov_b32_e32 v108, 0
	v_mov_b32_e32 v111, 0
	v_mov_b32_e32 v110, 0
	v_mov_b32_e32 v87, 0
	v_mov_b32_e32 v86, 0
	v_mov_b32_e32 v85, 0
	v_mov_b32_e32 v84, 0
	v_mov_b32_e32 v83, 0
	v_mov_b32_e32 v82, 0
	v_mov_b32_e32 v81, 0
	v_mov_b32_e32 v80, 0
	v_mov_b32_e32 v65, 0
	v_mov_b32_e32 v64, 0
	v_mov_b32_e32 v67, 0
	v_mov_b32_e32 v66, 0
	v_mov_b32_e32 v69, 0
	v_mov_b32_e32 v68, 0
	v_mov_b32_e32 v71, 0
	v_mov_b32_e32 v70, 0
	v_mov_b32_e32 v55, 0
	v_mov_b32_e32 v54, 0
	v_mov_b32_e32 v53, 0
	v_mov_b32_e32 v52, 0
	v_mov_b32_e32 v51, 0
	v_mov_b32_e32 v50, 0
	v_mov_b32_e32 v49, 0
	v_mov_b32_e32 v48, 0
	v_mov_b32_e32 v33, 0
	v_mov_b32_e32 v32, 0
	v_mov_b32_e32 v35, 0
	v_mov_b32_e32 v34, 0
	v_mov_b32_e32 v37, 0
	v_mov_b32_e32 v36, 0
	v_mov_b32_e32 v39, 0
	v_mov_b32_e32 v38, 0
	v_mov_b32_e32 v95, 0
	v_mov_b32_e32 v94, 0
	v_mov_b32_e32 v93, 0
	v_mov_b32_e32 v92, 0
	v_mov_b32_e32 v91, 0
	v_mov_b32_e32 v90, 0
	v_mov_b32_e32 v89, 0
	v_mov_b32_e32 v88, 0
	v_mov_b32_e32 v73, 0
	v_mov_b32_e32 v72, 0
	v_mov_b32_e32 v75, 0
	v_mov_b32_e32 v74, 0
	v_mov_b32_e32 v77, 0
	v_mov_b32_e32 v76, 0
	v_mov_b32_e32 v79, 0
	v_mov_b32_e32 v78, 0
	v_mov_b32_e32 v63, 0
	v_mov_b32_e32 v62, 0
	v_mov_b32_e32 v61, 0
	v_mov_b32_e32 v60, 0
	v_mov_b32_e32 v59, 0
	v_mov_b32_e32 v58, 0
	v_mov_b32_e32 v57, 0
	v_mov_b32_e32 v56, 0
	v_mov_b32_e32 v41, 0
	v_mov_b32_e32 v40, 0
	v_mov_b32_e32 v43, 0
	v_mov_b32_e32 v42, 0
	v_mov_b32_e32 v45, 0
	v_mov_b32_e32 v44, 0
	v_mov_b32_e32 v47, 0
	v_mov_b32_e32 v46, 0
	s_branch .LBB0_953

.LBB0_949:
	s_add_u32 s6, s20, s38
	s_addc_u32 s7, s21, s39
	s_and_b64 s[4:5], s[12:13], exec
	v_readlane_b32 s4, v255, 24
	s_cselect_b32 s59, s7, s3
	s_cselect_b32 s58, s6, s2
	v_readlane_b32 s5, v255, 25
	s_add_u32 s6, s4, s52
	s_addc_u32 s7, s5, s53
	s_and_b64 s[4:5], s[12:13], exec
	s_cselect_b32 s61, s7, s17
	s_cselect_b32 s60, s6, s16
	s_and_b64 vcc, exec, s[10:11]
	s_cbranch_vccnz .Lcoldzero_d0
	v_mov_b64_e32 v[0:1], 0
	s_mov_b32 s4, 0
	s_mov_b64 s[36:37], 0
	v_mov_b64_e32 v[2:3], 0
	v_mov_b64_e32 v[4:5], 0
	v_mov_b64_e32 v[6:7], 0
	v_mov_b64_e32 v[8:9], 0
	v_mov_b64_e32 v[10:11], 0
	v_mov_b64_e32 v[12:13], 0
	v_mov_b64_e32 v[14:15], 0
	v_mov_b64_e32 v[16:17], 0
	v_mov_b64_e32 v[18:19], 0
	v_mov_b64_e32 v[20:21], 0
	v_mov_b64_e32 v[22:23], 0
	v_mov_b64_e32 v[24:25], 0
	v_mov_b64_e32 v[26:27], 0
	v_mov_b64_e32 v[28:29], 0
	v_mov_b64_e32 v[30:31], 0
	v_mov_b64_e32 v[32:33], 0
	v_mov_b64_e32 v[34:35], 0
	v_mov_b64_e32 v[36:37], 0
	v_mov_b64_e32 v[38:39], 0
	v_mov_b64_e32 v[40:41], 0
	v_mov_b64_e32 v[42:43], 0
	v_mov_b64_e32 v[44:45], 0
	v_mov_b64_e32 v[46:47], 0
	v_mov_b64_e32 v[48:49], 0
	v_mov_b64_e32 v[50:51], 0
	v_mov_b64_e32 v[52:53], 0
	v_mov_b64_e32 v[54:55], 0
	v_mov_b64_e32 v[56:57], 0
	v_mov_b64_e32 v[58:59], 0
	v_mov_b64_e32 v[60:61], 0
	v_mov_b64_e32 v[62:63], 0
	v_mov_b64_e32 v[64:65], 0
	v_mov_b64_e32 v[66:67], 0
	v_mov_b64_e32 v[68:69], 0
	v_mov_b64_e32 v[70:71], 0
	v_mov_b64_e32 v[72:73], 0
	v_mov_b64_e32 v[74:75], 0
	v_mov_b64_e32 v[76:77], 0
	v_mov_b64_e32 v[78:79], 0
	v_mov_b64_e32 v[80:81], 0
	v_mov_b64_e32 v[82:83], 0
	v_mov_b64_e32 v[84:85], 0
	v_mov_b64_e32 v[86:87], 0
	v_mov_b64_e32 v[88:89], 0
	v_mov_b64_e32 v[90:91], 0
	v_mov_b64_e32 v[92:93], 0
	v_mov_b64_e32 v[94:95], 0
	v_mov_b64_e32 v[96:97], 0
	v_mov_b64_e32 v[98:99], 0
	v_mov_b64_e32 v[100:101], 0
	v_mov_b64_e32 v[102:103], 0
	v_mov_b64_e32 v[104:105], 0
	v_mov_b64_e32 v[106:107], 0
	v_mov_b64_e32 v[108:109], 0
	v_mov_b64_e32 v[110:111], 0
	v_mov_b64_e32 v[112:113], 0
	v_mov_b64_e32 v[114:115], 0
	v_mov_b64_e32 v[116:117], 0
	v_mov_b64_e32 v[118:119], 0
	v_mov_b64_e32 v[120:121], 0
	v_mov_b64_e32 v[122:123], 0
	v_mov_b64_e32 v[124:125], 0
	v_mov_b64_e32 v[126:127], 0
.LBB0_951:
	s_mov_b64 s[6:7], s[36:37]
	ds_read_b128 v[136:139], v183
	ds_read_b128 v[140:143], v183 offset:1024
	ds_read_b128 v[144:147], v183 offset:2048
	ds_read_b128 v[148:151], v183 offset:3072
	ds_read_b128 v[152:155], v184
	ds_read_b128 v[156:159], v184 offset:1024
	ds_read_b128 v[160:163], v184 offset:2048
	ds_read_b128 v[164:167], v184 offset:3072
	s_add_u32 s5, s2, s6
	s_addc_u32 s8, s3, s7
	s_add_u32 s9, s5, 0x100
	s_addc_u32 s28, s8, 0
	s_add_u32 s6, s16, s6
	s_addc_u32 s7, s17, s7
	s_add_u32 s6, s6, 0x100
	s_addc_u32 s7, s7, 0
	s_cmp_eq_u32 s70, s4
	s_cselect_b32 s63, s59, s28
	s_cselect_b32 s62, s58, s9
	s_cselect_b32 s55, s61, s7
	s_cselect_b32 s54, s60, s6
	s_add_u32 s6, s5, 0x160080
	s_addc_u32 s7, s8, 0
	v_lshl_add_u64 v[176:177], s[6:7], 0, v[128:129]
	s_add_i32 m0, s31, 0xc000
	ds_read_b128 v[168:171], v185
	ds_read_b128 v[172:175], v185 offset:1024
	ds_read_b128 v[186:189], v185 offset:2048
	ds_read_b128 v[190:193], v185 offset:3072
	ds_read_b128 v[194:197], v185 offset:4096
	ds_read_b128 v[198:201], v185 offset:5120
	ds_read_b128 v[202:205], v185 offset:6144
	ds_read_b128 v[206:209], v185 offset:7168
	global_load_lds_dwordx4 v[176:177], off
	v_lshl_add_u64 v[176:177], s[6:7], 0, v[130:131]
	s_add_i32 m0, s31, 0xe000
	s_nop 0
	global_load_lds_dwordx4 v[176:177], off
	s_waitcnt vmcnt(8)
	s_waitcnt lgkmcnt(0)
	s_barrier
	s_setprio 1
	v_mfma_f32_16x16x32_bf16 v[124:127], v[136:139], v[168:171], v[124:127]
	v_mfma_f32_16x16x32_bf16 v[120:123], v[144:147], v[168:171], v[120:123]
	v_mfma_f32_16x16x32_bf16 v[116:119], v[136:139], v[186:189], v[116:119]
	v_mfma_f32_16x16x32_bf16 v[112:115], v[144:147], v[186:189], v[112:115]
	v_mfma_f32_16x16x32_bf16 v[104:107], v[136:139], v[194:197], v[104:107]
	v_mfma_f32_16x16x32_bf16 v[96:99], v[144:147], v[194:197], v[96:99]
	v_mfma_f32_16x16x32_bf16 v[88:91], v[136:139], v[202:205], v[88:91]
	v_mfma_f32_16x16x32_bf16 v[80:83], v[144:147], v[202:205], v[80:83]
	v_mfma_f32_16x16x32_bf16 v[124:127], v[140:143], v[172:175], v[124:127]
	v_mfma_f32_16x16x32_bf16 v[120:123], v[148:151], v[172:175], v[120:123]
	v_mfma_f32_16x16x32_bf16 v[116:119], v[140:143], v[190:193], v[116:119]
	v_mfma_f32_16x16x32_bf16 v[112:115], v[148:151], v[190:193], v[112:115]
	v_mfma_f32_16x16x32_bf16 v[104:107], v[140:143], v[198:201], v[104:107]
	v_mfma_f32_16x16x32_bf16 v[96:99], v[148:151], v[198:201], v[96:99]
	v_mfma_f32_16x16x32_bf16 v[88:91], v[140:143], v[206:209], v[88:91]
	v_mfma_f32_16x16x32_bf16 v[80:83], v[148:151], v[206:209], v[80:83]
	s_setprio 0
	s_setprio 1
	v_mfma_f32_16x16x32_bf16 v[108:111], v[152:155], v[168:171], v[108:111]
	v_mfma_f32_16x16x32_bf16 v[100:103], v[160:163], v[168:171], v[100:103]
	v_mfma_f32_16x16x32_bf16 v[92:95], v[152:155], v[186:189], v[92:95]
	v_mfma_f32_16x16x32_bf16 v[84:87], v[160:163], v[186:189], v[84:87]
	v_mfma_f32_16x16x32_bf16 v[76:79], v[152:155], v[194:197], v[76:79]
	v_mfma_f32_16x16x32_bf16 v[72:75], v[160:163], v[194:197], v[72:75]
	v_mfma_f32_16x16x32_bf16 v[68:71], v[152:155], v[202:205], v[68:71]
	v_mfma_f32_16x16x32_bf16 v[64:67], v[160:163], v[202:205], v[64:67]
	v_mfma_f32_16x16x32_bf16 v[108:111], v[156:159], v[172:175], v[108:111]
	v_mfma_f32_16x16x32_bf16 v[100:103], v[164:167], v[172:175], v[100:103]
	v_mfma_f32_16x16x32_bf16 v[92:95], v[156:159], v[190:193], v[92:95]
	v_mfma_f32_16x16x32_bf16 v[84:87], v[164:167], v[190:193], v[84:87]
	v_mfma_f32_16x16x32_bf16 v[76:79], v[156:159], v[198:201], v[76:79]
	v_mfma_f32_16x16x32_bf16 v[72:75], v[164:167], v[198:201], v[72:75]
	v_mfma_f32_16x16x32_bf16 v[68:71], v[156:159], v[206:209], v[68:71]
	v_mfma_f32_16x16x32_bf16 v[64:67], v[164:167], v[206:209], v[64:67]
	s_setprio 0
	s_barrier
	s_add_i32 s5, s71, s30
	v_lshl_add_u64 v[176:177], s[54:55], 0, v[128:129]
	s_mov_b32 m0, s5
	ds_read_b128 v[168:171], v185 offset:16384
	ds_read_b128 v[172:175], v185 offset:17408
	ds_read_b128 v[186:189], v185 offset:18432
	ds_read_b128 v[190:193], v185 offset:19456
	ds_read_b128 v[194:197], v185 offset:20480
	ds_read_b128 v[198:201], v185 offset:21504
	ds_read_b128 v[202:205], v185 offset:22528
	ds_read_b128 v[206:209], v185 offset:23552
	global_load_lds_dwordx4 v[176:177], off
	s_add_i32 m0, s5, 0x2000
	s_add_u32 s6, s54, 0x160000
	v_lshl_add_u64 v[210:211], s[54:55], 0, v[130:131]
	s_addc_u32 s7, s55, 0
	s_add_i32 s5, s72, s30
	global_load_lds_dwordx4 v[210:211], off
	v_lshl_add_u64 v[212:213], s[6:7], 0, v[128:129]
	s_mov_b32 m0, s5
	v_lshl_add_u64 v[214:215], s[62:63], 0, v[130:131]
	global_load_lds_dwordx4 v[212:213], off
	v_lshl_add_u64 v[212:213], s[6:7], 0, v[130:131]
	s_add_i32 m0, s5, 0x2000
	s_nop 0
	global_load_lds_dwordx4 v[212:213], off
	v_lshl_add_u64 v[212:213], s[62:63], 0, v[128:129]
	s_mov_b32 m0, s31
	s_nop 0
	global_load_lds_dwordx4 v[212:213], off
	s_mov_b32 m0, s56
	s_nop 0
	global_load_lds_dwordx4 v[214:215], off
	s_waitcnt vmcnt(8)
	s_waitcnt lgkmcnt(0)
	s_barrier
	s_setprio 1
	v_mfma_f32_16x16x32_bf16 v[60:63], v[136:139], v[168:171], v[60:63]
	v_mfma_f32_16x16x32_bf16 v[56:59], v[144:147], v[168:171], v[56:59]
	v_mfma_f32_16x16x32_bf16 v[52:55], v[136:139], v[186:189], v[52:55]
	v_mfma_f32_16x16x32_bf16 v[48:51], v[144:147], v[186:189], v[48:51]
	v_mfma_f32_16x16x32_bf16 v[40:43], v[136:139], v[194:197], v[40:43]
	v_mfma_f32_16x16x32_bf16 v[32:35], v[144:147], v[194:197], v[32:35]
	v_mfma_f32_16x16x32_bf16 v[24:27], v[136:139], v[202:205], v[24:27]
	v_mfma_f32_16x16x32_bf16 v[16:19], v[144:147], v[202:205], v[16:19]
	v_mfma_f32_16x16x32_bf16 v[60:63], v[140:143], v[172:175], v[60:63]
	v_mfma_f32_16x16x32_bf16 v[56:59], v[148:151], v[172:175], v[56:59]
	v_mfma_f32_16x16x32_bf16 v[52:55], v[140:143], v[190:193], v[52:55]
	v_mfma_f32_16x16x32_bf16 v[48:51], v[148:151], v[190:193], v[48:51]
	v_mfma_f32_16x16x32_bf16 v[40:43], v[140:143], v[198:201], v[40:43]
	v_mfma_f32_16x16x32_bf16 v[32:35], v[148:151], v[198:201], v[32:35]
	v_mfma_f32_16x16x32_bf16 v[24:27], v[140:143], v[206:209], v[24:27]
	v_mfma_f32_16x16x32_bf16 v[16:19], v[148:151], v[206:209], v[16:19]
	s_setprio 0
	s_setprio 1
	v_mfma_f32_16x16x32_bf16 v[44:47], v[152:155], v[168:171], v[44:47]
	v_mfma_f32_16x16x32_bf16 v[36:39], v[160:163], v[168:171], v[36:39]
	v_mfma_f32_16x16x32_bf16 v[28:31], v[152:155], v[186:189], v[28:31]
	v_mfma_f32_16x16x32_bf16 v[20:23], v[160:163], v[186:189], v[20:23]
	v_mfma_f32_16x16x32_bf16 v[12:15], v[152:155], v[194:197], v[12:15]
	v_mfma_f32_16x16x32_bf16 v[8:11], v[160:163], v[194:197], v[8:11]
	v_mfma_f32_16x16x32_bf16 v[4:7], v[152:155], v[202:205], v[4:7]
	v_mfma_f32_16x16x32_bf16 v[0:3], v[160:163], v[202:205], v[0:3]
	v_mfma_f32_16x16x32_bf16 v[44:47], v[156:159], v[172:175], v[44:47]
	v_mfma_f32_16x16x32_bf16 v[36:39], v[164:167], v[172:175], v[36:39]
	v_mfma_f32_16x16x32_bf16 v[28:31], v[156:159], v[190:193], v[28:31]
	v_mfma_f32_16x16x32_bf16 v[20:23], v[164:167], v[190:193], v[20:23]
	v_mfma_f32_16x16x32_bf16 v[12:15], v[156:159], v[198:201], v[12:15]
	v_mfma_f32_16x16x32_bf16 v[8:11], v[164:167], v[198:201], v[8:11]
	v_mfma_f32_16x16x32_bf16 v[4:7], v[156:159], v[206:209], v[4:7]
	v_mfma_f32_16x16x32_bf16 v[0:3], v[164:167], v[206:209], v[0:3]
	s_setprio 0
	s_barrier
	s_add_i32 s5, 0, 0x18000
	v_add_u32_e32 v132, s5, v182
	s_add_i32 s8, 0, 0x1c000
	ds_read_b128 v[136:139], v132
	ds_read_b128 v[140:143], v132 offset:1024
	ds_read_b128 v[144:147], v132 offset:2048
	ds_read_b128 v[148:151], v132 offset:3072
	v_add_u32_e32 v132, s8, v182
	ds_read_b128 v[152:155], v132
	ds_read_b128 v[156:159], v132 offset:1024
	ds_read_b128 v[160:163], v132 offset:2048
	ds_read_b128 v[164:167], v132 offset:3072
	s_add_u32 s6, s62, 0x160000
	s_addc_u32 s7, s63, 0
	s_mov_b32 m0, s57
	v_lshl_add_u64 v[216:217], s[6:7], 0, v[128:129]
	ds_read_b128 v[168:171], v185 offset:32768
	ds_read_b128 v[172:175], v185 offset:33792
	ds_read_b128 v[186:189], v185 offset:34816
	ds_read_b128 v[190:193], v185 offset:35840
	ds_read_b128 v[194:197], v185 offset:36864
	ds_read_b128 v[198:201], v185 offset:37888
	ds_read_b128 v[202:205], v185 offset:38912
	ds_read_b128 v[206:209], v185 offset:39936
	global_load_lds_dwordx4 v[216:217], off
	v_lshl_add_u64 v[216:217], s[6:7], 0, v[130:131]
	s_mov_b32 m0, s64
	s_nop 0
	global_load_lds_dwordx4 v[216:217], off
	s_waitcnt vmcnt(8)
	s_waitcnt lgkmcnt(0)
	s_barrier
	s_setprio 1
	v_mfma_f32_16x16x32_bf16 v[124:127], v[136:139], v[168:171], v[124:127]
	v_mfma_f32_16x16x32_bf16 v[120:123], v[144:147], v[168:171], v[120:123]
	v_mfma_f32_16x16x32_bf16 v[116:119], v[136:139], v[186:189], v[116:119]
	v_mfma_f32_16x16x32_bf16 v[112:115], v[144:147], v[186:189], v[112:115]
	v_mfma_f32_16x16x32_bf16 v[104:107], v[136:139], v[194:197], v[104:107]
	v_mfma_f32_16x16x32_bf16 v[96:99], v[144:147], v[194:197], v[96:99]
	v_mfma_f32_16x16x32_bf16 v[88:91], v[136:139], v[202:205], v[88:91]
	v_mfma_f32_16x16x32_bf16 v[80:83], v[144:147], v[202:205], v[80:83]
	v_mfma_f32_16x16x32_bf16 v[124:127], v[140:143], v[172:175], v[124:127]
	v_mfma_f32_16x16x32_bf16 v[120:123], v[148:151], v[172:175], v[120:123]
	v_mfma_f32_16x16x32_bf16 v[116:119], v[140:143], v[190:193], v[116:119]
	v_mfma_f32_16x16x32_bf16 v[112:115], v[148:151], v[190:193], v[112:115]
	v_mfma_f32_16x16x32_bf16 v[104:107], v[140:143], v[198:201], v[104:107]
	v_mfma_f32_16x16x32_bf16 v[96:99], v[148:151], v[198:201], v[96:99]
	v_mfma_f32_16x16x32_bf16 v[88:91], v[140:143], v[206:209], v[88:91]
	v_mfma_f32_16x16x32_bf16 v[80:83], v[148:151], v[206:209], v[80:83]
	s_setprio 0
	s_setprio 1
	v_mfma_f32_16x16x32_bf16 v[108:111], v[152:155], v[168:171], v[108:111]
	v_mfma_f32_16x16x32_bf16 v[100:103], v[160:163], v[168:171], v[100:103]
	v_mfma_f32_16x16x32_bf16 v[92:95], v[152:155], v[186:189], v[92:95]
	v_mfma_f32_16x16x32_bf16 v[84:87], v[160:163], v[186:189], v[84:87]
	v_mfma_f32_16x16x32_bf16 v[76:79], v[152:155], v[194:197], v[76:79]
	v_mfma_f32_16x16x32_bf16 v[72:75], v[160:163], v[194:197], v[72:75]
	v_mfma_f32_16x16x32_bf16 v[68:71], v[152:155], v[202:205], v[68:71]
	v_mfma_f32_16x16x32_bf16 v[64:67], v[160:163], v[202:205], v[64:67]
	v_mfma_f32_16x16x32_bf16 v[108:111], v[156:159], v[172:175], v[108:111]
	v_mfma_f32_16x16x32_bf16 v[100:103], v[164:167], v[172:175], v[100:103]
	v_mfma_f32_16x16x32_bf16 v[92:95], v[156:159], v[190:193], v[92:95]
	v_mfma_f32_16x16x32_bf16 v[84:87], v[164:167], v[190:193], v[84:87]
	v_mfma_f32_16x16x32_bf16 v[76:79], v[156:159], v[198:201], v[76:79]
	v_mfma_f32_16x16x32_bf16 v[72:75], v[164:167], v[198:201], v[72:75]
	v_mfma_f32_16x16x32_bf16 v[68:71], v[156:159], v[206:209], v[68:71]
	v_mfma_f32_16x16x32_bf16 v[64:67], v[164:167], v[206:209], v[64:67]
	s_setprio 0
	s_barrier
	s_add_i32 s5, s5, s30
	v_lshl_add_u64 v[176:177], v[176:177], 0, s[14:15]
	s_mov_b32 m0, s5
	ds_read_b128 v[168:171], v185 offset:49152
	ds_read_b128 v[172:175], v185 offset:50176
	ds_read_b128 v[186:189], v185 offset:51200
	ds_read_b128 v[190:193], v185 offset:52224
	ds_read_b128 v[194:197], v185 offset:53248
	ds_read_b128 v[198:201], v185 offset:54272
	ds_read_b128 v[202:205], v185 offset:55296
	ds_read_b128 v[206:209], v185 offset:56320
	global_load_lds_dwordx4 v[176:177], off
	s_add_i32 m0, s5, 0x2000
	s_add_u32 s6, s54, 0x160080
	v_lshl_add_u64 v[176:177], v[210:211], 0, s[14:15]
	s_addc_u32 s7, s55, 0
	s_add_i32 s5, s8, s30
	global_load_lds_dwordx4 v[176:177], off
	v_lshl_add_u64 v[176:177], s[6:7], 0, v[128:129]
	s_mov_b32 m0, s5
	s_nop 0
	global_load_lds_dwordx4 v[176:177], off
	v_lshl_add_u64 v[176:177], s[6:7], 0, v[130:131]
	s_add_i32 m0, s5, 0x2000
	s_nop 0
	global_load_lds_dwordx4 v[176:177], off
	v_lshl_add_u64 v[176:177], v[212:213], 0, s[14:15]
	s_mov_b32 m0, s68
	s_nop 0
	global_load_lds_dwordx4 v[176:177], off
	v_lshl_add_u64 v[176:177], v[214:215], 0, s[14:15]
	s_mov_b32 m0, s69
	s_nop 0
	global_load_lds_dwordx4 v[176:177], off
	s_waitcnt vmcnt(8)
	s_waitcnt lgkmcnt(0)
	s_barrier
	s_setprio 1
	v_mfma_f32_16x16x32_bf16 v[60:63], v[136:139], v[168:171], v[60:63]
	v_mfma_f32_16x16x32_bf16 v[56:59], v[144:147], v[168:171], v[56:59]
	v_mfma_f32_16x16x32_bf16 v[52:55], v[136:139], v[186:189], v[52:55]
	v_mfma_f32_16x16x32_bf16 v[48:51], v[144:147], v[186:189], v[48:51]
	v_mfma_f32_16x16x32_bf16 v[40:43], v[136:139], v[194:197], v[40:43]
	v_mfma_f32_16x16x32_bf16 v[32:35], v[144:147], v[194:197], v[32:35]
	v_mfma_f32_16x16x32_bf16 v[24:27], v[136:139], v[202:205], v[24:27]
	v_mfma_f32_16x16x32_bf16 v[16:19], v[144:147], v[202:205], v[16:19]
	v_mfma_f32_16x16x32_bf16 v[60:63], v[140:143], v[172:175], v[60:63]
	v_mfma_f32_16x16x32_bf16 v[56:59], v[148:151], v[172:175], v[56:59]
	v_mfma_f32_16x16x32_bf16 v[52:55], v[140:143], v[190:193], v[52:55]
	v_mfma_f32_16x16x32_bf16 v[48:51], v[148:151], v[190:193], v[48:51]
	v_mfma_f32_16x16x32_bf16 v[40:43], v[140:143], v[198:201], v[40:43]
	v_mfma_f32_16x16x32_bf16 v[32:35], v[148:151], v[198:201], v[32:35]
	v_mfma_f32_16x16x32_bf16 v[24:27], v[140:143], v[206:209], v[24:27]
	v_mfma_f32_16x16x32_bf16 v[16:19], v[148:151], v[206:209], v[16:19]
	s_setprio 0
	s_setprio 1
	v_mfma_f32_16x16x32_bf16 v[44:47], v[152:155], v[168:171], v[44:47]
	v_mfma_f32_16x16x32_bf16 v[36:39], v[160:163], v[168:171], v[36:39]
	v_mfma_f32_16x16x32_bf16 v[28:31], v[152:155], v[186:189], v[28:31]
	v_mfma_f32_16x16x32_bf16 v[20:23], v[160:163], v[186:189], v[20:23]
	v_mfma_f32_16x16x32_bf16 v[12:15], v[152:155], v[194:197], v[12:15]
	v_mfma_f32_16x16x32_bf16 v[8:11], v[160:163], v[194:197], v[8:11]
	v_mfma_f32_16x16x32_bf16 v[4:7], v[152:155], v[202:205], v[4:7]
	v_mfma_f32_16x16x32_bf16 v[0:3], v[160:163], v[202:205], v[0:3]
	v_mfma_f32_16x16x32_bf16 v[44:47], v[156:159], v[172:175], v[44:47]
	v_mfma_f32_16x16x32_bf16 v[36:39], v[164:167], v[172:175], v[36:39]
	v_mfma_f32_16x16x32_bf16 v[28:31], v[156:159], v[190:193], v[28:31]
	v_mfma_f32_16x16x32_bf16 v[20:23], v[164:167], v[190:193], v[20:23]
	v_mfma_f32_16x16x32_bf16 v[12:15], v[156:159], v[198:201], v[12:15]
	v_mfma_f32_16x16x32_bf16 v[8:11], v[164:167], v[198:201], v[8:11]
	v_mfma_f32_16x16x32_bf16 v[4:7], v[156:159], v[206:209], v[4:7]
	v_mfma_f32_16x16x32_bf16 v[0:3], v[164:167], v[206:209], v[0:3]
	s_setprio 0
	s_barrier
	s_add_i32 s4, s4, 2
	s_add_u32 s36, s36, 0x100
	s_addc_u32 s37, s37, 0
	s_cmp_ge_i32 s4, s65
	s_cbranch_scc0 .LBB0_951
	v_pk_add_f32 v[160:161], v[126:127], 0 op_sel_hi:[1,0]
	v_pk_add_f32 v[162:163], v[124:125], 0 op_sel_hi:[1,0]
	v_pk_add_f32 v[158:159], v[122:123], 0 op_sel_hi:[1,0]
	v_pk_add_f32 v[156:157], v[120:121], 0 op_sel_hi:[1,0]
	v_pk_add_f32 v[170:171], v[110:111], 0 op_sel_hi:[1,0]
	v_pk_add_f32 v[168:169], v[108:109], 0 op_sel_hi:[1,0]
	v_pk_add_f32 v[166:167], v[102:103], 0 op_sel_hi:[1,0]
	v_pk_add_f32 v[164:165], v[100:101], 0 op_sel_hi:[1,0]
	v_pk_add_f32 v[138:139], v[118:119], 0 op_sel_hi:[1,0]
	v_pk_add_f32 v[140:141], v[116:117], 0 op_sel_hi:[1,0]
	v_pk_add_f32 v[142:143], v[114:115], 0 op_sel_hi:[1,0]
	v_pk_add_f32 v[144:145], v[112:113], 0 op_sel_hi:[1,0]
	v_pk_add_f32 v[146:147], v[94:95], 0 op_sel_hi:[1,0]
	v_pk_add_f32 v[148:149], v[92:93], 0 op_sel_hi:[1,0]
	v_pk_add_f32 v[150:151], v[86:87], 0 op_sel_hi:[1,0]
	v_pk_add_f32 v[152:153], v[84:85], 0 op_sel_hi:[1,0]
	v_pk_add_f32 v[120:121], v[106:107], 0 op_sel_hi:[1,0]
	v_pk_add_f32 v[118:119], v[104:105], 0 op_sel_hi:[1,0]
	v_pk_add_f32 v[116:117], v[98:99], 0 op_sel_hi:[1,0]
	v_pk_add_f32 v[114:115], v[96:97], 0 op_sel_hi:[1,0]
	v_pk_add_f32 v[136:137], v[78:79], 0 op_sel_hi:[1,0]
	v_pk_add_f32 v[126:127], v[76:77], 0 op_sel_hi:[1,0]
	v_pk_add_f32 v[124:125], v[74:75], 0 op_sel_hi:[1,0]
	v_pk_add_f32 v[122:123], v[72:73], 0 op_sel_hi:[1,0]
	v_pk_add_f32 v[96:97], v[90:91], 0 op_sel_hi:[1,0]
	v_pk_add_f32 v[98:99], v[88:89], 0 op_sel_hi:[1,0]
	v_pk_add_f32 v[100:101], v[82:83], 0 op_sel_hi:[1,0]
	v_pk_add_f32 v[102:103], v[80:81], 0 op_sel_hi:[1,0]
	v_pk_add_f32 v[104:105], v[70:71], 0 op_sel_hi:[1,0]
	v_pk_add_f32 v[106:107], v[68:69], 0 op_sel_hi:[1,0]
	v_pk_add_f32 v[108:109], v[66:67], 0 op_sel_hi:[1,0]
	v_pk_add_f32 v[110:111], v[64:65], 0 op_sel_hi:[1,0]
	v_pk_add_f32 v[86:87], v[62:63], 0 op_sel_hi:[1,0]
	v_pk_add_f32 v[84:85], v[60:61], 0 op_sel_hi:[1,0]
	v_pk_add_f32 v[82:83], v[58:59], 0 op_sel_hi:[1,0]
	v_pk_add_f32 v[80:81], v[56:57], 0 op_sel_hi:[1,0]
	v_pk_add_f32 v[94:95], v[46:47], 0 op_sel_hi:[1,0]
	v_pk_add_f32 v[92:93], v[44:45], 0 op_sel_hi:[1,0]
	v_pk_add_f32 v[90:91], v[38:39], 0 op_sel_hi:[1,0]
	v_pk_add_f32 v[88:89], v[36:37], 0 op_sel_hi:[1,0]
	v_pk_add_f32 v[64:65], v[54:55], 0 op_sel_hi:[1,0]
	v_pk_add_f32 v[66:67], v[52:53], 0 op_sel_hi:[1,0]
	v_pk_add_f32 v[68:69], v[50:51], 0 op_sel_hi:[1,0]
	v_pk_add_f32 v[70:71], v[48:49], 0 op_sel_hi:[1,0]
	v_pk_add_f32 v[72:73], v[30:31], 0 op_sel_hi:[1,0]
	v_pk_add_f32 v[74:75], v[28:29], 0 op_sel_hi:[1,0]
	v_pk_add_f32 v[76:77], v[22:23], 0 op_sel_hi:[1,0]
	v_pk_add_f32 v[78:79], v[20:21], 0 op_sel_hi:[1,0]
	v_pk_add_f32 v[54:55], v[42:43], 0 op_sel_hi:[1,0]
	v_pk_add_f32 v[52:53], v[40:41], 0 op_sel_hi:[1,0]
	v_pk_add_f32 v[50:51], v[34:35], 0 op_sel_hi:[1,0]
	v_pk_add_f32 v[48:49], v[32:33], 0 op_sel_hi:[1,0]
	v_pk_add_f32 v[62:63], v[14:15], 0 op_sel_hi:[1,0]
	v_pk_add_f32 v[60:61], v[12:13], 0 op_sel_hi:[1,0]
	v_pk_add_f32 v[58:59], v[10:11], 0 op_sel_hi:[1,0]
	v_pk_add_f32 v[56:57], v[8:9], 0 op_sel_hi:[1,0]
	v_pk_add_f32 v[32:33], v[26:27], 0 op_sel_hi:[1,0]
	v_pk_add_f32 v[34:35], v[24:25], 0 op_sel_hi:[1,0]
	v_pk_add_f32 v[36:37], v[18:19], 0 op_sel_hi:[1,0]
	v_pk_add_f32 v[38:39], v[16:17], 0 op_sel_hi:[1,0]
	v_pk_add_f32 v[40:41], v[6:7], 0 op_sel_hi:[1,0]
	v_pk_add_f32 v[42:43], v[4:5], 0 op_sel_hi:[1,0]
	v_pk_add_f32 v[44:45], v[2:3], 0 op_sel_hi:[1,0]
	v_pk_add_f32 v[46:47], v[0:1], 0 op_sel_hi:[1,0]

.LBB0_983:
	s_mov_b64 s[34:35], s[16:17]
	ds_read_b128 v[140:143], v134
	ds_read_b128 v[144:147], v134 offset:1024
	ds_read_b128 v[148:151], v134 offset:2048
	ds_read_b128 v[152:155], v134 offset:3072
	ds_read_b128 v[156:159], v135
	ds_read_b128 v[160:163], v135 offset:1024
	ds_read_b128 v[164:167], v135 offset:2048
	ds_read_b128 v[168:171], v135 offset:3072
	s_add_u32 s40, s0, s34
	s_addc_u32 s41, s1, s35
	s_add_u32 s36, s40, 0x100
	s_addc_u32 s37, s41, 0
	s_add_u32 s34, s2, s34
	s_addc_u32 s35, s3, s35
	s_add_u32 s34, s34, 0x100
	s_addc_u32 s35, s35, 0
	s_cmp_eq_u32 s39, s52
	s_cselect_b32 s37, s13, s37
	s_cselect_b32 s36, s12, s36
	s_cselect_b32 s35, s15, s35
	s_cselect_b32 s34, s14, s34
	s_add_u32 s40, s40, 0x160080
	s_addc_u32 s41, s41, 0
	s_mov_b32 m0, s53
	v_lshl_add_u64 v[206:207], s[40:41], 0, v[128:129]
	ds_read_b128 v[172:175], v136
	ds_read_b128 v[176:179], v136 offset:1024
	ds_read_b128 v[182:185], v136 offset:2048
	ds_read_b128 v[186:189], v136 offset:3072
	ds_read_b128 v[190:193], v136 offset:4096
	ds_read_b128 v[194:197], v136 offset:5120
	ds_read_b128 v[198:201], v136 offset:6144
	ds_read_b128 v[202:205], v136 offset:7168
	global_load_lds_dwordx4 v[206:207], off
	v_lshl_add_u64 v[206:207], s[40:41], 0, v[130:131]
	s_mov_b32 m0, s54
	s_nop 0
	global_load_lds_dwordx4 v[206:207], off
	s_waitcnt vmcnt(8)
	s_waitcnt lgkmcnt(0)
	s_barrier
	s_setprio 1
	v_mfma_f32_16x16x32_bf16 v[124:127], v[140:143], v[172:175], v[124:127]
	v_mfma_f32_16x16x32_bf16 v[120:123], v[148:151], v[172:175], v[120:123]
	v_mfma_f32_16x16x32_bf16 v[108:111], v[140:143], v[182:185], v[108:111]
	v_mfma_f32_16x16x32_bf16 v[104:107], v[148:151], v[182:185], v[104:107]
	v_mfma_f32_16x16x32_bf16 v[92:95], v[140:143], v[190:193], v[92:95]
	v_mfma_f32_16x16x32_bf16 v[88:91], v[148:151], v[190:193], v[88:91]
	v_mfma_f32_16x16x32_bf16 v[76:79], v[140:143], v[198:201], v[76:79]
	v_mfma_f32_16x16x32_bf16 v[72:75], v[148:151], v[198:201], v[72:75]
	v_mfma_f32_16x16x32_bf16 v[124:127], v[144:147], v[176:179], v[124:127]
	v_mfma_f32_16x16x32_bf16 v[120:123], v[152:155], v[176:179], v[120:123]
	v_mfma_f32_16x16x32_bf16 v[108:111], v[144:147], v[186:189], v[108:111]
	v_mfma_f32_16x16x32_bf16 v[104:107], v[152:155], v[186:189], v[104:107]
	v_mfma_f32_16x16x32_bf16 v[92:95], v[144:147], v[194:197], v[92:95]
	v_mfma_f32_16x16x32_bf16 v[88:91], v[152:155], v[194:197], v[88:91]
	v_mfma_f32_16x16x32_bf16 v[76:79], v[144:147], v[202:205], v[76:79]
	v_mfma_f32_16x16x32_bf16 v[72:75], v[152:155], v[202:205], v[72:75]
	s_setprio 0
	s_setprio 1
	v_mfma_f32_16x16x32_bf16 v[116:119], v[156:159], v[172:175], v[116:119]
	v_mfma_f32_16x16x32_bf16 v[112:115], v[164:167], v[172:175], v[112:115]
	v_mfma_f32_16x16x32_bf16 v[100:103], v[156:159], v[182:185], v[100:103]
	v_mfma_f32_16x16x32_bf16 v[96:99], v[164:167], v[182:185], v[96:99]
	v_mfma_f32_16x16x32_bf16 v[84:87], v[156:159], v[190:193], v[84:87]
	v_mfma_f32_16x16x32_bf16 v[80:83], v[164:167], v[190:193], v[80:83]
	v_mfma_f32_16x16x32_bf16 v[68:71], v[156:159], v[198:201], v[68:71]
	v_mfma_f32_16x16x32_bf16 v[64:67], v[164:167], v[198:201], v[64:67]
	v_mfma_f32_16x16x32_bf16 v[116:119], v[160:163], v[176:179], v[116:119]
	v_mfma_f32_16x16x32_bf16 v[112:115], v[168:171], v[176:179], v[112:115]
	v_mfma_f32_16x16x32_bf16 v[100:103], v[160:163], v[186:189], v[100:103]
	v_mfma_f32_16x16x32_bf16 v[96:99], v[168:171], v[186:189], v[96:99]
	v_mfma_f32_16x16x32_bf16 v[84:87], v[160:163], v[194:197], v[84:87]
	v_mfma_f32_16x16x32_bf16 v[80:83], v[168:171], v[194:197], v[80:83]
	v_mfma_f32_16x16x32_bf16 v[68:71], v[160:163], v[202:205], v[68:71]
	v_mfma_f32_16x16x32_bf16 v[64:67], v[168:171], v[202:205], v[64:67]
	s_setprio 0
	s_barrier
	s_mov_b32 m0, s55
	v_lshl_add_u64 v[206:207], s[34:35], 0, v[128:129]
	s_add_u32 s40, s34, 0x160000
	ds_read_b128 v[172:175], v136 offset:16384
	ds_read_b128 v[176:179], v136 offset:17408
	ds_read_b128 v[182:185], v136 offset:18432
	ds_read_b128 v[186:189], v136 offset:19456
	ds_read_b128 v[190:193], v136 offset:20480
	ds_read_b128 v[194:197], v136 offset:21504
	ds_read_b128 v[198:201], v136 offset:22528
	ds_read_b128 v[202:205], v136 offset:23552
	global_load_lds_dwordx4 v[206:207], off
	v_lshl_add_u64 v[208:209], s[34:35], 0, v[130:131]
	s_mov_b32 m0, s56
	s_addc_u32 s41, s35, 0
	global_load_lds_dwordx4 v[208:209], off
	v_lshl_add_u64 v[210:211], s[40:41], 0, v[128:129]
	s_mov_b32 m0, s57
	v_lshl_add_u64 v[212:213], s[36:37], 0, v[130:131]
	global_load_lds_dwordx4 v[210:211], off
	v_lshl_add_u64 v[210:211], s[40:41], 0, v[130:131]
	s_mov_b32 m0, s58
	s_nop 0
	global_load_lds_dwordx4 v[210:211], off
	v_lshl_add_u64 v[210:211], s[36:37], 0, v[128:129]
	s_mov_b32 m0, s9
	s_nop 0
	global_load_lds_dwordx4 v[210:211], off
	s_mov_b32 m0, s23
	s_nop 0
	global_load_lds_dwordx4 v[212:213], off
	s_waitcnt vmcnt(8)
	s_waitcnt lgkmcnt(0)
	s_barrier
	s_setprio 1
	v_mfma_f32_16x16x32_bf16 v[60:63], v[140:143], v[172:175], v[60:63]
	v_mfma_f32_16x16x32_bf16 v[56:59], v[148:151], v[172:175], v[56:59]
	v_mfma_f32_16x16x32_bf16 v[44:47], v[140:143], v[182:185], v[44:47]
	v_mfma_f32_16x16x32_bf16 v[40:43], v[148:151], v[182:185], v[40:43]
	v_mfma_f32_16x16x32_bf16 v[28:31], v[140:143], v[190:193], v[28:31]
	v_mfma_f32_16x16x32_bf16 v[24:27], v[148:151], v[190:193], v[24:27]
	v_mfma_f32_16x16x32_bf16 v[12:15], v[140:143], v[198:201], v[12:15]
	v_mfma_f32_16x16x32_bf16 v[8:11], v[148:151], v[198:201], v[8:11]
	v_mfma_f32_16x16x32_bf16 v[60:63], v[144:147], v[176:179], v[60:63]
	v_mfma_f32_16x16x32_bf16 v[56:59], v[152:155], v[176:179], v[56:59]
	v_mfma_f32_16x16x32_bf16 v[44:47], v[144:147], v[186:189], v[44:47]
	v_mfma_f32_16x16x32_bf16 v[40:43], v[152:155], v[186:189], v[40:43]
	v_mfma_f32_16x16x32_bf16 v[28:31], v[144:147], v[194:197], v[28:31]
	v_mfma_f32_16x16x32_bf16 v[24:27], v[152:155], v[194:197], v[24:27]
	v_mfma_f32_16x16x32_bf16 v[12:15], v[144:147], v[202:205], v[12:15]
	v_mfma_f32_16x16x32_bf16 v[8:11], v[152:155], v[202:205], v[8:11]
	s_setprio 0
	s_setprio 1
	v_mfma_f32_16x16x32_bf16 v[52:55], v[156:159], v[172:175], v[52:55]
	v_mfma_f32_16x16x32_bf16 v[48:51], v[164:167], v[172:175], v[48:51]
	v_mfma_f32_16x16x32_bf16 v[36:39], v[156:159], v[182:185], v[36:39]
	v_mfma_f32_16x16x32_bf16 v[32:35], v[164:167], v[182:185], v[32:35]
	v_mfma_f32_16x16x32_bf16 v[20:23], v[156:159], v[190:193], v[20:23]
	v_mfma_f32_16x16x32_bf16 v[16:19], v[164:167], v[190:193], v[16:19]
	v_mfma_f32_16x16x32_bf16 v[4:7], v[156:159], v[198:201], v[4:7]
	v_mfma_f32_16x16x32_bf16 v[0:3], v[164:167], v[198:201], v[0:3]
	v_mfma_f32_16x16x32_bf16 v[52:55], v[160:163], v[176:179], v[52:55]
	v_mfma_f32_16x16x32_bf16 v[48:51], v[168:171], v[176:179], v[48:51]
	v_mfma_f32_16x16x32_bf16 v[36:39], v[160:163], v[186:189], v[36:39]
	v_mfma_f32_16x16x32_bf16 v[32:35], v[168:171], v[186:189], v[32:35]
	v_mfma_f32_16x16x32_bf16 v[20:23], v[160:163], v[194:197], v[20:23]
	v_mfma_f32_16x16x32_bf16 v[16:19], v[168:171], v[194:197], v[16:19]
	v_mfma_f32_16x16x32_bf16 v[4:7], v[160:163], v[202:205], v[4:7]
	v_mfma_f32_16x16x32_bf16 v[0:3], v[168:171], v[202:205], v[0:3]
	s_setprio 0
	s_barrier
	ds_read_b128 v[140:143], v137
	ds_read_b128 v[144:147], v137 offset:1024
	ds_read_b128 v[148:151], v137 offset:2048
	ds_read_b128 v[152:155], v137 offset:3072
	ds_read_b128 v[156:159], v138
	ds_read_b128 v[160:163], v138 offset:1024
	ds_read_b128 v[164:167], v138 offset:2048
	ds_read_b128 v[168:171], v138 offset:3072
	s_add_u32 s36, s36, 0x160000
	s_addc_u32 s37, s37, 0
	s_mov_b32 m0, s28
	v_lshl_add_u64 v[214:215], s[36:37], 0, v[128:129]
	ds_read_b128 v[172:175], v136 offset:32768
	ds_read_b128 v[176:179], v136 offset:33792
	ds_read_b128 v[182:185], v136 offset:34816
	ds_read_b128 v[186:189], v136 offset:35840
	ds_read_b128 v[190:193], v136 offset:36864
	ds_read_b128 v[194:197], v136 offset:37888
	ds_read_b128 v[198:201], v136 offset:38912
	ds_read_b128 v[202:205], v136 offset:39936
	global_load_lds_dwordx4 v[214:215], off
	v_lshl_add_u64 v[214:215], s[36:37], 0, v[130:131]
	s_mov_b32 m0, s29
	s_nop 0
	global_load_lds_dwordx4 v[214:215], off
	s_waitcnt vmcnt(8)
	s_waitcnt lgkmcnt(0)
	s_barrier
	s_setprio 1
	v_mfma_f32_16x16x32_bf16 v[124:127], v[140:143], v[172:175], v[124:127]
	v_mfma_f32_16x16x32_bf16 v[120:123], v[148:151], v[172:175], v[120:123]
	v_mfma_f32_16x16x32_bf16 v[108:111], v[140:143], v[182:185], v[108:111]
	v_mfma_f32_16x16x32_bf16 v[104:107], v[148:151], v[182:185], v[104:107]
	v_mfma_f32_16x16x32_bf16 v[92:95], v[140:143], v[190:193], v[92:95]
	v_mfma_f32_16x16x32_bf16 v[88:91], v[148:151], v[190:193], v[88:91]
	v_mfma_f32_16x16x32_bf16 v[76:79], v[140:143], v[198:201], v[76:79]
	v_mfma_f32_16x16x32_bf16 v[72:75], v[148:151], v[198:201], v[72:75]
	v_mfma_f32_16x16x32_bf16 v[124:127], v[144:147], v[176:179], v[124:127]
	v_mfma_f32_16x16x32_bf16 v[120:123], v[152:155], v[176:179], v[120:123]
	v_mfma_f32_16x16x32_bf16 v[108:111], v[144:147], v[186:189], v[108:111]
	v_mfma_f32_16x16x32_bf16 v[104:107], v[152:155], v[186:189], v[104:107]
	v_mfma_f32_16x16x32_bf16 v[92:95], v[144:147], v[194:197], v[92:95]
	v_mfma_f32_16x16x32_bf16 v[88:91], v[152:155], v[194:197], v[88:91]
	v_mfma_f32_16x16x32_bf16 v[76:79], v[144:147], v[202:205], v[76:79]
	v_mfma_f32_16x16x32_bf16 v[72:75], v[152:155], v[202:205], v[72:75]
	s_setprio 0
	s_setprio 1
	v_mfma_f32_16x16x32_bf16 v[116:119], v[156:159], v[172:175], v[116:119]
	v_mfma_f32_16x16x32_bf16 v[112:115], v[164:167], v[172:175], v[112:115]
	v_mfma_f32_16x16x32_bf16 v[100:103], v[156:159], v[182:185], v[100:103]
	v_mfma_f32_16x16x32_bf16 v[96:99], v[164:167], v[182:185], v[96:99]
	v_mfma_f32_16x16x32_bf16 v[84:87], v[156:159], v[190:193], v[84:87]
	v_mfma_f32_16x16x32_bf16 v[80:83], v[164:167], v[190:193], v[80:83]
	v_mfma_f32_16x16x32_bf16 v[68:71], v[156:159], v[198:201], v[68:71]
	v_mfma_f32_16x16x32_bf16 v[64:67], v[164:167], v[198:201], v[64:67]
	v_mfma_f32_16x16x32_bf16 v[116:119], v[160:163], v[176:179], v[116:119]
	v_mfma_f32_16x16x32_bf16 v[112:115], v[168:171], v[176:179], v[112:115]
	v_mfma_f32_16x16x32_bf16 v[100:103], v[160:163], v[186:189], v[100:103]
	v_mfma_f32_16x16x32_bf16 v[96:99], v[168:171], v[186:189], v[96:99]
	v_mfma_f32_16x16x32_bf16 v[84:87], v[160:163], v[194:197], v[84:87]
	v_mfma_f32_16x16x32_bf16 v[80:83], v[168:171], v[194:197], v[80:83]
	v_mfma_f32_16x16x32_bf16 v[68:71], v[160:163], v[202:205], v[68:71]
	v_mfma_f32_16x16x32_bf16 v[64:67], v[168:171], v[202:205], v[64:67]
	s_setprio 0
	s_barrier
	s_mov_b32 m0, s59
	v_lshl_add_u64 v[206:207], v[206:207], 0, s[10:11]
	s_add_u32 s34, s34, 0x160080
	ds_read_b128 v[172:175], v136 offset:49152
	ds_read_b128 v[176:179], v136 offset:50176
	ds_read_b128 v[182:185], v136 offset:51200
	ds_read_b128 v[186:189], v136 offset:52224
	ds_read_b128 v[190:193], v136 offset:53248
	ds_read_b128 v[194:197], v136 offset:54272
	ds_read_b128 v[198:201], v136 offset:55296
	ds_read_b128 v[202:205], v136 offset:56320
	global_load_lds_dwordx4 v[206:207], off
	v_lshl_add_u64 v[206:207], v[208:209], 0, s[10:11]
	s_mov_b32 m0, s60
	s_addc_u32 s35, s35, 0
	global_load_lds_dwordx4 v[206:207], off
	v_lshl_add_u64 v[206:207], s[34:35], 0, v[128:129]
	s_mov_b32 m0, s61
	s_nop 0
	global_load_lds_dwordx4 v[206:207], off
	v_lshl_add_u64 v[206:207], s[34:35], 0, v[130:131]
	s_mov_b32 m0, s62
	s_nop 0
	global_load_lds_dwordx4 v[206:207], off
	v_lshl_add_u64 v[206:207], v[210:211], 0, s[10:11]
	s_mov_b32 m0, s30
	s_nop 0
	global_load_lds_dwordx4 v[206:207], off
	v_lshl_add_u64 v[206:207], v[212:213], 0, s[10:11]
	s_mov_b32 m0, s31
	s_nop 0
	global_load_lds_dwordx4 v[206:207], off
	s_waitcnt vmcnt(8)
	s_waitcnt lgkmcnt(0)
	s_barrier
	s_setprio 1
	v_mfma_f32_16x16x32_bf16 v[60:63], v[140:143], v[172:175], v[60:63]
	v_mfma_f32_16x16x32_bf16 v[56:59], v[148:151], v[172:175], v[56:59]
	v_mfma_f32_16x16x32_bf16 v[44:47], v[140:143], v[182:185], v[44:47]
	v_mfma_f32_16x16x32_bf16 v[40:43], v[148:151], v[182:185], v[40:43]
	v_mfma_f32_16x16x32_bf16 v[28:31], v[140:143], v[190:193], v[28:31]
	v_mfma_f32_16x16x32_bf16 v[24:27], v[148:151], v[190:193], v[24:27]
	v_mfma_f32_16x16x32_bf16 v[12:15], v[140:143], v[198:201], v[12:15]
	v_mfma_f32_16x16x32_bf16 v[8:11], v[148:151], v[198:201], v[8:11]
	v_mfma_f32_16x16x32_bf16 v[60:63], v[144:147], v[176:179], v[60:63]
	v_mfma_f32_16x16x32_bf16 v[56:59], v[152:155], v[176:179], v[56:59]
	v_mfma_f32_16x16x32_bf16 v[44:47], v[144:147], v[186:189], v[44:47]
	v_mfma_f32_16x16x32_bf16 v[40:43], v[152:155], v[186:189], v[40:43]
	v_mfma_f32_16x16x32_bf16 v[28:31], v[144:147], v[194:197], v[28:31]
	v_mfma_f32_16x16x32_bf16 v[24:27], v[152:155], v[194:197], v[24:27]
	v_mfma_f32_16x16x32_bf16 v[12:15], v[144:147], v[202:205], v[12:15]
	v_mfma_f32_16x16x32_bf16 v[8:11], v[152:155], v[202:205], v[8:11]
	s_setprio 0
	s_setprio 1
	v_mfma_f32_16x16x32_bf16 v[52:55], v[156:159], v[172:175], v[52:55]
	v_mfma_f32_16x16x32_bf16 v[48:51], v[164:167], v[172:175], v[48:51]
	v_mfma_f32_16x16x32_bf16 v[36:39], v[156:159], v[182:185], v[36:39]
	v_mfma_f32_16x16x32_bf16 v[32:35], v[164:167], v[182:185], v[32:35]
	v_mfma_f32_16x16x32_bf16 v[20:23], v[156:159], v[190:193], v[20:23]
	v_mfma_f32_16x16x32_bf16 v[16:19], v[164:167], v[190:193], v[16:19]
	v_mfma_f32_16x16x32_bf16 v[4:7], v[156:159], v[198:201], v[4:7]
	v_mfma_f32_16x16x32_bf16 v[0:3], v[164:167], v[198:201], v[0:3]
	v_mfma_f32_16x16x32_bf16 v[52:55], v[160:163], v[176:179], v[52:55]
	v_mfma_f32_16x16x32_bf16 v[48:51], v[168:171], v[176:179], v[48:51]
	v_mfma_f32_16x16x32_bf16 v[36:39], v[160:163], v[186:189], v[36:39]
	v_mfma_f32_16x16x32_bf16 v[32:35], v[168:171], v[186:189], v[32:35]
	v_mfma_f32_16x16x32_bf16 v[20:23], v[160:163], v[194:197], v[20:23]
	v_mfma_f32_16x16x32_bf16 v[16:19], v[168:171], v[194:197], v[16:19]
	v_mfma_f32_16x16x32_bf16 v[4:7], v[160:163], v[202:205], v[4:7]
	v_mfma_f32_16x16x32_bf16 v[0:3], v[168:171], v[202:205], v[0:3]
	s_setprio 0
	s_barrier
	s_add_i32 s52, s52, 2
	s_add_u32 s16, s16, 0x100
	s_addc_u32 s17, s17, 0
	s_cmp_ge_i32 s52, s38
	s_cbranch_scc0 .LBB0_983
	v_mov_b32_e32 v129, v127

.LBB0_1193:
	s_mov_b64 s[6:7], s[14:15]
	ds_read_b128 v[128:131], v191
	ds_read_b128 v[132:135], v191 offset:1024
	ds_read_b128 v[136:139], v191 offset:2048
	ds_read_b128 v[140:143], v191 offset:3072
	ds_read_b128 v[144:147], v192
	ds_read_b128 v[148:151], v192 offset:1024
	ds_read_b128 v[168:171], v192 offset:2048
	ds_read_b128 v[172:175], v192 offset:3072
	s_add_u32 s5, s2, s6
	s_addc_u32 s8, s3, s7
	s_add_u32 s9, s5, 0x100
	s_addc_u32 s16, s8, 0
	s_add_u32 s6, s12, s6
	s_addc_u32 s7, s13, s7
	s_add_u32 s6, s6, 0x100
	s_addc_u32 s7, s7, 0
	s_cmp_eq_u32 s93, s4
	s_cselect_b32 s37, s81, s16
	s_cselect_b32 s36, s80, s9
	s_cselect_b32 s17, s83, s7
	s_cselect_b32 s16, s82, s6
	s_add_u32 s6, s5, 0x80080
	s_addc_u32 s7, s8, 0
	v_lshl_add_u64 v[186:187], s[6:7], 0, v[152:153]
	s_add_i32 m0, s19, 0xc000
	ds_read_b128 v[176:179], v193
	ds_read_b128 v[182:185], v193 offset:1024
	ds_read_b128 v[196:199], v193 offset:2048
	ds_read_b128 v[200:203], v193 offset:3072
	ds_read_b128 v[204:207], v193 offset:4096
	ds_read_b128 v[208:211], v193 offset:5120
	ds_read_b128 v[212:215], v193 offset:6144
	ds_read_b128 v[216:219], v193 offset:7168
	global_load_lds_dwordx4 v[186:187], off
	v_lshl_add_u64 v[186:187], s[6:7], 0, v[156:157]
	s_add_i32 m0, s19, 0xe000
	s_nop 0
	global_load_lds_dwordx4 v[186:187], off
	s_waitcnt vmcnt(8)
	s_waitcnt lgkmcnt(0)
	s_barrier
	s_setprio 1
	v_mfma_f32_16x16x32_bf16 v[120:123], v[128:131], v[176:179], v[120:123]
	v_mfma_f32_16x16x32_bf16 v[124:127], v[136:139], v[176:179], v[124:127]
	v_mfma_f32_16x16x32_bf16 v[108:111], v[128:131], v[196:199], v[108:111]
	v_mfma_f32_16x16x32_bf16 v[104:107], v[136:139], v[196:199], v[104:107]
	v_mfma_f32_16x16x32_bf16 v[92:95], v[128:131], v[204:207], v[92:95]
	v_mfma_f32_16x16x32_bf16 v[88:91], v[136:139], v[204:207], v[88:91]
	v_mfma_f32_16x16x32_bf16 v[76:79], v[128:131], v[212:215], v[76:79]
	v_mfma_f32_16x16x32_bf16 v[72:75], v[136:139], v[212:215], v[72:75]
	v_mfma_f32_16x16x32_bf16 v[120:123], v[132:135], v[182:185], v[120:123]
	v_mfma_f32_16x16x32_bf16 v[124:127], v[140:143], v[182:185], v[124:127]
	v_mfma_f32_16x16x32_bf16 v[108:111], v[132:135], v[200:203], v[108:111]
	v_mfma_f32_16x16x32_bf16 v[104:107], v[140:143], v[200:203], v[104:107]
	v_mfma_f32_16x16x32_bf16 v[92:95], v[132:135], v[208:211], v[92:95]
	v_mfma_f32_16x16x32_bf16 v[88:91], v[140:143], v[208:211], v[88:91]
	v_mfma_f32_16x16x32_bf16 v[76:79], v[132:135], v[216:219], v[76:79]
	v_mfma_f32_16x16x32_bf16 v[72:75], v[140:143], v[216:219], v[72:75]
	s_setprio 0
	s_setprio 1
	v_mfma_f32_16x16x32_bf16 v[116:119], v[144:147], v[176:179], v[116:119]
	v_mfma_f32_16x16x32_bf16 v[112:115], v[168:171], v[176:179], v[112:115]
	v_mfma_f32_16x16x32_bf16 v[100:103], v[144:147], v[196:199], v[100:103]
	v_mfma_f32_16x16x32_bf16 v[96:99], v[168:171], v[196:199], v[96:99]
	v_mfma_f32_16x16x32_bf16 v[84:87], v[144:147], v[204:207], v[84:87]
	v_mfma_f32_16x16x32_bf16 v[80:83], v[168:171], v[204:207], v[80:83]
	v_mfma_f32_16x16x32_bf16 v[68:71], v[144:147], v[212:215], v[68:71]
	v_mfma_f32_16x16x32_bf16 v[64:67], v[168:171], v[212:215], v[64:67]
	v_mfma_f32_16x16x32_bf16 v[116:119], v[148:151], v[182:185], v[116:119]
	v_mfma_f32_16x16x32_bf16 v[112:115], v[172:175], v[182:185], v[112:115]
	v_mfma_f32_16x16x32_bf16 v[100:103], v[148:151], v[200:203], v[100:103]
	v_mfma_f32_16x16x32_bf16 v[96:99], v[172:175], v[200:203], v[96:99]
	v_mfma_f32_16x16x32_bf16 v[84:87], v[148:151], v[208:211], v[84:87]
	v_mfma_f32_16x16x32_bf16 v[80:83], v[172:175], v[208:211], v[80:83]
	v_mfma_f32_16x16x32_bf16 v[68:71], v[148:151], v[216:219], v[68:71]
	v_mfma_f32_16x16x32_bf16 v[64:67], v[172:175], v[216:219], v[64:67]
	s_setprio 0
	s_barrier
	s_add_i32 s5, s95, s18
	v_lshl_add_u64 v[186:187], s[16:17], 0, v[154:155]
	s_mov_b32 m0, s5
	ds_read_b128 v[176:179], v193 offset:16384
	ds_read_b128 v[182:185], v193 offset:17408
	ds_read_b128 v[196:199], v193 offset:18432
	ds_read_b128 v[200:203], v193 offset:19456
	ds_read_b128 v[204:207], v193 offset:20480
	ds_read_b128 v[208:211], v193 offset:21504
	ds_read_b128 v[212:215], v193 offset:22528
	ds_read_b128 v[216:219], v193 offset:23552
	global_load_lds_dwordx4 v[186:187], off
	s_add_i32 m0, s5, 0x2000
	s_add_u32 s6, s16, 0x80000
	v_lshl_add_u64 v[220:221], s[16:17], 0, v[158:159]
	s_addc_u32 s7, s17, 0
	s_add_i32 s5, s96, s18
	global_load_lds_dwordx4 v[220:221], off
	v_lshl_add_u64 v[222:223], s[6:7], 0, v[154:155]
	s_mov_b32 m0, s5
	v_lshl_add_u64 v[224:225], s[36:37], 0, v[156:157]
	global_load_lds_dwordx4 v[222:223], off
	v_lshl_add_u64 v[222:223], s[6:7], 0, v[158:159]
	s_add_i32 m0, s5, 0x2000
	s_nop 0
	global_load_lds_dwordx4 v[222:223], off
	v_lshl_add_u64 v[222:223], s[36:37], 0, v[152:153]
	s_mov_b32 m0, s19
	s_nop 0
	global_load_lds_dwordx4 v[222:223], off
	s_mov_b32 m0, s23
	s_nop 0
	global_load_lds_dwordx4 v[224:225], off
	s_waitcnt vmcnt(8)
	s_waitcnt lgkmcnt(0)
	s_barrier
	s_setprio 1
	v_mfma_f32_16x16x32_bf16 v[60:63], v[128:131], v[176:179], v[60:63]
	v_mfma_f32_16x16x32_bf16 v[56:59], v[136:139], v[176:179], v[56:59]
	v_mfma_f32_16x16x32_bf16 v[44:47], v[128:131], v[196:199], v[44:47]
	v_mfma_f32_16x16x32_bf16 v[40:43], v[136:139], v[196:199], v[40:43]
	v_mfma_f32_16x16x32_bf16 v[28:31], v[128:131], v[204:207], v[28:31]
	v_mfma_f32_16x16x32_bf16 v[24:27], v[136:139], v[204:207], v[24:27]
	v_mfma_f32_16x16x32_bf16 v[12:15], v[128:131], v[212:215], v[12:15]
	v_mfma_f32_16x16x32_bf16 v[8:11], v[136:139], v[212:215], v[8:11]
	v_mfma_f32_16x16x32_bf16 v[60:63], v[132:135], v[182:185], v[60:63]
	v_mfma_f32_16x16x32_bf16 v[56:59], v[140:143], v[182:185], v[56:59]
	v_mfma_f32_16x16x32_bf16 v[44:47], v[132:135], v[200:203], v[44:47]
	v_mfma_f32_16x16x32_bf16 v[40:43], v[140:143], v[200:203], v[40:43]
	v_mfma_f32_16x16x32_bf16 v[28:31], v[132:135], v[208:211], v[28:31]
	v_mfma_f32_16x16x32_bf16 v[24:27], v[140:143], v[208:211], v[24:27]
	v_mfma_f32_16x16x32_bf16 v[12:15], v[132:135], v[216:219], v[12:15]
	v_mfma_f32_16x16x32_bf16 v[8:11], v[140:143], v[216:219], v[8:11]
	s_setprio 0
	s_setprio 1
	v_mfma_f32_16x16x32_bf16 v[52:55], v[144:147], v[176:179], v[52:55]
	v_mfma_f32_16x16x32_bf16 v[48:51], v[168:171], v[176:179], v[48:51]
	v_mfma_f32_16x16x32_bf16 v[36:39], v[144:147], v[196:199], v[36:39]
	v_mfma_f32_16x16x32_bf16 v[32:35], v[168:171], v[196:199], v[32:35]
	v_mfma_f32_16x16x32_bf16 v[20:23], v[144:147], v[204:207], v[20:23]
	v_mfma_f32_16x16x32_bf16 v[16:19], v[168:171], v[204:207], v[16:19]
	v_mfma_f32_16x16x32_bf16 v[4:7], v[144:147], v[212:215], v[4:7]
	v_mfma_f32_16x16x32_bf16 v[0:3], v[168:171], v[212:215], v[0:3]
	v_mfma_f32_16x16x32_bf16 v[52:55], v[148:151], v[182:185], v[52:55]
	v_mfma_f32_16x16x32_bf16 v[48:51], v[172:175], v[182:185], v[48:51]
	v_mfma_f32_16x16x32_bf16 v[36:39], v[148:151], v[200:203], v[36:39]
	v_mfma_f32_16x16x32_bf16 v[32:35], v[172:175], v[200:203], v[32:35]
	v_mfma_f32_16x16x32_bf16 v[20:23], v[148:151], v[208:211], v[20:23]
	v_mfma_f32_16x16x32_bf16 v[16:19], v[172:175], v[208:211], v[16:19]
	v_mfma_f32_16x16x32_bf16 v[4:7], v[148:151], v[216:219], v[4:7]
	v_mfma_f32_16x16x32_bf16 v[0:3], v[172:175], v[216:219], v[0:3]
	s_setprio 0
	s_barrier
	s_add_i32 s5, 0, 0x18000
	s_add_i32 s8, 0, 0x1c000
	v_add_u32_e32 v140, s5, v190
	v_add_u32_e32 v160, s8, v190
	ds_read_b128 v[128:131], v140
	ds_read_b128 v[132:135], v140 offset:1024
	ds_read_b128 v[136:139], v140 offset:2048
	ds_read_b128 v[140:143], v140 offset:3072
	ds_read_b128 v[144:147], v160
	ds_read_b128 v[148:151], v160 offset:1024
	ds_read_b128 v[168:171], v160 offset:2048
	ds_read_b128 v[172:175], v160 offset:3072
	s_add_u32 s6, s36, 0x80000
	s_addc_u32 s7, s37, 0
	s_mov_b32 m0, s54
	v_lshl_add_u64 v[226:227], s[6:7], 0, v[152:153]
	ds_read_b128 v[176:179], v193 offset:32768
	ds_read_b128 v[182:185], v193 offset:33792
	ds_read_b128 v[196:199], v193 offset:34816
	ds_read_b128 v[200:203], v193 offset:35840
	ds_read_b128 v[204:207], v193 offset:36864
	ds_read_b128 v[208:211], v193 offset:37888
	ds_read_b128 v[212:215], v193 offset:38912
	ds_read_b128 v[216:219], v193 offset:39936
	global_load_lds_dwordx4 v[226:227], off
	v_lshl_add_u64 v[226:227], s[6:7], 0, v[156:157]
	s_mov_b32 m0, s55
	s_nop 0
	global_load_lds_dwordx4 v[226:227], off
	s_waitcnt vmcnt(8)
	s_waitcnt lgkmcnt(0)
	s_barrier
	s_setprio 1
	v_mfma_f32_16x16x32_bf16 v[120:123], v[128:131], v[176:179], v[120:123]
	v_mfma_f32_16x16x32_bf16 v[124:127], v[136:139], v[176:179], v[124:127]
	v_mfma_f32_16x16x32_bf16 v[108:111], v[128:131], v[196:199], v[108:111]
	v_mfma_f32_16x16x32_bf16 v[104:107], v[136:139], v[196:199], v[104:107]
	v_mfma_f32_16x16x32_bf16 v[92:95], v[128:131], v[204:207], v[92:95]
	v_mfma_f32_16x16x32_bf16 v[88:91], v[136:139], v[204:207], v[88:91]
	v_mfma_f32_16x16x32_bf16 v[76:79], v[128:131], v[212:215], v[76:79]
	v_mfma_f32_16x16x32_bf16 v[72:75], v[136:139], v[212:215], v[72:75]
	v_mfma_f32_16x16x32_bf16 v[120:123], v[132:135], v[182:185], v[120:123]
	v_mfma_f32_16x16x32_bf16 v[124:127], v[140:143], v[182:185], v[124:127]
	v_mfma_f32_16x16x32_bf16 v[108:111], v[132:135], v[200:203], v[108:111]
	v_mfma_f32_16x16x32_bf16 v[104:107], v[140:143], v[200:203], v[104:107]
	v_mfma_f32_16x16x32_bf16 v[92:95], v[132:135], v[208:211], v[92:95]
	v_mfma_f32_16x16x32_bf16 v[88:91], v[140:143], v[208:211], v[88:91]
	v_mfma_f32_16x16x32_bf16 v[76:79], v[132:135], v[216:219], v[76:79]
	v_mfma_f32_16x16x32_bf16 v[72:75], v[140:143], v[216:219], v[72:75]
	s_setprio 0
	s_setprio 1
	v_mfma_f32_16x16x32_bf16 v[116:119], v[144:147], v[176:179], v[116:119]
	v_mfma_f32_16x16x32_bf16 v[112:115], v[168:171], v[176:179], v[112:115]
	v_mfma_f32_16x16x32_bf16 v[100:103], v[144:147], v[196:199], v[100:103]
	v_mfma_f32_16x16x32_bf16 v[96:99], v[168:171], v[196:199], v[96:99]
	v_mfma_f32_16x16x32_bf16 v[84:87], v[144:147], v[204:207], v[84:87]
	v_mfma_f32_16x16x32_bf16 v[80:83], v[168:171], v[204:207], v[80:83]
	v_mfma_f32_16x16x32_bf16 v[68:71], v[144:147], v[212:215], v[68:71]
	v_mfma_f32_16x16x32_bf16 v[64:67], v[168:171], v[212:215], v[64:67]
	v_mfma_f32_16x16x32_bf16 v[116:119], v[148:151], v[182:185], v[116:119]
	v_mfma_f32_16x16x32_bf16 v[112:115], v[172:175], v[182:185], v[112:115]
	v_mfma_f32_16x16x32_bf16 v[100:103], v[148:151], v[200:203], v[100:103]
	v_mfma_f32_16x16x32_bf16 v[96:99], v[172:175], v[200:203], v[96:99]
	v_mfma_f32_16x16x32_bf16 v[84:87], v[148:151], v[208:211], v[84:87]
	v_mfma_f32_16x16x32_bf16 v[80:83], v[172:175], v[208:211], v[80:83]
	v_mfma_f32_16x16x32_bf16 v[68:71], v[148:151], v[216:219], v[68:71]
	v_mfma_f32_16x16x32_bf16 v[64:67], v[172:175], v[216:219], v[64:67]
	s_setprio 0
	s_barrier
	s_add_i32 s5, s5, s18
	v_lshl_add_u64 v[186:187], v[186:187], 0, s[64:65]
	s_mov_b32 m0, s5
	ds_read_b128 v[176:179], v193 offset:49152
	ds_read_b128 v[182:185], v193 offset:50176
	ds_read_b128 v[196:199], v193 offset:51200
	ds_read_b128 v[200:203], v193 offset:52224
	ds_read_b128 v[204:207], v193 offset:53248
	ds_read_b128 v[208:211], v193 offset:54272
	ds_read_b128 v[212:215], v193 offset:55296
	ds_read_b128 v[216:219], v193 offset:56320
	global_load_lds_dwordx4 v[186:187], off
	s_add_i32 m0, s5, 0x2000
	s_add_u32 s6, s16, 0x80080
	v_lshl_add_u64 v[186:187], v[220:221], 0, s[64:65]
	s_addc_u32 s7, s17, 0
	s_add_i32 s5, s8, s18
	global_load_lds_dwordx4 v[186:187], off
	v_lshl_add_u64 v[186:187], s[6:7], 0, v[154:155]
	s_mov_b32 m0, s5
	s_nop 0
	global_load_lds_dwordx4 v[186:187], off
	v_lshl_add_u64 v[186:187], s[6:7], 0, v[158:159]
	s_add_i32 m0, s5, 0x2000
	s_nop 0
	global_load_lds_dwordx4 v[186:187], off
	v_lshl_add_u64 v[186:187], v[222:223], 0, s[64:65]
	s_mov_b32 m0, s90
	s_nop 0
	global_load_lds_dwordx4 v[186:187], off
	v_lshl_add_u64 v[186:187], v[224:225], 0, s[64:65]
	s_mov_b32 m0, s91
	s_nop 0
	global_load_lds_dwordx4 v[186:187], off
	s_waitcnt vmcnt(8)
	s_waitcnt lgkmcnt(0)
	s_barrier
	s_setprio 1
	v_mfma_f32_16x16x32_bf16 v[60:63], v[128:131], v[176:179], v[60:63]
	v_mfma_f32_16x16x32_bf16 v[56:59], v[136:139], v[176:179], v[56:59]
	v_mfma_f32_16x16x32_bf16 v[44:47], v[128:131], v[196:199], v[44:47]
	v_mfma_f32_16x16x32_bf16 v[40:43], v[136:139], v[196:199], v[40:43]
	v_mfma_f32_16x16x32_bf16 v[28:31], v[128:131], v[204:207], v[28:31]
	v_mfma_f32_16x16x32_bf16 v[24:27], v[136:139], v[204:207], v[24:27]
	v_mfma_f32_16x16x32_bf16 v[12:15], v[128:131], v[212:215], v[12:15]
	v_mfma_f32_16x16x32_bf16 v[8:11], v[136:139], v[212:215], v[8:11]
	v_mfma_f32_16x16x32_bf16 v[60:63], v[132:135], v[182:185], v[60:63]
	v_mfma_f32_16x16x32_bf16 v[56:59], v[140:143], v[182:185], v[56:59]
	v_mfma_f32_16x16x32_bf16 v[44:47], v[132:135], v[200:203], v[44:47]
	v_mfma_f32_16x16x32_bf16 v[40:43], v[140:143], v[200:203], v[40:43]
	v_mfma_f32_16x16x32_bf16 v[28:31], v[132:135], v[208:211], v[28:31]
	v_mfma_f32_16x16x32_bf16 v[24:27], v[140:143], v[208:211], v[24:27]
	v_mfma_f32_16x16x32_bf16 v[12:15], v[132:135], v[216:219], v[12:15]
	v_mfma_f32_16x16x32_bf16 v[8:11], v[140:143], v[216:219], v[8:11]
	s_setprio 0
	s_setprio 1
	v_mfma_f32_16x16x32_bf16 v[52:55], v[144:147], v[176:179], v[52:55]
	v_mfma_f32_16x16x32_bf16 v[48:51], v[168:171], v[176:179], v[48:51]
	v_mfma_f32_16x16x32_bf16 v[36:39], v[144:147], v[196:199], v[36:39]
	v_mfma_f32_16x16x32_bf16 v[32:35], v[168:171], v[196:199], v[32:35]
	v_mfma_f32_16x16x32_bf16 v[20:23], v[144:147], v[204:207], v[20:23]
	v_mfma_f32_16x16x32_bf16 v[16:19], v[168:171], v[204:207], v[16:19]
	v_mfma_f32_16x16x32_bf16 v[4:7], v[144:147], v[212:215], v[4:7]
	v_mfma_f32_16x16x32_bf16 v[0:3], v[168:171], v[212:215], v[0:3]
	v_mfma_f32_16x16x32_bf16 v[52:55], v[148:151], v[182:185], v[52:55]
	v_mfma_f32_16x16x32_bf16 v[48:51], v[172:175], v[182:185], v[48:51]
	v_mfma_f32_16x16x32_bf16 v[36:39], v[148:151], v[200:203], v[36:39]
	v_mfma_f32_16x16x32_bf16 v[32:35], v[172:175], v[200:203], v[32:35]
	v_mfma_f32_16x16x32_bf16 v[20:23], v[148:151], v[208:211], v[20:23]
	v_mfma_f32_16x16x32_bf16 v[16:19], v[172:175], v[208:211], v[16:19]
	v_mfma_f32_16x16x32_bf16 v[4:7], v[148:151], v[216:219], v[4:7]
	v_mfma_f32_16x16x32_bf16 v[0:3], v[172:175], v[216:219], v[0:3]
	s_setprio 0
	s_barrier
	s_add_i32 s4, s4, 2
	s_add_u32 s14, s14, 0x100
	s_addc_u32 s15, s15, 0
	s_cmp_ge_i32 s4, s84
	s_cbranch_scc0 .LBB0_1193

.Lcoldzero_d1:
	v_mov_b32_e32 v127, 0
	v_mov_b32_e32 v126, 0
	v_mov_b32_e32 v125, 0
	v_mov_b32_e32 v124, 0
	v_mov_b32_e32 v123, 0
	v_mov_b32_e32 v122, 0
	v_mov_b32_e32 v121, 0
	v_mov_b32_e32 v120, 0
	v_mov_b32_e32 v101, 0
	v_mov_b32_e32 v100, 0
	v_mov_b32_e32 v103, 0
	v_mov_b32_e32 v102, 0
	v_mov_b32_e32 v109, 0
	v_mov_b32_e32 v108, 0
	v_mov_b32_e32 v111, 0
	v_mov_b32_e32 v110, 0
	v_mov_b32_e32 v85, 0
	v_mov_b32_e32 v84, 0
	v_mov_b32_e32 v87, 0
	v_mov_b32_e32 v86, 0
	v_mov_b32_e32 v93, 0
	v_mov_b32_e32 v92, 0
	v_mov_b32_e32 v95, 0
	v_mov_b32_e32 v94, 0
	v_mov_b32_e32 v73, 0
	v_mov_b32_e32 v72, 0
	v_mov_b32_e32 v75, 0
	v_mov_b32_e32 v74, 0
	v_mov_b32_e32 v77, 0
	v_mov_b32_e32 v76, 0
	v_mov_b32_e32 v79, 0
	v_mov_b32_e32 v78, 0
	v_mov_b32_e32 v141, 0
	v_mov_b32_e32 v140, 0
	v_mov_b32_e32 v143, 0
	v_mov_b32_e32 v142, 0
	v_mov_b32_e32 v145, 0
	v_mov_b32_e32 v144, 0
	v_mov_b32_e32 v147, 0
	v_mov_b32_e32 v146, 0
	v_mov_b32_e32 v113, 0
	v_mov_b32_e32 v112, 0
	v_mov_b32_e32 v115, 0
	v_mov_b32_e32 v114, 0
	v_mov_b32_e32 v117, 0
	v_mov_b32_e32 v116, 0
	v_mov_b32_e32 v119, 0
	v_mov_b32_e32 v118, 0
	v_mov_b32_e32 v97, 0
	v_mov_b32_e32 v96, 0
	v_mov_b32_e32 v99, 0
	v_mov_b32_e32 v98, 0
	v_mov_b32_e32 v105, 0
	v_mov_b32_e32 v104, 0
	v_mov_b32_e32 v107, 0
	v_mov_b32_e32 v106, 0
	v_mov_b32_e32 v71, 0
	v_mov_b32_e32 v70, 0
	v_mov_b32_e32 v69, 0
	v_mov_b32_e32 v68, 0
	v_mov_b32_e32 v67, 0
	v_mov_b32_e32 v66, 0
	v_mov_b32_e32 v65, 0
	v_mov_b32_e32 v64, 0
	v_mov_b32_e32 v63, 0
	v_mov_b32_e32 v62, 0
	v_mov_b32_e32 v61, 0
	v_mov_b32_e32 v60, 0
	v_mov_b32_e32 v59, 0
	v_mov_b32_e32 v58, 0
	v_mov_b32_e32 v57, 0
	v_mov_b32_e32 v56, 0
	v_mov_b32_e32 v37, 0
	v_mov_b32_e32 v36, 0
	v_mov_b32_e32 v39, 0
	v_mov_b32_e32 v38, 0
	v_mov_b32_e32 v45, 0
	v_mov_b32_e32 v44, 0
	v_mov_b32_e32 v47, 0
	v_mov_b32_e32 v46, 0
	v_mov_b32_e32 v21, 0
	v_mov_b32_e32 v20, 0
	v_mov_b32_e32 v23, 0
	v_mov_b32_e32 v22, 0
	v_mov_b32_e32 v29, 0
	v_mov_b32_e32 v28, 0
	v_mov_b32_e32 v31, 0
	v_mov_b32_e32 v30, 0
	v_mov_b32_e32 v9, 0
	v_mov_b32_e32 v8, 0
	v_mov_b32_e32 v11, 0
	v_mov_b32_e32 v10, 0
	v_mov_b32_e32 v13, 0
	v_mov_b32_e32 v12, 0
	v_mov_b32_e32 v15, 0
	v_mov_b32_e32 v14, 0
	v_mov_b32_e32 v81, 0
	v_mov_b32_e32 v80, 0
	v_mov_b32_e32 v83, 0
	v_mov_b32_e32 v82, 0
	v_mov_b32_e32 v89, 0
	v_mov_b32_e32 v88, 0
	v_mov_b32_e32 v91, 0
	v_mov_b32_e32 v90, 0
	v_mov_b32_e32 v49, 0
	v_mov_b32_e32 v48, 0
	v_mov_b32_e32 v51, 0
	v_mov_b32_e32 v50, 0
	v_mov_b32_e32 v53, 0
	v_mov_b32_e32 v52, 0
	v_mov_b32_e32 v55, 0
	v_mov_b32_e32 v54, 0
	v_mov_b32_e32 v33, 0
	v_mov_b32_e32 v32, 0
	v_mov_b32_e32 v35, 0
	v_mov_b32_e32 v34, 0
	v_mov_b32_e32 v41, 0
	v_mov_b32_e32 v40, 0
	v_mov_b32_e32 v43, 0
	v_mov_b32_e32 v42, 0
	v_mov_b32_e32 v7, 0
	v_mov_b32_e32 v6, 0
	v_mov_b32_e32 v5, 0
	v_mov_b32_e32 v4, 0
	v_mov_b32_e32 v3, 0
	v_mov_b32_e32 v2, 0
	v_mov_b32_e32 v1, 0
	v_mov_b32_e32 v0, 0
	s_branch .LBB0_1251

.LBB0_1247:
	v_readlane_b32 s4, v255, 6
	v_readlane_b32 s5, v255, 7
	s_add_u32 s6, s4, s58
	s_addc_u32 s7, s5, s59
	s_and_b64 s[4:5], s[12:13], exec
	v_readlane_b32 s4, v255, 50
	s_cselect_b32 s63, s7, s67
	s_cselect_b32 s62, s6, s66
	v_readlane_b32 s5, v255, 51
	s_add_u32 s6, s4, s60
	s_addc_u32 s7, s5, s61
	s_and_b64 s[4:5], s[12:13], exec
	s_cselect_b32 s65, s7, s69
	s_cselect_b32 s64, s6, s68
	s_and_b64 vcc, exec, s[10:11]
	s_cbranch_vccnz .Lcoldzero_d1
	v_mov_b64_e32 v[0:1], 0
	s_mov_b32 s4, 0
	s_mov_b64 s[70:71], 0
	v_mov_b64_e32 v[2:3], 0
	v_mov_b64_e32 v[4:5], 0
	v_mov_b64_e32 v[6:7], 0
	v_mov_b64_e32 v[8:9], 0
	v_mov_b64_e32 v[10:11], 0
	v_mov_b64_e32 v[12:13], 0
	v_mov_b64_e32 v[14:15], 0
	v_mov_b64_e32 v[16:17], 0
	v_mov_b64_e32 v[18:19], 0
	v_mov_b64_e32 v[20:21], 0
	v_mov_b64_e32 v[22:23], 0
	v_mov_b64_e32 v[24:25], 0
	v_mov_b64_e32 v[26:27], 0
	v_mov_b64_e32 v[28:29], 0
	v_mov_b64_e32 v[30:31], 0
	v_mov_b64_e32 v[32:33], 0
	v_mov_b64_e32 v[34:35], 0
	v_mov_b64_e32 v[36:37], 0
	v_mov_b64_e32 v[38:39], 0
	v_mov_b64_e32 v[40:41], 0
	v_mov_b64_e32 v[42:43], 0
	v_mov_b64_e32 v[44:45], 0
	v_mov_b64_e32 v[46:47], 0
	v_mov_b64_e32 v[48:49], 0
	v_mov_b64_e32 v[50:51], 0
	v_mov_b64_e32 v[52:53], 0
	v_mov_b64_e32 v[54:55], 0
	v_mov_b64_e32 v[56:57], 0
	v_mov_b64_e32 v[58:59], 0
	v_mov_b64_e32 v[60:61], 0
	v_mov_b64_e32 v[62:63], 0
	v_mov_b64_e32 v[64:65], 0
	v_mov_b64_e32 v[66:67], 0
	v_mov_b64_e32 v[68:69], 0
	v_mov_b64_e32 v[70:71], 0
	v_mov_b64_e32 v[72:73], 0
	v_mov_b64_e32 v[74:75], 0
	v_mov_b64_e32 v[76:77], 0
	v_mov_b64_e32 v[78:79], 0
	v_mov_b64_e32 v[80:81], 0
	v_mov_b64_e32 v[82:83], 0
	v_mov_b64_e32 v[84:85], 0
	v_mov_b64_e32 v[86:87], 0
	v_mov_b64_e32 v[88:89], 0
	v_mov_b64_e32 v[90:91], 0
	v_mov_b64_e32 v[92:93], 0
	v_mov_b64_e32 v[94:95], 0
	v_mov_b64_e32 v[96:97], 0
	v_mov_b64_e32 v[98:99], 0
	v_mov_b64_e32 v[100:101], 0
	v_mov_b64_e32 v[102:103], 0
	v_mov_b64_e32 v[104:105], 0
	v_mov_b64_e32 v[106:107], 0
	v_mov_b64_e32 v[108:109], 0
	v_mov_b64_e32 v[110:111], 0
	v_mov_b64_e32 v[112:113], 0
	v_mov_b64_e32 v[114:115], 0
	v_mov_b64_e32 v[116:117], 0
	v_mov_b64_e32 v[118:119], 0
	v_mov_b64_e32 v[120:121], 0
	v_mov_b64_e32 v[122:123], 0
	v_mov_b64_e32 v[124:125], 0
	v_mov_b64_e32 v[126:127], 0
.LBB0_1249:
	s_mov_b64 s[6:7], s[70:71]
	ds_read_b128 v[140:143], v151
	ds_read_b128 v[144:147], v151 offset:1024
	ds_read_b128 v[154:157], v151 offset:2048
	ds_read_b128 v[158:161], v151 offset:3072
	ds_read_b128 v[162:165], v152
	ds_read_b128 v[166:169], v152 offset:1024
	ds_read_b128 v[170:173], v152 offset:2048
	ds_read_b128 v[174:177], v152 offset:3072
	s_add_u32 s5, s66, s6
	s_addc_u32 s8, s67, s7
	s_add_u32 s9, s5, 0x100
	s_addc_u32 s28, s8, 0
	s_add_u32 s6, s68, s6
	s_addc_u32 s7, s69, s7
	s_add_u32 s6, s6, 0x100
	s_addc_u32 s7, s7, 0
	s_cmp_eq_u32 s80, s4
	s_cselect_b32 s75, s63, s28
	s_cselect_b32 s74, s62, s9
	s_cselect_b32 s73, s65, s7
	s_cselect_b32 s72, s64, s6
	s_add_u32 s6, s5, 0x80080
	s_addc_u32 s7, s8, 0
	v_lshl_add_u64 v[178:179], s[6:7], 0, v[134:135]
	s_add_i32 m0, s23, 0xc000
	ds_read_b128 v[182:185], v153
	ds_read_b128 v[186:189], v153 offset:1024
	ds_read_b128 v[190:193], v153 offset:2048
	ds_read_b128 v[194:197], v153 offset:3072
	ds_read_b128 v[198:201], v153 offset:4096
	ds_read_b128 v[202:205], v153 offset:5120
	ds_read_b128 v[206:209], v153 offset:6144
	ds_read_b128 v[210:213], v153 offset:7168
	global_load_lds_dwordx4 v[178:179], off
	v_lshl_add_u64 v[178:179], s[6:7], 0, v[130:131]
	s_add_i32 m0, s23, 0xe000
	s_nop 0
	global_load_lds_dwordx4 v[178:179], off
	s_waitcnt vmcnt(8)
	s_waitcnt lgkmcnt(0)
	s_barrier
	s_setprio 1
	v_mfma_f32_16x16x32_bf16 v[124:127], v[140:143], v[182:185], v[124:127]
	v_mfma_f32_16x16x32_bf16 v[120:123], v[154:157], v[182:185], v[120:123]
	v_mfma_f32_16x16x32_bf16 v[116:119], v[140:143], v[190:193], v[116:119]
	v_mfma_f32_16x16x32_bf16 v[112:115], v[154:157], v[190:193], v[112:115]
	v_mfma_f32_16x16x32_bf16 v[104:107], v[140:143], v[198:201], v[104:107]
	v_mfma_f32_16x16x32_bf16 v[96:99], v[154:157], v[198:201], v[96:99]
	v_mfma_f32_16x16x32_bf16 v[88:91], v[140:143], v[206:209], v[88:91]
	v_mfma_f32_16x16x32_bf16 v[80:83], v[154:157], v[206:209], v[80:83]
	v_mfma_f32_16x16x32_bf16 v[124:127], v[144:147], v[186:189], v[124:127]
	v_mfma_f32_16x16x32_bf16 v[120:123], v[158:161], v[186:189], v[120:123]
	v_mfma_f32_16x16x32_bf16 v[116:119], v[144:147], v[194:197], v[116:119]
	v_mfma_f32_16x16x32_bf16 v[112:115], v[158:161], v[194:197], v[112:115]
	v_mfma_f32_16x16x32_bf16 v[104:107], v[144:147], v[202:205], v[104:107]
	v_mfma_f32_16x16x32_bf16 v[96:99], v[158:161], v[202:205], v[96:99]
	v_mfma_f32_16x16x32_bf16 v[88:91], v[144:147], v[210:213], v[88:91]
	v_mfma_f32_16x16x32_bf16 v[80:83], v[158:161], v[210:213], v[80:83]
	s_setprio 0
	s_setprio 1
	v_mfma_f32_16x16x32_bf16 v[108:111], v[162:165], v[182:185], v[108:111]
	v_mfma_f32_16x16x32_bf16 v[100:103], v[170:173], v[182:185], v[100:103]
	v_mfma_f32_16x16x32_bf16 v[92:95], v[162:165], v[190:193], v[92:95]
	v_mfma_f32_16x16x32_bf16 v[84:87], v[170:173], v[190:193], v[84:87]
	v_mfma_f32_16x16x32_bf16 v[76:79], v[162:165], v[198:201], v[76:79]
	v_mfma_f32_16x16x32_bf16 v[72:75], v[170:173], v[198:201], v[72:75]
	v_mfma_f32_16x16x32_bf16 v[68:71], v[162:165], v[206:209], v[68:71]
	v_mfma_f32_16x16x32_bf16 v[64:67], v[170:173], v[206:209], v[64:67]
	v_mfma_f32_16x16x32_bf16 v[108:111], v[166:169], v[186:189], v[108:111]
	v_mfma_f32_16x16x32_bf16 v[100:103], v[174:177], v[186:189], v[100:103]
	v_mfma_f32_16x16x32_bf16 v[92:95], v[166:169], v[194:197], v[92:95]
	v_mfma_f32_16x16x32_bf16 v[84:87], v[174:177], v[194:197], v[84:87]
	v_mfma_f32_16x16x32_bf16 v[76:79], v[166:169], v[202:205], v[76:79]
	v_mfma_f32_16x16x32_bf16 v[72:75], v[174:177], v[202:205], v[72:75]
	v_mfma_f32_16x16x32_bf16 v[68:71], v[166:169], v[210:213], v[68:71]
	v_mfma_f32_16x16x32_bf16 v[64:67], v[174:177], v[210:213], v[64:67]
	s_setprio 0
	s_barrier
	s_add_i32 s5, s81, s18
	v_lshl_add_u64 v[178:179], s[72:73], 0, v[132:133]
	s_mov_b32 m0, s5
	ds_read_b128 v[182:185], v153 offset:16384
	ds_read_b128 v[186:189], v153 offset:17408
	ds_read_b128 v[190:193], v153 offset:18432
	ds_read_b128 v[194:197], v153 offset:19456
	ds_read_b128 v[198:201], v153 offset:20480
	ds_read_b128 v[202:205], v153 offset:21504
	ds_read_b128 v[206:209], v153 offset:22528
	ds_read_b128 v[210:213], v153 offset:23552
	global_load_lds_dwordx4 v[178:179], off
	s_add_i32 m0, s5, 0x2000
	s_add_u32 s6, s72, 0x80000
	v_lshl_add_u64 v[214:215], s[72:73], 0, v[128:129]
	s_addc_u32 s7, s73, 0
	s_add_i32 s5, s82, s18
	global_load_lds_dwordx4 v[214:215], off
	v_lshl_add_u64 v[216:217], s[6:7], 0, v[132:133]
	s_mov_b32 m0, s5
	v_lshl_add_u64 v[218:219], s[74:75], 0, v[130:131]
	global_load_lds_dwordx4 v[216:217], off
	v_lshl_add_u64 v[216:217], s[6:7], 0, v[128:129]
	s_add_i32 m0, s5, 0x2000
	s_nop 0
	global_load_lds_dwordx4 v[216:217], off
	v_lshl_add_u64 v[216:217], s[74:75], 0, v[134:135]
	s_mov_b32 m0, s23
	s_nop 0
	global_load_lds_dwordx4 v[216:217], off
	s_mov_b32 m0, s30
	s_nop 0
	global_load_lds_dwordx4 v[218:219], off
	s_waitcnt vmcnt(8)
	s_waitcnt lgkmcnt(0)
	s_barrier
	s_setprio 1
	v_mfma_f32_16x16x32_bf16 v[60:63], v[140:143], v[182:185], v[60:63]
	v_mfma_f32_16x16x32_bf16 v[56:59], v[154:157], v[182:185], v[56:59]
	v_mfma_f32_16x16x32_bf16 v[52:55], v[140:143], v[190:193], v[52:55]
	v_mfma_f32_16x16x32_bf16 v[48:51], v[154:157], v[190:193], v[48:51]
	v_mfma_f32_16x16x32_bf16 v[40:43], v[140:143], v[198:201], v[40:43]
	v_mfma_f32_16x16x32_bf16 v[32:35], v[154:157], v[198:201], v[32:35]
	v_mfma_f32_16x16x32_bf16 v[24:27], v[140:143], v[206:209], v[24:27]
	v_mfma_f32_16x16x32_bf16 v[16:19], v[154:157], v[206:209], v[16:19]
	v_mfma_f32_16x16x32_bf16 v[60:63], v[144:147], v[186:189], v[60:63]
	v_mfma_f32_16x16x32_bf16 v[56:59], v[158:161], v[186:189], v[56:59]
	v_mfma_f32_16x16x32_bf16 v[52:55], v[144:147], v[194:197], v[52:55]
	v_mfma_f32_16x16x32_bf16 v[48:51], v[158:161], v[194:197], v[48:51]
	v_mfma_f32_16x16x32_bf16 v[40:43], v[144:147], v[202:205], v[40:43]
	v_mfma_f32_16x16x32_bf16 v[32:35], v[158:161], v[202:205], v[32:35]
	v_mfma_f32_16x16x32_bf16 v[24:27], v[144:147], v[210:213], v[24:27]
	v_mfma_f32_16x16x32_bf16 v[16:19], v[158:161], v[210:213], v[16:19]
	s_setprio 0
	s_setprio 1
	v_mfma_f32_16x16x32_bf16 v[44:47], v[162:165], v[182:185], v[44:47]
	v_mfma_f32_16x16x32_bf16 v[36:39], v[170:173], v[182:185], v[36:39]
	v_mfma_f32_16x16x32_bf16 v[28:31], v[162:165], v[190:193], v[28:31]
	v_mfma_f32_16x16x32_bf16 v[20:23], v[170:173], v[190:193], v[20:23]
	v_mfma_f32_16x16x32_bf16 v[12:15], v[162:165], v[198:201], v[12:15]
	v_mfma_f32_16x16x32_bf16 v[8:11], v[170:173], v[198:201], v[8:11]
	v_mfma_f32_16x16x32_bf16 v[4:7], v[162:165], v[206:209], v[4:7]
	v_mfma_f32_16x16x32_bf16 v[0:3], v[170:173], v[206:209], v[0:3]
	v_mfma_f32_16x16x32_bf16 v[44:47], v[166:169], v[186:189], v[44:47]
	v_mfma_f32_16x16x32_bf16 v[36:39], v[174:177], v[186:189], v[36:39]
	v_mfma_f32_16x16x32_bf16 v[28:31], v[166:169], v[194:197], v[28:31]
	v_mfma_f32_16x16x32_bf16 v[20:23], v[174:177], v[194:197], v[20:23]
	v_mfma_f32_16x16x32_bf16 v[12:15], v[166:169], v[202:205], v[12:15]
	v_mfma_f32_16x16x32_bf16 v[8:11], v[174:177], v[202:205], v[8:11]
	v_mfma_f32_16x16x32_bf16 v[4:7], v[166:169], v[210:213], v[4:7]
	v_mfma_f32_16x16x32_bf16 v[0:3], v[174:177], v[210:213], v[0:3]
	s_setprio 0
	s_barrier
	s_add_i32 s5, 0, 0x18000
	s_add_i32 s8, 0, 0x1c000
	v_add_u32_e32 v158, s5, v150
	v_add_u32_e32 v174, s8, v150
	ds_read_b128 v[140:143], v158
	ds_read_b128 v[144:147], v158 offset:1024
	ds_read_b128 v[154:157], v158 offset:2048
	ds_read_b128 v[158:161], v158 offset:3072
	ds_read_b128 v[162:165], v174
	ds_read_b128 v[166:169], v174 offset:1024
	ds_read_b128 v[170:173], v174 offset:2048
	ds_read_b128 v[174:177], v174 offset:3072
	s_add_u32 s6, s74, 0x80000
	s_addc_u32 s7, s75, 0
	s_mov_b32 m0, s31
	v_lshl_add_u64 v[220:221], s[6:7], 0, v[134:135]
	ds_read_b128 v[182:185], v153 offset:32768
	ds_read_b128 v[186:189], v153 offset:33792
	ds_read_b128 v[190:193], v153 offset:34816
	ds_read_b128 v[194:197], v153 offset:35840
	ds_read_b128 v[198:201], v153 offset:36864
	ds_read_b128 v[202:205], v153 offset:37888
	ds_read_b128 v[206:209], v153 offset:38912
	ds_read_b128 v[210:213], v153 offset:39936
	global_load_lds_dwordx4 v[220:221], off
	v_lshl_add_u64 v[220:221], s[6:7], 0, v[130:131]
	s_mov_b32 m0, s56
	s_nop 0
	global_load_lds_dwordx4 v[220:221], off
	s_waitcnt vmcnt(8)
	s_waitcnt lgkmcnt(0)
	s_barrier
	s_setprio 1
	v_mfma_f32_16x16x32_bf16 v[124:127], v[140:143], v[182:185], v[124:127]
	v_mfma_f32_16x16x32_bf16 v[120:123], v[154:157], v[182:185], v[120:123]
	v_mfma_f32_16x16x32_bf16 v[116:119], v[140:143], v[190:193], v[116:119]
	v_mfma_f32_16x16x32_bf16 v[112:115], v[154:157], v[190:193], v[112:115]
	v_mfma_f32_16x16x32_bf16 v[104:107], v[140:143], v[198:201], v[104:107]
	v_mfma_f32_16x16x32_bf16 v[96:99], v[154:157], v[198:201], v[96:99]
	v_mfma_f32_16x16x32_bf16 v[88:91], v[140:143], v[206:209], v[88:91]
	v_mfma_f32_16x16x32_bf16 v[80:83], v[154:157], v[206:209], v[80:83]
	v_mfma_f32_16x16x32_bf16 v[124:127], v[144:147], v[186:189], v[124:127]
	v_mfma_f32_16x16x32_bf16 v[120:123], v[158:161], v[186:189], v[120:123]
	v_mfma_f32_16x16x32_bf16 v[116:119], v[144:147], v[194:197], v[116:119]
	v_mfma_f32_16x16x32_bf16 v[112:115], v[158:161], v[194:197], v[112:115]
	v_mfma_f32_16x16x32_bf16 v[104:107], v[144:147], v[202:205], v[104:107]
	v_mfma_f32_16x16x32_bf16 v[96:99], v[158:161], v[202:205], v[96:99]
	v_mfma_f32_16x16x32_bf16 v[88:91], v[144:147], v[210:213], v[88:91]
	v_mfma_f32_16x16x32_bf16 v[80:83], v[158:161], v[210:213], v[80:83]
	s_setprio 0
	s_setprio 1
	v_mfma_f32_16x16x32_bf16 v[108:111], v[162:165], v[182:185], v[108:111]
	v_mfma_f32_16x16x32_bf16 v[100:103], v[170:173], v[182:185], v[100:103]
	v_mfma_f32_16x16x32_bf16 v[92:95], v[162:165], v[190:193], v[92:95]
	v_mfma_f32_16x16x32_bf16 v[84:87], v[170:173], v[190:193], v[84:87]
	v_mfma_f32_16x16x32_bf16 v[76:79], v[162:165], v[198:201], v[76:79]
	v_mfma_f32_16x16x32_bf16 v[72:75], v[170:173], v[198:201], v[72:75]
	v_mfma_f32_16x16x32_bf16 v[68:71], v[162:165], v[206:209], v[68:71]
	v_mfma_f32_16x16x32_bf16 v[64:67], v[170:173], v[206:209], v[64:67]
	v_mfma_f32_16x16x32_bf16 v[108:111], v[166:169], v[186:189], v[108:111]
	v_mfma_f32_16x16x32_bf16 v[100:103], v[174:177], v[186:189], v[100:103]
	v_mfma_f32_16x16x32_bf16 v[92:95], v[166:169], v[194:197], v[92:95]
	v_mfma_f32_16x16x32_bf16 v[84:87], v[174:177], v[194:197], v[84:87]
	v_mfma_f32_16x16x32_bf16 v[76:79], v[166:169], v[202:205], v[76:79]
	v_mfma_f32_16x16x32_bf16 v[72:75], v[174:177], v[202:205], v[72:75]
	v_mfma_f32_16x16x32_bf16 v[68:71], v[166:169], v[210:213], v[68:71]
	v_mfma_f32_16x16x32_bf16 v[64:67], v[174:177], v[210:213], v[64:67]
	s_setprio 0
	s_barrier
	s_add_i32 s5, s5, s18
	v_lshl_add_u64 v[178:179], v[178:179], 0, s[2:3]
	s_mov_b32 m0, s5
	ds_read_b128 v[182:185], v153 offset:49152
	ds_read_b128 v[186:189], v153 offset:50176
	ds_read_b128 v[190:193], v153 offset:51200
	ds_read_b128 v[194:197], v153 offset:52224
	ds_read_b128 v[198:201], v153 offset:53248
	ds_read_b128 v[202:205], v153 offset:54272
	ds_read_b128 v[206:209], v153 offset:55296
	ds_read_b128 v[210:213], v153 offset:56320
	global_load_lds_dwordx4 v[178:179], off
	s_add_i32 m0, s5, 0x2000
	s_add_u32 s6, s72, 0x80080
	v_lshl_add_u64 v[178:179], v[214:215], 0, s[2:3]
	s_addc_u32 s7, s73, 0
	s_add_i32 s5, s8, s18
	global_load_lds_dwordx4 v[178:179], off
	v_lshl_add_u64 v[178:179], s[6:7], 0, v[132:133]
	s_mov_b32 m0, s5
	s_nop 0
	global_load_lds_dwordx4 v[178:179], off
	v_lshl_add_u64 v[178:179], s[6:7], 0, v[128:129]
	s_add_i32 m0, s5, 0x2000
	s_nop 0
	global_load_lds_dwordx4 v[178:179], off
	v_lshl_add_u64 v[178:179], v[216:217], 0, s[2:3]
	s_mov_b32 m0, s77
	s_nop 0
	global_load_lds_dwordx4 v[178:179], off
	v_lshl_add_u64 v[178:179], v[218:219], 0, s[2:3]
	s_mov_b32 m0, s79
	s_nop 0
	global_load_lds_dwordx4 v[178:179], off
	s_waitcnt vmcnt(8)
	s_waitcnt lgkmcnt(0)
	s_barrier
	s_setprio 1
	v_mfma_f32_16x16x32_bf16 v[60:63], v[140:143], v[182:185], v[60:63]
	v_mfma_f32_16x16x32_bf16 v[56:59], v[154:157], v[182:185], v[56:59]
	v_mfma_f32_16x16x32_bf16 v[52:55], v[140:143], v[190:193], v[52:55]
	v_mfma_f32_16x16x32_bf16 v[48:51], v[154:157], v[190:193], v[48:51]
	v_mfma_f32_16x16x32_bf16 v[40:43], v[140:143], v[198:201], v[40:43]
	v_mfma_f32_16x16x32_bf16 v[32:35], v[154:157], v[198:201], v[32:35]
	v_mfma_f32_16x16x32_bf16 v[24:27], v[140:143], v[206:209], v[24:27]
	v_mfma_f32_16x16x32_bf16 v[16:19], v[154:157], v[206:209], v[16:19]
	v_mfma_f32_16x16x32_bf16 v[60:63], v[144:147], v[186:189], v[60:63]
	v_mfma_f32_16x16x32_bf16 v[56:59], v[158:161], v[186:189], v[56:59]
	v_mfma_f32_16x16x32_bf16 v[52:55], v[144:147], v[194:197], v[52:55]
	v_mfma_f32_16x16x32_bf16 v[48:51], v[158:161], v[194:197], v[48:51]
	v_mfma_f32_16x16x32_bf16 v[40:43], v[144:147], v[202:205], v[40:43]
	v_mfma_f32_16x16x32_bf16 v[32:35], v[158:161], v[202:205], v[32:35]
	v_mfma_f32_16x16x32_bf16 v[24:27], v[144:147], v[210:213], v[24:27]
	v_mfma_f32_16x16x32_bf16 v[16:19], v[158:161], v[210:213], v[16:19]
	s_setprio 0
	s_setprio 1
	v_mfma_f32_16x16x32_bf16 v[44:47], v[162:165], v[182:185], v[44:47]
	v_mfma_f32_16x16x32_bf16 v[36:39], v[170:173], v[182:185], v[36:39]
	v_mfma_f32_16x16x32_bf16 v[28:31], v[162:165], v[190:193], v[28:31]
	v_mfma_f32_16x16x32_bf16 v[20:23], v[170:173], v[190:193], v[20:23]
	v_mfma_f32_16x16x32_bf16 v[12:15], v[162:165], v[198:201], v[12:15]
	v_mfma_f32_16x16x32_bf16 v[8:11], v[170:173], v[198:201], v[8:11]
	v_mfma_f32_16x16x32_bf16 v[4:7], v[162:165], v[206:209], v[4:7]
	v_mfma_f32_16x16x32_bf16 v[0:3], v[170:173], v[206:209], v[0:3]
	v_mfma_f32_16x16x32_bf16 v[44:47], v[166:169], v[186:189], v[44:47]
	v_mfma_f32_16x16x32_bf16 v[36:39], v[174:177], v[186:189], v[36:39]
	v_mfma_f32_16x16x32_bf16 v[28:31], v[166:169], v[194:197], v[28:31]
	v_mfma_f32_16x16x32_bf16 v[20:23], v[174:177], v[194:197], v[20:23]
	v_mfma_f32_16x16x32_bf16 v[12:15], v[166:169], v[202:205], v[12:15]
	v_mfma_f32_16x16x32_bf16 v[8:11], v[174:177], v[202:205], v[8:11]
	v_mfma_f32_16x16x32_bf16 v[4:7], v[166:169], v[210:213], v[4:7]
	v_mfma_f32_16x16x32_bf16 v[0:3], v[174:177], v[210:213], v[0:3]
	s_setprio 0
	s_barrier
	s_add_i32 s4, s4, 2
	s_add_u32 s70, s70, 0x100
	s_addc_u32 s71, s71, 0
	s_cmp_ge_i32 s4, s57
	s_cbranch_scc0 .LBB0_1249
	v_pk_add_f32 v[126:127], v[126:127], 0 op_sel_hi:[1,0]
	v_pk_add_f32 v[124:125], v[124:125], 0 op_sel_hi:[1,0]
	v_pk_add_f32 v[122:123], v[122:123], 0 op_sel_hi:[1,0]
	v_pk_add_f32 v[120:121], v[120:121], 0 op_sel_hi:[1,0]
	v_pk_add_f32 v[140:141], v[110:111], 0 op_sel_hi:[1,0]
	v_pk_add_f32 v[142:143], v[108:109], 0 op_sel_hi:[1,0]
	v_pk_add_f32 v[144:145], v[102:103], 0 op_sel_hi:[1,0]
	v_pk_add_f32 v[146:147], v[100:101], 0 op_sel_hi:[1,0]
	v_pk_add_f32 v[100:101], v[118:119], 0 op_sel_hi:[1,0]
	v_pk_add_f32 v[102:103], v[116:117], 0 op_sel_hi:[1,0]
	v_pk_add_f32 v[108:109], v[114:115], 0 op_sel_hi:[1,0]
	v_pk_add_f32 v[110:111], v[112:113], 0 op_sel_hi:[1,0]
	v_pk_add_f32 v[112:113], v[94:95], 0 op_sel_hi:[1,0]
	v_pk_add_f32 v[114:115], v[92:93], 0 op_sel_hi:[1,0]
	v_pk_add_f32 v[116:117], v[86:87], 0 op_sel_hi:[1,0]
	v_pk_add_f32 v[118:119], v[84:85], 0 op_sel_hi:[1,0]
	v_pk_add_f32 v[84:85], v[106:107], 0 op_sel_hi:[1,0]
	v_pk_add_f32 v[86:87], v[104:105], 0 op_sel_hi:[1,0]
	v_pk_add_f32 v[92:93], v[98:99], 0 op_sel_hi:[1,0]
	v_pk_add_f32 v[94:95], v[96:97], 0 op_sel_hi:[1,0]
	v_pk_add_f32 v[96:97], v[78:79], 0 op_sel_hi:[1,0]
	v_pk_add_f32 v[98:99], v[76:77], 0 op_sel_hi:[1,0]
	v_pk_add_f32 v[104:105], v[74:75], 0 op_sel_hi:[1,0]
	v_pk_add_f32 v[106:107], v[72:73], 0 op_sel_hi:[1,0]
	v_pk_add_f32 v[72:73], v[90:91], 0 op_sel_hi:[1,0]
	v_pk_add_f32 v[74:75], v[88:89], 0 op_sel_hi:[1,0]
	v_pk_add_f32 v[76:77], v[82:83], 0 op_sel_hi:[1,0]
	v_pk_add_f32 v[78:79], v[80:81], 0 op_sel_hi:[1,0]
	v_pk_add_f32 v[70:71], v[70:71], 0 op_sel_hi:[1,0]
	v_pk_add_f32 v[68:69], v[68:69], 0 op_sel_hi:[1,0]
	v_pk_add_f32 v[66:67], v[66:67], 0 op_sel_hi:[1,0]
	v_pk_add_f32 v[64:65], v[64:65], 0 op_sel_hi:[1,0]
	v_pk_add_f32 v[62:63], v[62:63], 0 op_sel_hi:[1,0]
	v_pk_add_f32 v[60:61], v[60:61], 0 op_sel_hi:[1,0]
	v_pk_add_f32 v[58:59], v[58:59], 0 op_sel_hi:[1,0]
	v_pk_add_f32 v[56:57], v[56:57], 0 op_sel_hi:[1,0]
	v_pk_add_f32 v[80:81], v[46:47], 0 op_sel_hi:[1,0]
	v_pk_add_f32 v[82:83], v[44:45], 0 op_sel_hi:[1,0]
	v_pk_add_f32 v[88:89], v[38:39], 0 op_sel_hi:[1,0]
	v_pk_add_f32 v[90:91], v[36:37], 0 op_sel_hi:[1,0]
	v_pk_add_f32 v[36:37], v[54:55], 0 op_sel_hi:[1,0]
	v_pk_add_f32 v[38:39], v[52:53], 0 op_sel_hi:[1,0]
	v_pk_add_f32 v[44:45], v[50:51], 0 op_sel_hi:[1,0]
	v_pk_add_f32 v[46:47], v[48:49], 0 op_sel_hi:[1,0]
	v_pk_add_f32 v[48:49], v[30:31], 0 op_sel_hi:[1,0]
	v_pk_add_f32 v[50:51], v[28:29], 0 op_sel_hi:[1,0]
	v_pk_add_f32 v[52:53], v[22:23], 0 op_sel_hi:[1,0]
	v_pk_add_f32 v[54:55], v[20:21], 0 op_sel_hi:[1,0]
	v_pk_add_f32 v[20:21], v[42:43], 0 op_sel_hi:[1,0]
	v_pk_add_f32 v[22:23], v[40:41], 0 op_sel_hi:[1,0]
	v_pk_add_f32 v[28:29], v[34:35], 0 op_sel_hi:[1,0]
	v_pk_add_f32 v[30:31], v[32:33], 0 op_sel_hi:[1,0]
	v_pk_add_f32 v[32:33], v[14:15], 0 op_sel_hi:[1,0]
	v_pk_add_f32 v[34:35], v[12:13], 0 op_sel_hi:[1,0]
	v_pk_add_f32 v[40:41], v[10:11], 0 op_sel_hi:[1,0]
	v_pk_add_f32 v[42:43], v[8:9], 0 op_sel_hi:[1,0]
	v_pk_add_f32 v[8:9], v[26:27], 0 op_sel_hi:[1,0]
	v_pk_add_f32 v[10:11], v[24:25], 0 op_sel_hi:[1,0]
	v_pk_add_f32 v[12:13], v[18:19], 0 op_sel_hi:[1,0]
	v_pk_add_f32 v[14:15], v[16:17], 0 op_sel_hi:[1,0]
	v_pk_add_f32 v[6:7], v[6:7], 0 op_sel_hi:[1,0]
	v_pk_add_f32 v[4:5], v[4:5], 0 op_sel_hi:[1,0]
	v_pk_add_f32 v[2:3], v[2:3], 0 op_sel_hi:[1,0]
	v_pk_add_f32 v[0:1], v[0:1], 0 op_sel_hi:[1,0]

.LBB0_1323:
	s_mov_b64 s[42:43], s[72:73]
	s_add_u32 s44, s70, s42
	s_addc_u32 s45, s71, s43
	s_add_u32 s48, s44, 0x100
	s_addc_u32 s49, s45, 0
	s_add_u32 s42, s68, s42
	s_addc_u32 s43, s69, s43
	s_add_u32 s42, s42, 0x100
	s_addc_u32 s43, s43, 0
	s_add_i32 s50, 0, 0x10000
	s_cmp_eq_u32 s9, s86
	s_cselect_b32 s77, s65, s49
	s_cselect_b32 s76, s64, s48
	s_cselect_b32 s75, s67, s43
	s_cselect_b32 s74, s66, s42
	s_add_i32 s48, 0, 0x14000
	v_add_u32_e32 v152, s50, v138
	v_add_u32_e32 v168, s48, v138
	ds_read_b128 v[140:143], v152
	ds_read_b128 v[144:147], v152 offset:1024
	ds_read_b128 v[148:151], v152 offset:2048
	ds_read_b128 v[152:155], v152 offset:3072
	ds_read_b128 v[156:159], v168
	ds_read_b128 v[160:163], v168 offset:1024
	ds_read_b128 v[164:167], v168 offset:2048
	ds_read_b128 v[168:171], v168 offset:3072
	s_add_u32 s42, s44, 0x100080
	s_addc_u32 s43, s45, 0
	v_lshl_add_u64 v[186:187], s[42:43], 0, v[134:135]
	s_add_i32 m0, s93, 0xc000
	ds_read_b128 v[172:175], v139
	ds_read_b128 v[176:179], v139 offset:1024
	ds_read_b128 v[182:185], v139 offset:2048
	ds_read_b128 v[190:193], v139 offset:3072
	ds_read_b128 v[194:197], v139 offset:4096
	ds_read_b128 v[198:201], v139 offset:5120
	ds_read_b128 v[202:205], v139 offset:6144
	ds_read_b128 v[206:209], v139 offset:7168
	global_load_lds_dwordx4 v[186:187], off
	v_lshl_add_u64 v[186:187], s[42:43], 0, v[132:133]
	s_add_i32 m0, s93, 0xe000
	s_nop 0
	global_load_lds_dwordx4 v[186:187], off
	s_waitcnt vmcnt(8)
	s_waitcnt lgkmcnt(0)
	s_barrier
	s_setprio 1
	v_mfma_f32_16x16x32_bf16 v[126:129], v[140:143], v[172:175], v[126:129]
	v_mfma_f32_16x16x32_bf16 v[122:125], v[148:151], v[172:175], v[122:125]
	v_mfma_f32_16x16x32_bf16 v[110:113], v[140:143], v[182:185], v[110:113]
	v_mfma_f32_16x16x32_bf16 v[106:109], v[148:151], v[182:185], v[106:109]
	v_mfma_f32_16x16x32_bf16 v[94:97], v[140:143], v[194:197], v[94:97]
	v_mfma_f32_16x16x32_bf16 v[90:93], v[148:151], v[194:197], v[90:93]
	v_mfma_f32_16x16x32_bf16 v[78:81], v[140:143], v[202:205], v[78:81]
	v_mfma_f32_16x16x32_bf16 v[74:77], v[148:151], v[202:205], v[74:77]
	v_mfma_f32_16x16x32_bf16 v[126:129], v[144:147], v[176:179], v[126:129]
	v_mfma_f32_16x16x32_bf16 v[122:125], v[152:155], v[176:179], v[122:125]
	v_mfma_f32_16x16x32_bf16 v[110:113], v[144:147], v[190:193], v[110:113]
	v_mfma_f32_16x16x32_bf16 v[106:109], v[152:155], v[190:193], v[106:109]
	v_mfma_f32_16x16x32_bf16 v[94:97], v[144:147], v[198:201], v[94:97]
	v_mfma_f32_16x16x32_bf16 v[90:93], v[152:155], v[198:201], v[90:93]
	v_mfma_f32_16x16x32_bf16 v[78:81], v[144:147], v[206:209], v[78:81]
	v_mfma_f32_16x16x32_bf16 v[74:77], v[152:155], v[206:209], v[74:77]
	s_setprio 0
	s_setprio 1
	v_mfma_f32_16x16x32_bf16 v[118:121], v[156:159], v[172:175], v[118:121]
	v_mfma_f32_16x16x32_bf16 v[114:117], v[164:167], v[172:175], v[114:117]
	v_mfma_f32_16x16x32_bf16 v[102:105], v[156:159], v[182:185], v[102:105]
	v_mfma_f32_16x16x32_bf16 v[98:101], v[164:167], v[182:185], v[98:101]
	v_mfma_f32_16x16x32_bf16 v[86:89], v[156:159], v[194:197], v[86:89]
	v_mfma_f32_16x16x32_bf16 v[82:85], v[164:167], v[194:197], v[82:85]
	v_mfma_f32_16x16x32_bf16 v[70:73], v[156:159], v[202:205], v[70:73]
	v_mfma_f32_16x16x32_bf16 v[66:69], v[164:167], v[202:205], v[66:69]
	v_mfma_f32_16x16x32_bf16 v[118:121], v[160:163], v[176:179], v[118:121]
	v_mfma_f32_16x16x32_bf16 v[114:117], v[168:171], v[176:179], v[114:117]
	v_mfma_f32_16x16x32_bf16 v[102:105], v[160:163], v[190:193], v[102:105]
	v_mfma_f32_16x16x32_bf16 v[98:101], v[168:171], v[190:193], v[98:101]
	v_mfma_f32_16x16x32_bf16 v[86:89], v[160:163], v[198:201], v[86:89]
	v_mfma_f32_16x16x32_bf16 v[82:85], v[168:171], v[198:201], v[82:85]
	v_mfma_f32_16x16x32_bf16 v[70:73], v[160:163], v[206:209], v[70:73]
	v_mfma_f32_16x16x32_bf16 v[66:69], v[168:171], v[206:209], v[66:69]
	s_setprio 0
	s_barrier
	s_add_i32 s42, s50, s92
	v_lshl_add_u64 v[186:187], s[74:75], 0, v[0:1]
	s_mov_b32 m0, s42
	ds_read_b128 v[172:175], v139 offset:16384
	ds_read_b128 v[176:179], v139 offset:17408
	ds_read_b128 v[182:185], v139 offset:18432
	ds_read_b128 v[190:193], v139 offset:19456
	ds_read_b128 v[194:197], v139 offset:20480
	ds_read_b128 v[198:201], v139 offset:21504
	ds_read_b128 v[202:205], v139 offset:22528
	ds_read_b128 v[206:209], v139 offset:23552
	global_load_lds_dwordx4 v[186:187], off
	s_add_i32 m0, s42, 0x2000
	s_add_u32 s42, s74, 0x500000
	v_lshl_add_u64 v[210:211], s[74:75], 0, v[130:131]
	s_addc_u32 s43, s75, 0
	s_add_i32 s44, s48, s92
	global_load_lds_dwordx4 v[210:211], off
	v_lshl_add_u64 v[212:213], s[42:43], 0, v[0:1]
	s_mov_b32 m0, s44
	v_lshl_add_u64 v[214:215], s[76:77], 0, v[132:133]
	global_load_lds_dwordx4 v[212:213], off
	v_lshl_add_u64 v[212:213], s[42:43], 0, v[130:131]
	s_add_i32 m0, s44, 0x2000
	s_nop 0
	global_load_lds_dwordx4 v[212:213], off
	v_lshl_add_u64 v[212:213], s[76:77], 0, v[134:135]
	s_mov_b32 m0, s93
	s_nop 0
	global_load_lds_dwordx4 v[212:213], off
	s_mov_b32 m0, s94
	s_nop 0
	global_load_lds_dwordx4 v[214:215], off
	s_waitcnt vmcnt(8)
	s_waitcnt lgkmcnt(0)
	s_barrier
	s_setprio 1
	v_mfma_f32_16x16x32_bf16 v[62:65], v[140:143], v[172:175], v[62:65]
	v_mfma_f32_16x16x32_bf16 v[58:61], v[148:151], v[172:175], v[58:61]
	v_mfma_f32_16x16x32_bf16 v[46:49], v[140:143], v[182:185], v[46:49]
	v_mfma_f32_16x16x32_bf16 v[42:45], v[148:151], v[182:185], v[42:45]
	v_mfma_f32_16x16x32_bf16 v[30:33], v[140:143], v[194:197], v[30:33]
	v_mfma_f32_16x16x32_bf16 v[26:29], v[148:151], v[194:197], v[26:29]
	v_mfma_f32_16x16x32_bf16 v[14:17], v[140:143], v[202:205], v[14:17]
	v_mfma_f32_16x16x32_bf16 v[10:13], v[148:151], v[202:205], v[10:13]
	v_mfma_f32_16x16x32_bf16 v[62:65], v[144:147], v[176:179], v[62:65]
	v_mfma_f32_16x16x32_bf16 v[58:61], v[152:155], v[176:179], v[58:61]
	v_mfma_f32_16x16x32_bf16 v[46:49], v[144:147], v[190:193], v[46:49]
	v_mfma_f32_16x16x32_bf16 v[42:45], v[152:155], v[190:193], v[42:45]
	v_mfma_f32_16x16x32_bf16 v[30:33], v[144:147], v[198:201], v[30:33]
	v_mfma_f32_16x16x32_bf16 v[26:29], v[152:155], v[198:201], v[26:29]
	v_mfma_f32_16x16x32_bf16 v[14:17], v[144:147], v[206:209], v[14:17]
	v_mfma_f32_16x16x32_bf16 v[10:13], v[152:155], v[206:209], v[10:13]
	s_setprio 0
	s_setprio 1
	v_mfma_f32_16x16x32_bf16 v[54:57], v[156:159], v[172:175], v[54:57]
	v_mfma_f32_16x16x32_bf16 v[50:53], v[164:167], v[172:175], v[50:53]
	v_mfma_f32_16x16x32_bf16 v[38:41], v[156:159], v[182:185], v[38:41]
	v_mfma_f32_16x16x32_bf16 v[34:37], v[164:167], v[182:185], v[34:37]
	v_mfma_f32_16x16x32_bf16 v[22:25], v[156:159], v[194:197], v[22:25]
	v_mfma_f32_16x16x32_bf16 v[18:21], v[164:167], v[194:197], v[18:21]
	v_mfma_f32_16x16x32_bf16 v[6:9], v[156:159], v[202:205], v[6:9]
	v_mfma_f32_16x16x32_bf16 v[2:5], v[164:167], v[202:205], v[2:5]
	v_mfma_f32_16x16x32_bf16 v[54:57], v[160:163], v[176:179], v[54:57]
	v_mfma_f32_16x16x32_bf16 v[50:53], v[168:171], v[176:179], v[50:53]
	v_mfma_f32_16x16x32_bf16 v[38:41], v[160:163], v[190:193], v[38:41]
	v_mfma_f32_16x16x32_bf16 v[34:37], v[168:171], v[190:193], v[34:37]
	v_mfma_f32_16x16x32_bf16 v[22:25], v[160:163], v[198:201], v[22:25]
	v_mfma_f32_16x16x32_bf16 v[18:21], v[168:171], v[198:201], v[18:21]
	v_mfma_f32_16x16x32_bf16 v[6:9], v[160:163], v[206:209], v[6:9]
	v_mfma_f32_16x16x32_bf16 v[2:5], v[168:171], v[206:209], v[2:5]
	s_setprio 0
	s_barrier
	s_add_i32 s44, 0, 0x18000
	s_add_i32 s45, 0, 0x1c000
	v_add_u32_e32 v152, s44, v138
	v_add_u32_e32 v168, s45, v138
	ds_read_b128 v[140:143], v152
	ds_read_b128 v[144:147], v152 offset:1024
	ds_read_b128 v[148:151], v152 offset:2048
	ds_read_b128 v[152:155], v152 offset:3072
	ds_read_b128 v[156:159], v168
	ds_read_b128 v[160:163], v168 offset:1024
	ds_read_b128 v[164:167], v168 offset:2048
	ds_read_b128 v[168:171], v168 offset:3072
	s_add_u32 s42, s76, 0x100000
	s_addc_u32 s43, s77, 0
	s_mov_b32 m0, s95
	v_lshl_add_u64 v[216:217], s[42:43], 0, v[134:135]
	ds_read_b128 v[172:175], v139 offset:32768
	ds_read_b128 v[176:179], v139 offset:33792
	ds_read_b128 v[182:185], v139 offset:34816
	ds_read_b128 v[190:193], v139 offset:35840
	ds_read_b128 v[194:197], v139 offset:36864
	ds_read_b128 v[198:201], v139 offset:37888
	ds_read_b128 v[202:205], v139 offset:38912
	ds_read_b128 v[206:209], v139 offset:39936
	global_load_lds_dwordx4 v[216:217], off
	v_lshl_add_u64 v[216:217], s[42:43], 0, v[132:133]
	s_mov_b32 m0, s96
	s_nop 0
	global_load_lds_dwordx4 v[216:217], off
	s_waitcnt vmcnt(8)
	s_waitcnt lgkmcnt(0)
	s_barrier
	s_setprio 1
	v_mfma_f32_16x16x32_bf16 v[126:129], v[140:143], v[172:175], v[126:129]
	v_mfma_f32_16x16x32_bf16 v[122:125], v[148:151], v[172:175], v[122:125]
	v_mfma_f32_16x16x32_bf16 v[110:113], v[140:143], v[182:185], v[110:113]
	v_mfma_f32_16x16x32_bf16 v[106:109], v[148:151], v[182:185], v[106:109]
	v_mfma_f32_16x16x32_bf16 v[94:97], v[140:143], v[194:197], v[94:97]
	v_mfma_f32_16x16x32_bf16 v[90:93], v[148:151], v[194:197], v[90:93]
	v_mfma_f32_16x16x32_bf16 v[78:81], v[140:143], v[202:205], v[78:81]
	v_mfma_f32_16x16x32_bf16 v[74:77], v[148:151], v[202:205], v[74:77]
	v_mfma_f32_16x16x32_bf16 v[126:129], v[144:147], v[176:179], v[126:129]
	v_mfma_f32_16x16x32_bf16 v[122:125], v[152:155], v[176:179], v[122:125]
	v_mfma_f32_16x16x32_bf16 v[110:113], v[144:147], v[190:193], v[110:113]
	v_mfma_f32_16x16x32_bf16 v[106:109], v[152:155], v[190:193], v[106:109]
	v_mfma_f32_16x16x32_bf16 v[94:97], v[144:147], v[198:201], v[94:97]
	v_mfma_f32_16x16x32_bf16 v[90:93], v[152:155], v[198:201], v[90:93]
	v_mfma_f32_16x16x32_bf16 v[78:81], v[144:147], v[206:209], v[78:81]
	v_mfma_f32_16x16x32_bf16 v[74:77], v[152:155], v[206:209], v[74:77]
	s_setprio 0
	s_setprio 1
	v_mfma_f32_16x16x32_bf16 v[118:121], v[156:159], v[172:175], v[118:121]
	v_mfma_f32_16x16x32_bf16 v[114:117], v[164:167], v[172:175], v[114:117]
	v_mfma_f32_16x16x32_bf16 v[102:105], v[156:159], v[182:185], v[102:105]
	v_mfma_f32_16x16x32_bf16 v[98:101], v[164:167], v[182:185], v[98:101]
	v_mfma_f32_16x16x32_bf16 v[86:89], v[156:159], v[194:197], v[86:89]
	v_mfma_f32_16x16x32_bf16 v[82:85], v[164:167], v[194:197], v[82:85]
	v_mfma_f32_16x16x32_bf16 v[70:73], v[156:159], v[202:205], v[70:73]
	v_mfma_f32_16x16x32_bf16 v[66:69], v[164:167], v[202:205], v[66:69]
	v_mfma_f32_16x16x32_bf16 v[118:121], v[160:163], v[176:179], v[118:121]
	v_mfma_f32_16x16x32_bf16 v[114:117], v[168:171], v[176:179], v[114:117]
	v_mfma_f32_16x16x32_bf16 v[102:105], v[160:163], v[190:193], v[102:105]
	v_mfma_f32_16x16x32_bf16 v[98:101], v[168:171], v[190:193], v[98:101]
	v_mfma_f32_16x16x32_bf16 v[86:89], v[160:163], v[198:201], v[86:89]
	v_mfma_f32_16x16x32_bf16 v[82:85], v[168:171], v[198:201], v[82:85]
	v_mfma_f32_16x16x32_bf16 v[70:73], v[160:163], v[206:209], v[70:73]
	v_mfma_f32_16x16x32_bf16 v[66:69], v[168:171], v[206:209], v[66:69]
	s_setprio 0
	s_barrier
	s_add_i32 s42, s44, s92
	v_lshl_add_u64 v[186:187], v[186:187], 0, s[62:63]
	s_mov_b32 m0, s42
	ds_read_b128 v[172:175], v139 offset:49152
	ds_read_b128 v[176:179], v139 offset:50176
	ds_read_b128 v[182:185], v139 offset:51200
	ds_read_b128 v[190:193], v139 offset:52224
	ds_read_b128 v[194:197], v139 offset:53248
	ds_read_b128 v[198:201], v139 offset:54272
	ds_read_b128 v[202:205], v139 offset:55296
	ds_read_b128 v[206:209], v139 offset:56320
	global_load_lds_dwordx4 v[186:187], off
	s_add_i32 m0, s42, 0x2000
	s_add_u32 s42, s74, 0x500080
	v_lshl_add_u64 v[186:187], v[210:211], 0, s[62:63]
	s_addc_u32 s43, s75, 0
	s_add_i32 s44, s45, s92
	global_load_lds_dwordx4 v[186:187], off
	v_lshl_add_u64 v[186:187], s[42:43], 0, v[0:1]
	s_mov_b32 m0, s44
	s_nop 0
	global_load_lds_dwordx4 v[186:187], off
	v_lshl_add_u64 v[186:187], s[42:43], 0, v[130:131]
	s_add_i32 m0, s44, 0x2000
	s_nop 0
	global_load_lds_dwordx4 v[186:187], off
	v_lshl_add_u64 v[186:187], v[212:213], 0, s[62:63]
	s_mov_b32 m0, s7
	s_nop 0
	global_load_lds_dwordx4 v[186:187], off
	v_lshl_add_u64 v[186:187], v[214:215], 0, s[62:63]
	s_mov_b32 m0, s8
	s_nop 0
	global_load_lds_dwordx4 v[186:187], off
	s_waitcnt vmcnt(8)
	s_waitcnt lgkmcnt(0)
	s_barrier
	s_setprio 1
	v_mfma_f32_16x16x32_bf16 v[62:65], v[140:143], v[172:175], v[62:65]
	v_mfma_f32_16x16x32_bf16 v[58:61], v[148:151], v[172:175], v[58:61]
	v_mfma_f32_16x16x32_bf16 v[46:49], v[140:143], v[182:185], v[46:49]
	v_mfma_f32_16x16x32_bf16 v[42:45], v[148:151], v[182:185], v[42:45]
	v_mfma_f32_16x16x32_bf16 v[30:33], v[140:143], v[194:197], v[30:33]
	v_mfma_f32_16x16x32_bf16 v[26:29], v[148:151], v[194:197], v[26:29]
	v_mfma_f32_16x16x32_bf16 v[14:17], v[140:143], v[202:205], v[14:17]
	v_mfma_f32_16x16x32_bf16 v[10:13], v[148:151], v[202:205], v[10:13]
	v_mfma_f32_16x16x32_bf16 v[62:65], v[144:147], v[176:179], v[62:65]
	v_mfma_f32_16x16x32_bf16 v[58:61], v[152:155], v[176:179], v[58:61]
	v_mfma_f32_16x16x32_bf16 v[46:49], v[144:147], v[190:193], v[46:49]
	v_mfma_f32_16x16x32_bf16 v[42:45], v[152:155], v[190:193], v[42:45]
	v_mfma_f32_16x16x32_bf16 v[30:33], v[144:147], v[198:201], v[30:33]
	v_mfma_f32_16x16x32_bf16 v[26:29], v[152:155], v[198:201], v[26:29]
	v_mfma_f32_16x16x32_bf16 v[14:17], v[144:147], v[206:209], v[14:17]
	v_mfma_f32_16x16x32_bf16 v[10:13], v[152:155], v[206:209], v[10:13]
	s_setprio 0
	s_setprio 1
	v_mfma_f32_16x16x32_bf16 v[54:57], v[156:159], v[172:175], v[54:57]
	v_mfma_f32_16x16x32_bf16 v[50:53], v[164:167], v[172:175], v[50:53]
	v_mfma_f32_16x16x32_bf16 v[38:41], v[156:159], v[182:185], v[38:41]
	v_mfma_f32_16x16x32_bf16 v[34:37], v[164:167], v[182:185], v[34:37]
	v_mfma_f32_16x16x32_bf16 v[22:25], v[156:159], v[194:197], v[22:25]
	v_mfma_f32_16x16x32_bf16 v[18:21], v[164:167], v[194:197], v[18:21]
	v_mfma_f32_16x16x32_bf16 v[6:9], v[156:159], v[202:205], v[6:9]
	v_mfma_f32_16x16x32_bf16 v[2:5], v[164:167], v[202:205], v[2:5]
	v_mfma_f32_16x16x32_bf16 v[54:57], v[160:163], v[176:179], v[54:57]
	v_mfma_f32_16x16x32_bf16 v[50:53], v[168:171], v[176:179], v[50:53]
	v_mfma_f32_16x16x32_bf16 v[38:41], v[160:163], v[190:193], v[38:41]
	v_mfma_f32_16x16x32_bf16 v[34:37], v[168:171], v[190:193], v[34:37]
	v_mfma_f32_16x16x32_bf16 v[22:25], v[160:163], v[198:201], v[22:25]
	v_mfma_f32_16x16x32_bf16 v[18:21], v[168:171], v[198:201], v[18:21]
	v_mfma_f32_16x16x32_bf16 v[6:9], v[160:163], v[206:209], v[6:9]
	v_mfma_f32_16x16x32_bf16 v[2:5], v[168:171], v[206:209], v[2:5]
	s_setprio 0
	s_barrier
	s_add_i32 s86, s86, 2
	s_add_u32 s72, s72, 0x100
	s_addc_u32 s73, s73, 0
	s_cmp_ge_i32 s86, s97
	s_cbranch_scc0 .LBB0_1323

.LBB0_1351:
	s_andn2_b64 vcc, exec, s[36:37]
	s_cbranch_vccnz .LBB0_1353
	ds_read_b128 v[2:5], v217
	ds_read_b128 v[6:9], v201
	ds_read_b128 v[14:17], v201 offset:8448
	ds_read_b128 v[18:21], v217 offset:64
	ds_read_b128 v[26:29], v201 offset:64
	ds_read_b128 v[30:33], v201 offset:8512
	s_add_u32 s36, s8, s2
	s_addc_u32 s37, s9, s3
	s_nop 0
	v_lshl_add_u64 v[226:227], v[184:185], 0, s[36:37]
	v_add_co_u32_e32 v228, vcc, 0x280000, v226
	s_nop 1
	v_addc_co_u32_e32 v229, vcc, 0, v227, vcc
	global_load_dwordx4 v[10:13], v[226:227], off
	global_load_dwordx4 v[22:25], v[228:229], off
	v_add_co_u32_e32 v228, vcc, 0x500000, v226
	s_nop 1
	v_addc_co_u32_e32 v229, vcc, 0, v227, vcc
	v_add_co_u32_e32 v230, vcc, 0x780000, v226
	s_nop 1
	v_addc_co_u32_e32 v231, vcc, 0, v227, vcc
	global_load_dwordx4 v[34:37], v[228:229], off
	global_load_dwordx4 v[46:49], v[230:231], off
	v_add_co_u32_e32 v228, vcc, s85, v226
	s_nop 1
	v_addc_co_u32_e32 v229, vcc, 0, v227, vcc
	v_add_co_u32_e32 v230, vcc, 0xc80000, v226
	s_nop 1
	v_addc_co_u32_e32 v231, vcc, 0, v227, vcc
	global_load_dwordx4 v[58:61], v[228:229], off
	global_load_dwordx4 v[62:65], v[230:231], off
	v_add_co_u32_e32 v228, vcc, 0xf00000, v226
	s_nop 1
	v_addc_co_u32_e32 v229, vcc, 0, v227, vcc
	v_add_co_u32_e32 v226, vcc, 0x1180000, v226
	s_nop 1
	v_addc_co_u32_e32 v227, vcc, 0, v227, vcc
	global_load_dwordx4 v[66:69], v[228:229], off
	global_load_dwordx4 v[70:73], v[226:227], off
	s_mov_b64 s[36:37], 0
	s_mov_b64 s[54:55], -1
	s_branch .Lret_qk_rest

.Lret_qk_rest:
	s_cmp_lt_i32 s30, s70
	s_cselect_b64 vcc, -1, 0
	v_cndmask_b32_e64 v232, -v193, v192, vcc
	v_cndmask_b32_e32 v233, v189, v221, vcc
	v_cndmask_b32_e32 v234, v179, v181, vcc
	v_cndmask_b32_e32 v235, v199, v200, vcc
	v_add_u32_e32 v236, -13, v216
	v_cvt_f32_i32_e32 v236, v236
	v_add_u32_e32 v237, 3, v216
	v_cvt_f32_i32_e32 v237, v237
	v_mul_f32_e32 v236, v232, v236
	v_mul_f32_e32 v237, v232, v237
	v_exp_f32_e32 v238, v236
	v_exp_f32_e32 v242, v237
	v_mul_f32_e32 v239, v233, v238
	v_mul_f32_e32 v240, v234, v238
	v_mul_f32_e32 v241, v235, v238
	v_mul_f32_e32 v243, v233, v242
	v_mul_f32_e32 v244, v234, v242
	v_mul_f32_e32 v245, v235, v242
	s_waitcnt lgkmcnt(0)
	v_mfma_f32_16x16x32_bf16 v[6:9], v[2:5], v[6:9], 0
	v_mfma_f32_16x16x32_bf16 v[2:5], v[2:5], v[14:17], 0
	v_mfma_f32_16x16x32_bf16 v[6:9], v[18:21], v[26:29], v[6:9]
	ds_read_b128 v[14:17], v217 offset:128
	ds_read_b128 v[26:29], v201 offset:128
	ds_read_b128 v[38:41], v201 offset:8576
	v_mfma_f32_16x16x32_bf16 v[2:5], v[18:21], v[30:33], v[2:5]
	s_waitcnt lgkmcnt(1)
	v_mfma_f32_16x16x32_bf16 v[6:9], v[14:17], v[26:29], v[6:9]
	ds_read_b128 v[18:21], v217 offset:192
	ds_read_b128 v[26:29], v201 offset:192
	ds_read_b128 v[30:33], v201 offset:8640
	s_waitcnt lgkmcnt(3)
	v_mfma_f32_16x16x32_bf16 v[2:5], v[14:17], v[38:41], v[2:5]
	s_waitcnt lgkmcnt(1)
	v_mfma_f32_16x16x32_bf16 v[6:9], v[18:21], v[26:29], v[6:9]
	ds_read_b128 v[14:17], v217 offset:256
	ds_read_b128 v[26:29], v201 offset:256
	ds_read_b128 v[38:41], v201 offset:8704
	s_waitcnt lgkmcnt(3)
	v_mfma_f32_16x16x32_bf16 v[2:5], v[18:21], v[30:33], v[2:5]
	s_waitcnt lgkmcnt(1)
	v_mfma_f32_16x16x32_bf16 v[6:9], v[14:17], v[26:29], v[6:9]
	ds_read_b128 v[18:21], v217 offset:320
	ds_read_b128 v[26:29], v201 offset:320
	ds_read_b128 v[30:33], v201 offset:8768
	s_waitcnt lgkmcnt(3)
	v_mfma_f32_16x16x32_bf16 v[2:5], v[14:17], v[38:41], v[2:5]
	s_waitcnt lgkmcnt(1)
	v_mfma_f32_16x16x32_bf16 v[6:9], v[18:21], v[26:29], v[6:9]
	ds_read_b128 v[14:17], v217 offset:384
	ds_read_b128 v[26:29], v201 offset:384
	ds_read_b128 v[38:41], v201 offset:8832
	s_waitcnt lgkmcnt(3)
	v_mfma_f32_16x16x32_bf16 v[2:5], v[18:21], v[30:33], v[2:5]
	s_waitcnt lgkmcnt(1)
	v_mfma_f32_16x16x32_bf16 v[6:9], v[14:17], v[26:29], v[6:9]
	ds_read_b128 v[18:21], v217 offset:448
	ds_read_b128 v[26:29], v201 offset:448
	ds_read_b128 v[30:33], v201 offset:8896
	s_waitcnt lgkmcnt(3)
	v_mfma_f32_16x16x32_bf16 v[2:5], v[14:17], v[38:41], v[2:5]
	s_waitcnt lgkmcnt(1)
	v_mfma_f32_16x16x32_bf16 v[6:9], v[18:21], v[26:29], v[6:9]
	s_waitcnt lgkmcnt(0)
	v_mfma_f32_16x16x32_bf16 v[2:5], v[18:21], v[30:33], v[2:5]
	s_cmp_lg_u32 s70, s30
	s_cselect_b64 s[54:55], -1, 0
	s_nop 1
	v_add_u32_e32 v20, -13, v216
	s_mov_b64 s[66:67], -1
	s_and_b64 vcc, exec, s[54:55]
	s_cbranch_vccz .LBB0_1360
	s_mov_b64 s[66:67], 0
	v_mul_f32_e32 v21, v240, v8
	v_pk_mul_f32 v[14:15], v[238:239], v[6:7]
	v_mul_f32_e32 v26, v241, v9

.LBB0_1378:
	v_cvt_pk_bf16_f32 v6, v14, v15
	v_cvt_pk_bf16_f32 v7, v21, v26
	v_add_u32_e32 v8, 3, v216
	s_andn2_b64 vcc, exec, s[54:55]
	s_mov_b64 s[54:55], -1
	ds_write_b64 v219, v[6:7]
	s_cbranch_vccnz .LBB0_1380
	s_mov_b64 s[54:55], 0
	v_pk_mul_f32 v[6:7], v[242:243], v[2:3]
	v_mul_f32_e32 v9, v244, v4
	v_mul_f32_e32 v14, v245, v5

.Lcoldzero_d2:
	v_mov_b32_e32 v161, 0
	v_mov_b32_e32 v160, 0
	v_mov_b32_e32 v163, 0
	v_mov_b32_e32 v162, 0
	v_mov_b32_e32 v159, 0
	v_mov_b32_e32 v158, 0
	v_mov_b32_e32 v157, 0
	v_mov_b32_e32 v156, 0
	v_mov_b32_e32 v139, 0
	v_mov_b32_e32 v138, 0
	v_mov_b32_e32 v141, 0
	v_mov_b32_e32 v140, 0
	v_mov_b32_e32 v143, 0
	v_mov_b32_e32 v142, 0
	v_mov_b32_e32 v145, 0
	v_mov_b32_e32 v144, 0
	v_mov_b32_e32 v121, 0
	v_mov_b32_e32 v120, 0
	v_mov_b32_e32 v119, 0
	v_mov_b32_e32 v118, 0
	v_mov_b32_e32 v115, 0
	v_mov_b32_e32 v114, 0
	v_mov_b32_e32 v113, 0
	v_mov_b32_e32 v112, 0
	v_mov_b32_e32 v97, 0
	v_mov_b32_e32 v96, 0
	v_mov_b32_e32 v99, 0
	v_mov_b32_e32 v98, 0
	v_mov_b32_e32 v101, 0
	v_mov_b32_e32 v100, 0
	v_mov_b32_e32 v103, 0
	v_mov_b32_e32 v102, 0
	v_mov_b32_e32 v171, 0
	v_mov_b32_e32 v170, 0
	v_mov_b32_e32 v169, 0
	v_mov_b32_e32 v168, 0
	v_mov_b32_e32 v167, 0
	v_mov_b32_e32 v166, 0
	v_mov_b32_e32 v165, 0
	v_mov_b32_e32 v164, 0
	v_mov_b32_e32 v147, 0
	v_mov_b32_e32 v146, 0
	v_mov_b32_e32 v149, 0
	v_mov_b32_e32 v148, 0
	v_mov_b32_e32 v151, 0
	v_mov_b32_e32 v150, 0
	v_mov_b32_e32 v153, 0
	v_mov_b32_e32 v152, 0
	v_mov_b32_e32 v137, 0
	v_mov_b32_e32 v136, 0
	v_mov_b32_e32 v127, 0
	v_mov_b32_e32 v126, 0
	v_mov_b32_e32 v125, 0
	v_mov_b32_e32 v124, 0
	v_mov_b32_e32 v123, 0
	v_mov_b32_e32 v122, 0
	v_mov_b32_e32 v105, 0
	v_mov_b32_e32 v104, 0
	v_mov_b32_e32 v107, 0
	v_mov_b32_e32 v106, 0
	v_mov_b32_e32 v109, 0
	v_mov_b32_e32 v108, 0
	v_mov_b32_e32 v111, 0
	v_mov_b32_e32 v110, 0
	v_mov_b32_e32 v87, 0
	v_mov_b32_e32 v86, 0
	v_mov_b32_e32 v85, 0
	v_mov_b32_e32 v84, 0
	v_mov_b32_e32 v83, 0
	v_mov_b32_e32 v82, 0
	v_mov_b32_e32 v81, 0
	v_mov_b32_e32 v80, 0
	v_mov_b32_e32 v65, 0
	v_mov_b32_e32 v64, 0
	v_mov_b32_e32 v67, 0
	v_mov_b32_e32 v66, 0
	v_mov_b32_e32 v69, 0
	v_mov_b32_e32 v68, 0
	v_mov_b32_e32 v71, 0
	v_mov_b32_e32 v70, 0
	v_mov_b32_e32 v55, 0
	v_mov_b32_e32 v54, 0
	v_mov_b32_e32 v53, 0
	v_mov_b32_e32 v52, 0
	v_mov_b32_e32 v51, 0
	v_mov_b32_e32 v50, 0
	v_mov_b32_e32 v49, 0
	v_mov_b32_e32 v48, 0
	v_mov_b32_e32 v33, 0
	v_mov_b32_e32 v32, 0
	v_mov_b32_e32 v35, 0
	v_mov_b32_e32 v34, 0
	v_mov_b32_e32 v37, 0
	v_mov_b32_e32 v36, 0
	v_mov_b32_e32 v39, 0
	v_mov_b32_e32 v38, 0
	v_mov_b32_e32 v95, 0
	v_mov_b32_e32 v94, 0
	v_mov_b32_e32 v93, 0
	v_mov_b32_e32 v92, 0
	v_mov_b32_e32 v91, 0
	v_mov_b32_e32 v90, 0
	v_mov_b32_e32 v89, 0
	v_mov_b32_e32 v88, 0
	v_mov_b32_e32 v73, 0
	v_mov_b32_e32 v72, 0
	v_mov_b32_e32 v75, 0
	v_mov_b32_e32 v74, 0
	v_mov_b32_e32 v77, 0
	v_mov_b32_e32 v76, 0
	v_mov_b32_e32 v79, 0
	v_mov_b32_e32 v78, 0
	v_mov_b32_e32 v63, 0
	v_mov_b32_e32 v62, 0
	v_mov_b32_e32 v61, 0
	v_mov_b32_e32 v60, 0
	v_mov_b32_e32 v59, 0
	v_mov_b32_e32 v58, 0
	v_mov_b32_e32 v57, 0
	v_mov_b32_e32 v56, 0
	v_mov_b32_e32 v41, 0
	v_mov_b32_e32 v40, 0
	v_mov_b32_e32 v43, 0
	v_mov_b32_e32 v42, 0
	v_mov_b32_e32 v45, 0
	v_mov_b32_e32 v44, 0
	v_mov_b32_e32 v47, 0
	v_mov_b32_e32 v46, 0
	s_branch .LBB0_1481

.LBB0_1477:
	s_add_u32 s6, s26, s34
	s_addc_u32 s7, s27, s35
	s_and_b64 s[4:5], s[10:11], exec
	v_readlane_b32 s4, v255, 0
	s_cselect_b32 s53, s7, s37
	s_cselect_b32 s52, s6, s36
	v_readlane_b32 s5, v255, 1
	s_add_u32 s6, s4, s78
	s_addc_u32 s7, s5, s79
	s_and_b64 s[4:5], s[10:11], exec
	s_cselect_b32 s57, s7, s55
	s_cselect_b32 s56, s6, s54
	s_and_b64 vcc, exec, s[2:3]
	s_cbranch_vccnz .Lcoldzero_d2
	v_mov_b64_e32 v[0:1], 0
	s_mov_b32 s4, 0
	s_mov_b64 s[58:59], 0
	v_mov_b64_e32 v[2:3], 0
	v_mov_b64_e32 v[4:5], 0
	v_mov_b64_e32 v[6:7], 0
	v_mov_b64_e32 v[8:9], 0
	v_mov_b64_e32 v[10:11], 0
	v_mov_b64_e32 v[12:13], 0
	v_mov_b64_e32 v[14:15], 0
	v_mov_b64_e32 v[16:17], 0
	v_mov_b64_e32 v[18:19], 0
	v_mov_b64_e32 v[20:21], 0
	v_mov_b64_e32 v[22:23], 0
	v_mov_b64_e32 v[24:25], 0
	v_mov_b64_e32 v[26:27], 0
	v_mov_b64_e32 v[28:29], 0
	v_mov_b64_e32 v[30:31], 0
	v_mov_b64_e32 v[32:33], 0
	v_mov_b64_e32 v[34:35], 0
	v_mov_b64_e32 v[36:37], 0
	v_mov_b64_e32 v[38:39], 0
	v_mov_b64_e32 v[40:41], 0
	v_mov_b64_e32 v[42:43], 0
	v_mov_b64_e32 v[44:45], 0
	v_mov_b64_e32 v[46:47], 0
	v_mov_b64_e32 v[48:49], 0
	v_mov_b64_e32 v[50:51], 0
	v_mov_b64_e32 v[52:53], 0
	v_mov_b64_e32 v[54:55], 0
	v_mov_b64_e32 v[56:57], 0
	v_mov_b64_e32 v[58:59], 0
	v_mov_b64_e32 v[60:61], 0
	v_mov_b64_e32 v[62:63], 0
	v_mov_b64_e32 v[64:65], 0
	v_mov_b64_e32 v[66:67], 0
	v_mov_b64_e32 v[68:69], 0
	v_mov_b64_e32 v[70:71], 0
	v_mov_b64_e32 v[72:73], 0
	v_mov_b64_e32 v[74:75], 0
	v_mov_b64_e32 v[76:77], 0
	v_mov_b64_e32 v[78:79], 0
	v_mov_b64_e32 v[80:81], 0
	v_mov_b64_e32 v[82:83], 0
	v_mov_b64_e32 v[84:85], 0
	v_mov_b64_e32 v[86:87], 0
	v_mov_b64_e32 v[88:89], 0
	v_mov_b64_e32 v[90:91], 0
	v_mov_b64_e32 v[92:93], 0
	v_mov_b64_e32 v[94:95], 0
	v_mov_b64_e32 v[96:97], 0
	v_mov_b64_e32 v[98:99], 0
	v_mov_b64_e32 v[100:101], 0
	v_mov_b64_e32 v[102:103], 0
	v_mov_b64_e32 v[104:105], 0
	v_mov_b64_e32 v[106:107], 0
	v_mov_b64_e32 v[108:109], 0
	v_mov_b64_e32 v[110:111], 0
	v_mov_b64_e32 v[112:113], 0
	v_mov_b64_e32 v[114:115], 0
	v_mov_b64_e32 v[116:117], 0
	v_mov_b64_e32 v[118:119], 0
	v_mov_b64_e32 v[120:121], 0
	v_mov_b64_e32 v[122:123], 0
	v_mov_b64_e32 v[124:125], 0
	v_mov_b64_e32 v[126:127], 0
.LBB0_1479:
	s_mov_b64 s[6:7], s[58:59]
	ds_read_b128 v[136:139], v183
	ds_read_b128 v[140:143], v183 offset:1024
	ds_read_b128 v[144:147], v183 offset:2048
	ds_read_b128 v[148:151], v183 offset:3072
	ds_read_b128 v[152:155], v184
	ds_read_b128 v[156:159], v184 offset:1024
	ds_read_b128 v[160:163], v184 offset:2048
	ds_read_b128 v[164:167], v184 offset:3072
	s_add_u32 s5, s36, s6
	s_addc_u32 s8, s37, s7
	s_add_u32 s9, s5, 0x100
	s_addc_u32 s17, s8, 0
	s_add_u32 s6, s54, s6
	s_addc_u32 s7, s55, s7
	s_add_u32 s6, s6, 0x100
	s_addc_u32 s7, s7, 0
	s_cmp_eq_u32 s72, s4
	s_cselect_b32 s63, s53, s17
	s_cselect_b32 s62, s52, s9
	s_cselect_b32 s61, s57, s7
	s_cselect_b32 s60, s56, s6
	s_add_u32 s6, s5, 0x100080
	s_addc_u32 s7, s8, 0
	v_lshl_add_u64 v[176:177], s[6:7], 0, v[128:129]
	s_add_i32 m0, s31, 0xc000
	ds_read_b128 v[168:171], v185
	ds_read_b128 v[172:175], v185 offset:1024
	ds_read_b128 v[186:189], v185 offset:2048
	ds_read_b128 v[190:193], v185 offset:3072
	ds_read_b128 v[194:197], v185 offset:4096
	ds_read_b128 v[198:201], v185 offset:5120
	ds_read_b128 v[202:205], v185 offset:6144
	ds_read_b128 v[206:209], v185 offset:7168
	global_load_lds_dwordx4 v[176:177], off
	v_lshl_add_u64 v[176:177], s[6:7], 0, v[130:131]
	s_add_i32 m0, s31, 0xe000
	s_nop 0
	global_load_lds_dwordx4 v[176:177], off
	s_waitcnt vmcnt(8)
	s_waitcnt lgkmcnt(0)
	s_barrier
	s_setprio 1
	v_mfma_f32_16x16x32_bf16 v[124:127], v[136:139], v[168:171], v[124:127]
	v_mfma_f32_16x16x32_bf16 v[120:123], v[144:147], v[168:171], v[120:123]
	v_mfma_f32_16x16x32_bf16 v[116:119], v[136:139], v[186:189], v[116:119]
	v_mfma_f32_16x16x32_bf16 v[112:115], v[144:147], v[186:189], v[112:115]
	v_mfma_f32_16x16x32_bf16 v[104:107], v[136:139], v[194:197], v[104:107]
	v_mfma_f32_16x16x32_bf16 v[96:99], v[144:147], v[194:197], v[96:99]
	v_mfma_f32_16x16x32_bf16 v[88:91], v[136:139], v[202:205], v[88:91]
	v_mfma_f32_16x16x32_bf16 v[80:83], v[144:147], v[202:205], v[80:83]
	v_mfma_f32_16x16x32_bf16 v[124:127], v[140:143], v[172:175], v[124:127]
	v_mfma_f32_16x16x32_bf16 v[120:123], v[148:151], v[172:175], v[120:123]
	v_mfma_f32_16x16x32_bf16 v[116:119], v[140:143], v[190:193], v[116:119]
	v_mfma_f32_16x16x32_bf16 v[112:115], v[148:151], v[190:193], v[112:115]
	v_mfma_f32_16x16x32_bf16 v[104:107], v[140:143], v[198:201], v[104:107]
	v_mfma_f32_16x16x32_bf16 v[96:99], v[148:151], v[198:201], v[96:99]
	v_mfma_f32_16x16x32_bf16 v[88:91], v[140:143], v[206:209], v[88:91]
	v_mfma_f32_16x16x32_bf16 v[80:83], v[148:151], v[206:209], v[80:83]
	s_setprio 0
	s_setprio 1
	v_mfma_f32_16x16x32_bf16 v[108:111], v[152:155], v[168:171], v[108:111]
	v_mfma_f32_16x16x32_bf16 v[100:103], v[160:163], v[168:171], v[100:103]
	v_mfma_f32_16x16x32_bf16 v[92:95], v[152:155], v[186:189], v[92:95]
	v_mfma_f32_16x16x32_bf16 v[84:87], v[160:163], v[186:189], v[84:87]
	v_mfma_f32_16x16x32_bf16 v[76:79], v[152:155], v[194:197], v[76:79]
	v_mfma_f32_16x16x32_bf16 v[72:75], v[160:163], v[194:197], v[72:75]
	v_mfma_f32_16x16x32_bf16 v[68:71], v[152:155], v[202:205], v[68:71]
	v_mfma_f32_16x16x32_bf16 v[64:67], v[160:163], v[202:205], v[64:67]
	v_mfma_f32_16x16x32_bf16 v[108:111], v[156:159], v[172:175], v[108:111]
	v_mfma_f32_16x16x32_bf16 v[100:103], v[164:167], v[172:175], v[100:103]
	v_mfma_f32_16x16x32_bf16 v[92:95], v[156:159], v[190:193], v[92:95]
	v_mfma_f32_16x16x32_bf16 v[84:87], v[164:167], v[190:193], v[84:87]
	v_mfma_f32_16x16x32_bf16 v[76:79], v[156:159], v[198:201], v[76:79]
	v_mfma_f32_16x16x32_bf16 v[72:75], v[164:167], v[198:201], v[72:75]
	v_mfma_f32_16x16x32_bf16 v[68:71], v[156:159], v[206:209], v[68:71]
	v_mfma_f32_16x16x32_bf16 v[64:67], v[164:167], v[206:209], v[64:67]
	s_setprio 0
	s_barrier
	s_add_i32 s5, s73, s30
	v_lshl_add_u64 v[176:177], s[60:61], 0, v[128:129]
	s_mov_b32 m0, s5
	ds_read_b128 v[168:171], v185 offset:16384
	ds_read_b128 v[172:175], v185 offset:17408
	ds_read_b128 v[186:189], v185 offset:18432
	ds_read_b128 v[190:193], v185 offset:19456
	ds_read_b128 v[194:197], v185 offset:20480
	ds_read_b128 v[198:201], v185 offset:21504
	ds_read_b128 v[202:205], v185 offset:22528
	ds_read_b128 v[206:209], v185 offset:23552
	global_load_lds_dwordx4 v[176:177], off
	s_add_i32 m0, s5, 0x2000
	s_add_u32 s6, s60, 0x100000
	v_lshl_add_u64 v[210:211], s[60:61], 0, v[130:131]
	s_addc_u32 s7, s61, 0
	s_add_i32 s5, s74, s30
	global_load_lds_dwordx4 v[210:211], off
	v_lshl_add_u64 v[212:213], s[6:7], 0, v[128:129]
	s_mov_b32 m0, s5
	v_lshl_add_u64 v[214:215], s[62:63], 0, v[130:131]
	global_load_lds_dwordx4 v[212:213], off
	v_lshl_add_u64 v[212:213], s[6:7], 0, v[130:131]
	s_add_i32 m0, s5, 0x2000
	s_nop 0
	global_load_lds_dwordx4 v[212:213], off
	v_lshl_add_u64 v[212:213], s[62:63], 0, v[128:129]
	s_mov_b32 m0, s31
	s_nop 0
	global_load_lds_dwordx4 v[212:213], off
	s_mov_b32 m0, s64
	s_nop 0
	global_load_lds_dwordx4 v[214:215], off
	s_waitcnt vmcnt(8)
	s_waitcnt lgkmcnt(0)
	s_barrier
	s_setprio 1
	v_mfma_f32_16x16x32_bf16 v[60:63], v[136:139], v[168:171], v[60:63]
	v_mfma_f32_16x16x32_bf16 v[56:59], v[144:147], v[168:171], v[56:59]
	v_mfma_f32_16x16x32_bf16 v[52:55], v[136:139], v[186:189], v[52:55]
	v_mfma_f32_16x16x32_bf16 v[48:51], v[144:147], v[186:189], v[48:51]
	v_mfma_f32_16x16x32_bf16 v[40:43], v[136:139], v[194:197], v[40:43]
	v_mfma_f32_16x16x32_bf16 v[32:35], v[144:147], v[194:197], v[32:35]
	v_mfma_f32_16x16x32_bf16 v[24:27], v[136:139], v[202:205], v[24:27]
	v_mfma_f32_16x16x32_bf16 v[16:19], v[144:147], v[202:205], v[16:19]
	v_mfma_f32_16x16x32_bf16 v[60:63], v[140:143], v[172:175], v[60:63]
	v_mfma_f32_16x16x32_bf16 v[56:59], v[148:151], v[172:175], v[56:59]
	v_mfma_f32_16x16x32_bf16 v[52:55], v[140:143], v[190:193], v[52:55]
	v_mfma_f32_16x16x32_bf16 v[48:51], v[148:151], v[190:193], v[48:51]
	v_mfma_f32_16x16x32_bf16 v[40:43], v[140:143], v[198:201], v[40:43]
	v_mfma_f32_16x16x32_bf16 v[32:35], v[148:151], v[198:201], v[32:35]
	v_mfma_f32_16x16x32_bf16 v[24:27], v[140:143], v[206:209], v[24:27]
	v_mfma_f32_16x16x32_bf16 v[16:19], v[148:151], v[206:209], v[16:19]
	s_setprio 0
	s_setprio 1
	v_mfma_f32_16x16x32_bf16 v[44:47], v[152:155], v[168:171], v[44:47]
	v_mfma_f32_16x16x32_bf16 v[36:39], v[160:163], v[168:171], v[36:39]
	v_mfma_f32_16x16x32_bf16 v[28:31], v[152:155], v[186:189], v[28:31]
	v_mfma_f32_16x16x32_bf16 v[20:23], v[160:163], v[186:189], v[20:23]
	v_mfma_f32_16x16x32_bf16 v[12:15], v[152:155], v[194:197], v[12:15]
	v_mfma_f32_16x16x32_bf16 v[8:11], v[160:163], v[194:197], v[8:11]
	v_mfma_f32_16x16x32_bf16 v[4:7], v[152:155], v[202:205], v[4:7]
	v_mfma_f32_16x16x32_bf16 v[0:3], v[160:163], v[202:205], v[0:3]
	v_mfma_f32_16x16x32_bf16 v[44:47], v[156:159], v[172:175], v[44:47]
	v_mfma_f32_16x16x32_bf16 v[36:39], v[164:167], v[172:175], v[36:39]
	v_mfma_f32_16x16x32_bf16 v[28:31], v[156:159], v[190:193], v[28:31]
	v_mfma_f32_16x16x32_bf16 v[20:23], v[164:167], v[190:193], v[20:23]
	v_mfma_f32_16x16x32_bf16 v[12:15], v[156:159], v[198:201], v[12:15]
	v_mfma_f32_16x16x32_bf16 v[8:11], v[164:167], v[198:201], v[8:11]
	v_mfma_f32_16x16x32_bf16 v[4:7], v[156:159], v[206:209], v[4:7]
	v_mfma_f32_16x16x32_bf16 v[0:3], v[164:167], v[206:209], v[0:3]
	s_setprio 0
	s_barrier
	s_add_i32 s5, 0, 0x18000
	v_add_u32_e32 v132, s5, v182
	s_add_i32 s8, 0, 0x1c000
	ds_read_b128 v[136:139], v132
	ds_read_b128 v[140:143], v132 offset:1024
	ds_read_b128 v[144:147], v132 offset:2048
	ds_read_b128 v[148:151], v132 offset:3072
	v_add_u32_e32 v132, s8, v182
	ds_read_b128 v[152:155], v132
	ds_read_b128 v[156:159], v132 offset:1024
	ds_read_b128 v[160:163], v132 offset:2048
	ds_read_b128 v[164:167], v132 offset:3072
	s_add_u32 s6, s62, 0x100000
	s_addc_u32 s7, s63, 0
	s_mov_b32 m0, s65
	v_lshl_add_u64 v[216:217], s[6:7], 0, v[128:129]
	ds_read_b128 v[168:171], v185 offset:32768
	ds_read_b128 v[172:175], v185 offset:33792
	ds_read_b128 v[186:189], v185 offset:34816
	ds_read_b128 v[190:193], v185 offset:35840
	ds_read_b128 v[194:197], v185 offset:36864
	ds_read_b128 v[198:201], v185 offset:37888
	ds_read_b128 v[202:205], v185 offset:38912
	ds_read_b128 v[206:209], v185 offset:39936
	global_load_lds_dwordx4 v[216:217], off
	v_lshl_add_u64 v[216:217], s[6:7], 0, v[130:131]
	s_mov_b32 m0, s66
	s_nop 0
	global_load_lds_dwordx4 v[216:217], off
	s_waitcnt vmcnt(8)
	s_waitcnt lgkmcnt(0)
	s_barrier
	s_setprio 1
	v_mfma_f32_16x16x32_bf16 v[124:127], v[136:139], v[168:171], v[124:127]
	v_mfma_f32_16x16x32_bf16 v[120:123], v[144:147], v[168:171], v[120:123]
	v_mfma_f32_16x16x32_bf16 v[116:119], v[136:139], v[186:189], v[116:119]
	v_mfma_f32_16x16x32_bf16 v[112:115], v[144:147], v[186:189], v[112:115]
	v_mfma_f32_16x16x32_bf16 v[104:107], v[136:139], v[194:197], v[104:107]
	v_mfma_f32_16x16x32_bf16 v[96:99], v[144:147], v[194:197], v[96:99]
	v_mfma_f32_16x16x32_bf16 v[88:91], v[136:139], v[202:205], v[88:91]
	v_mfma_f32_16x16x32_bf16 v[80:83], v[144:147], v[202:205], v[80:83]
	v_mfma_f32_16x16x32_bf16 v[124:127], v[140:143], v[172:175], v[124:127]
	v_mfma_f32_16x16x32_bf16 v[120:123], v[148:151], v[172:175], v[120:123]
	v_mfma_f32_16x16x32_bf16 v[116:119], v[140:143], v[190:193], v[116:119]
	v_mfma_f32_16x16x32_bf16 v[112:115], v[148:151], v[190:193], v[112:115]
	v_mfma_f32_16x16x32_bf16 v[104:107], v[140:143], v[198:201], v[104:107]
	v_mfma_f32_16x16x32_bf16 v[96:99], v[148:151], v[198:201], v[96:99]
	v_mfma_f32_16x16x32_bf16 v[88:91], v[140:143], v[206:209], v[88:91]
	v_mfma_f32_16x16x32_bf16 v[80:83], v[148:151], v[206:209], v[80:83]
	s_setprio 0
	s_setprio 1
	v_mfma_f32_16x16x32_bf16 v[108:111], v[152:155], v[168:171], v[108:111]
	v_mfma_f32_16x16x32_bf16 v[100:103], v[160:163], v[168:171], v[100:103]
	v_mfma_f32_16x16x32_bf16 v[92:95], v[152:155], v[186:189], v[92:95]
	v_mfma_f32_16x16x32_bf16 v[84:87], v[160:163], v[186:189], v[84:87]
	v_mfma_f32_16x16x32_bf16 v[76:79], v[152:155], v[194:197], v[76:79]
	v_mfma_f32_16x16x32_bf16 v[72:75], v[160:163], v[194:197], v[72:75]
	v_mfma_f32_16x16x32_bf16 v[68:71], v[152:155], v[202:205], v[68:71]
	v_mfma_f32_16x16x32_bf16 v[64:67], v[160:163], v[202:205], v[64:67]
	v_mfma_f32_16x16x32_bf16 v[108:111], v[156:159], v[172:175], v[108:111]
	v_mfma_f32_16x16x32_bf16 v[100:103], v[164:167], v[172:175], v[100:103]
	v_mfma_f32_16x16x32_bf16 v[92:95], v[156:159], v[190:193], v[92:95]
	v_mfma_f32_16x16x32_bf16 v[84:87], v[164:167], v[190:193], v[84:87]
	v_mfma_f32_16x16x32_bf16 v[76:79], v[156:159], v[198:201], v[76:79]
	v_mfma_f32_16x16x32_bf16 v[72:75], v[164:167], v[198:201], v[72:75]
	v_mfma_f32_16x16x32_bf16 v[68:71], v[156:159], v[206:209], v[68:71]
	v_mfma_f32_16x16x32_bf16 v[64:67], v[164:167], v[206:209], v[64:67]
	s_setprio 0
	s_barrier
	s_add_i32 s5, s5, s30
	v_lshl_add_u64 v[176:177], v[176:177], 0, s[14:15]
	s_mov_b32 m0, s5
	ds_read_b128 v[168:171], v185 offset:49152
	ds_read_b128 v[172:175], v185 offset:50176
	ds_read_b128 v[186:189], v185 offset:51200
	ds_read_b128 v[190:193], v185 offset:52224
	ds_read_b128 v[194:197], v185 offset:53248
	ds_read_b128 v[198:201], v185 offset:54272
	ds_read_b128 v[202:205], v185 offset:55296
	ds_read_b128 v[206:209], v185 offset:56320
	global_load_lds_dwordx4 v[176:177], off
	s_add_i32 m0, s5, 0x2000
	s_add_u32 s6, s60, 0x100080
	v_lshl_add_u64 v[176:177], v[210:211], 0, s[14:15]
	s_addc_u32 s7, s61, 0
	s_add_i32 s5, s8, s30
	global_load_lds_dwordx4 v[176:177], off
	v_lshl_add_u64 v[176:177], s[6:7], 0, v[128:129]
	s_mov_b32 m0, s5
	s_nop 0
	global_load_lds_dwordx4 v[176:177], off
	v_lshl_add_u64 v[176:177], s[6:7], 0, v[130:131]
	s_add_i32 m0, s5, 0x2000
	s_nop 0
	global_load_lds_dwordx4 v[176:177], off
	v_lshl_add_u64 v[176:177], v[212:213], 0, s[14:15]
	s_mov_b32 m0, s70
	s_nop 0
	global_load_lds_dwordx4 v[176:177], off
	v_lshl_add_u64 v[176:177], v[214:215], 0, s[14:15]
	s_mov_b32 m0, s71
	s_nop 0
	global_load_lds_dwordx4 v[176:177], off
	s_waitcnt vmcnt(8)
	s_waitcnt lgkmcnt(0)
	s_barrier
	s_setprio 1
	v_mfma_f32_16x16x32_bf16 v[60:63], v[136:139], v[168:171], v[60:63]
	v_mfma_f32_16x16x32_bf16 v[56:59], v[144:147], v[168:171], v[56:59]
	v_mfma_f32_16x16x32_bf16 v[52:55], v[136:139], v[186:189], v[52:55]
	v_mfma_f32_16x16x32_bf16 v[48:51], v[144:147], v[186:189], v[48:51]
	v_mfma_f32_16x16x32_bf16 v[40:43], v[136:139], v[194:197], v[40:43]
	v_mfma_f32_16x16x32_bf16 v[32:35], v[144:147], v[194:197], v[32:35]
	v_mfma_f32_16x16x32_bf16 v[24:27], v[136:139], v[202:205], v[24:27]
	v_mfma_f32_16x16x32_bf16 v[16:19], v[144:147], v[202:205], v[16:19]
	v_mfma_f32_16x16x32_bf16 v[60:63], v[140:143], v[172:175], v[60:63]
	v_mfma_f32_16x16x32_bf16 v[56:59], v[148:151], v[172:175], v[56:59]
	v_mfma_f32_16x16x32_bf16 v[52:55], v[140:143], v[190:193], v[52:55]
	v_mfma_f32_16x16x32_bf16 v[48:51], v[148:151], v[190:193], v[48:51]
	v_mfma_f32_16x16x32_bf16 v[40:43], v[140:143], v[198:201], v[40:43]
	v_mfma_f32_16x16x32_bf16 v[32:35], v[148:151], v[198:201], v[32:35]
	v_mfma_f32_16x16x32_bf16 v[24:27], v[140:143], v[206:209], v[24:27]
	v_mfma_f32_16x16x32_bf16 v[16:19], v[148:151], v[206:209], v[16:19]
	s_setprio 0
	s_setprio 1
	v_mfma_f32_16x16x32_bf16 v[44:47], v[152:155], v[168:171], v[44:47]
	v_mfma_f32_16x16x32_bf16 v[36:39], v[160:163], v[168:171], v[36:39]
	v_mfma_f32_16x16x32_bf16 v[28:31], v[152:155], v[186:189], v[28:31]
	v_mfma_f32_16x16x32_bf16 v[20:23], v[160:163], v[186:189], v[20:23]
	v_mfma_f32_16x16x32_bf16 v[12:15], v[152:155], v[194:197], v[12:15]
	v_mfma_f32_16x16x32_bf16 v[8:11], v[160:163], v[194:197], v[8:11]
	v_mfma_f32_16x16x32_bf16 v[4:7], v[152:155], v[202:205], v[4:7]
	v_mfma_f32_16x16x32_bf16 v[0:3], v[160:163], v[202:205], v[0:3]
	v_mfma_f32_16x16x32_bf16 v[44:47], v[156:159], v[172:175], v[44:47]
	v_mfma_f32_16x16x32_bf16 v[36:39], v[164:167], v[172:175], v[36:39]
	v_mfma_f32_16x16x32_bf16 v[28:31], v[156:159], v[190:193], v[28:31]
	v_mfma_f32_16x16x32_bf16 v[20:23], v[164:167], v[190:193], v[20:23]
	v_mfma_f32_16x16x32_bf16 v[12:15], v[156:159], v[198:201], v[12:15]
	v_mfma_f32_16x16x32_bf16 v[8:11], v[164:167], v[198:201], v[8:11]
	v_mfma_f32_16x16x32_bf16 v[4:7], v[156:159], v[206:209], v[4:7]
	v_mfma_f32_16x16x32_bf16 v[0:3], v[164:167], v[206:209], v[0:3]
	s_setprio 0
	s_barrier
	s_add_i32 s4, s4, 2
	s_add_u32 s58, s58, 0x100
	s_addc_u32 s59, s59, 0
	s_cmp_ge_i32 s4, s67
	s_cbranch_scc0 .LBB0_1479
	v_pk_add_f32 v[160:161], v[126:127], 0 op_sel_hi:[1,0]
	v_pk_add_f32 v[162:163], v[124:125], 0 op_sel_hi:[1,0]
	v_pk_add_f32 v[158:159], v[122:123], 0 op_sel_hi:[1,0]
	v_pk_add_f32 v[156:157], v[120:121], 0 op_sel_hi:[1,0]
	v_pk_add_f32 v[170:171], v[110:111], 0 op_sel_hi:[1,0]
	v_pk_add_f32 v[168:169], v[108:109], 0 op_sel_hi:[1,0]
	v_pk_add_f32 v[166:167], v[102:103], 0 op_sel_hi:[1,0]
	v_pk_add_f32 v[164:165], v[100:101], 0 op_sel_hi:[1,0]
	v_pk_add_f32 v[138:139], v[118:119], 0 op_sel_hi:[1,0]
	v_pk_add_f32 v[140:141], v[116:117], 0 op_sel_hi:[1,0]
	v_pk_add_f32 v[142:143], v[114:115], 0 op_sel_hi:[1,0]
	v_pk_add_f32 v[144:145], v[112:113], 0 op_sel_hi:[1,0]
	v_pk_add_f32 v[146:147], v[94:95], 0 op_sel_hi:[1,0]
	v_pk_add_f32 v[148:149], v[92:93], 0 op_sel_hi:[1,0]
	v_pk_add_f32 v[150:151], v[86:87], 0 op_sel_hi:[1,0]
	v_pk_add_f32 v[152:153], v[84:85], 0 op_sel_hi:[1,0]
	v_pk_add_f32 v[120:121], v[106:107], 0 op_sel_hi:[1,0]
	v_pk_add_f32 v[118:119], v[104:105], 0 op_sel_hi:[1,0]
	v_pk_add_f32 v[114:115], v[98:99], 0 op_sel_hi:[1,0]
	v_pk_add_f32 v[112:113], v[96:97], 0 op_sel_hi:[1,0]
	v_pk_add_f32 v[136:137], v[78:79], 0 op_sel_hi:[1,0]
	v_pk_add_f32 v[126:127], v[76:77], 0 op_sel_hi:[1,0]
	v_pk_add_f32 v[124:125], v[74:75], 0 op_sel_hi:[1,0]
	v_pk_add_f32 v[122:123], v[72:73], 0 op_sel_hi:[1,0]
	v_pk_add_f32 v[96:97], v[90:91], 0 op_sel_hi:[1,0]
	v_pk_add_f32 v[98:99], v[88:89], 0 op_sel_hi:[1,0]
	v_pk_add_f32 v[100:101], v[82:83], 0 op_sel_hi:[1,0]
	v_pk_add_f32 v[102:103], v[80:81], 0 op_sel_hi:[1,0]
	v_pk_add_f32 v[104:105], v[70:71], 0 op_sel_hi:[1,0]
	v_pk_add_f32 v[106:107], v[68:69], 0 op_sel_hi:[1,0]
	v_pk_add_f32 v[108:109], v[66:67], 0 op_sel_hi:[1,0]
	v_pk_add_f32 v[110:111], v[64:65], 0 op_sel_hi:[1,0]
	v_pk_add_f32 v[86:87], v[62:63], 0 op_sel_hi:[1,0]
	v_pk_add_f32 v[84:85], v[60:61], 0 op_sel_hi:[1,0]
	v_pk_add_f32 v[82:83], v[58:59], 0 op_sel_hi:[1,0]
	v_pk_add_f32 v[80:81], v[56:57], 0 op_sel_hi:[1,0]
	v_pk_add_f32 v[94:95], v[46:47], 0 op_sel_hi:[1,0]
	v_pk_add_f32 v[92:93], v[44:45], 0 op_sel_hi:[1,0]
	v_pk_add_f32 v[90:91], v[38:39], 0 op_sel_hi:[1,0]
	v_pk_add_f32 v[88:89], v[36:37], 0 op_sel_hi:[1,0]
	v_pk_add_f32 v[64:65], v[54:55], 0 op_sel_hi:[1,0]
	v_pk_add_f32 v[66:67], v[52:53], 0 op_sel_hi:[1,0]
	v_pk_add_f32 v[68:69], v[50:51], 0 op_sel_hi:[1,0]
	v_pk_add_f32 v[70:71], v[48:49], 0 op_sel_hi:[1,0]
	v_pk_add_f32 v[72:73], v[30:31], 0 op_sel_hi:[1,0]
	v_pk_add_f32 v[74:75], v[28:29], 0 op_sel_hi:[1,0]
	v_pk_add_f32 v[76:77], v[22:23], 0 op_sel_hi:[1,0]
	v_pk_add_f32 v[78:79], v[20:21], 0 op_sel_hi:[1,0]
	v_pk_add_f32 v[54:55], v[42:43], 0 op_sel_hi:[1,0]
	v_pk_add_f32 v[52:53], v[40:41], 0 op_sel_hi:[1,0]
	v_pk_add_f32 v[50:51], v[34:35], 0 op_sel_hi:[1,0]
	v_pk_add_f32 v[48:49], v[32:33], 0 op_sel_hi:[1,0]
	v_pk_add_f32 v[62:63], v[14:15], 0 op_sel_hi:[1,0]
	v_pk_add_f32 v[60:61], v[12:13], 0 op_sel_hi:[1,0]
	v_pk_add_f32 v[58:59], v[10:11], 0 op_sel_hi:[1,0]
	v_pk_add_f32 v[56:57], v[8:9], 0 op_sel_hi:[1,0]
	v_pk_add_f32 v[32:33], v[26:27], 0 op_sel_hi:[1,0]
	v_pk_add_f32 v[34:35], v[24:25], 0 op_sel_hi:[1,0]
	v_pk_add_f32 v[36:37], v[18:19], 0 op_sel_hi:[1,0]
	v_pk_add_f32 v[38:39], v[16:17], 0 op_sel_hi:[1,0]
	v_pk_add_f32 v[40:41], v[6:7], 0 op_sel_hi:[1,0]
	v_pk_add_f32 v[42:43], v[4:5], 0 op_sel_hi:[1,0]
	v_pk_add_f32 v[44:45], v[2:3], 0 op_sel_hi:[1,0]
	v_pk_add_f32 v[46:47], v[0:1], 0 op_sel_hi:[1,0]

.LBB0_1511:
	s_mov_b64 s[34:35], s[16:17]
	ds_read_b128 v[140:143], v134
	ds_read_b128 v[144:147], v134 offset:1024
	ds_read_b128 v[148:151], v134 offset:2048
	ds_read_b128 v[152:155], v134 offset:3072
	ds_read_b128 v[156:159], v135
	ds_read_b128 v[160:163], v135 offset:1024
	ds_read_b128 v[164:167], v135 offset:2048
	ds_read_b128 v[168:171], v135 offset:3072
	s_add_u32 s48, s0, s34
	s_addc_u32 s49, s1, s35
	s_add_u32 s36, s48, 0x100
	s_addc_u32 s37, s49, 0
	s_add_u32 s34, s2, s34
	s_addc_u32 s35, s3, s35
	s_add_u32 s34, s34, 0x100
	s_addc_u32 s35, s35, 0
	s_cmp_eq_u32 s38, s39
	s_cselect_b32 s37, s13, s37
	s_cselect_b32 s36, s12, s36
	s_cselect_b32 s35, s15, s35
	s_cselect_b32 s34, s14, s34
	s_add_u32 s48, s48, 0x100080
	s_addc_u32 s49, s49, 0
	s_mov_b32 m0, s40
	v_lshl_add_u64 v[206:207], s[48:49], 0, v[128:129]
	ds_read_b128 v[172:175], v136
	ds_read_b128 v[176:179], v136 offset:1024
	ds_read_b128 v[182:185], v136 offset:2048
	ds_read_b128 v[186:189], v136 offset:3072
	ds_read_b128 v[190:193], v136 offset:4096
	ds_read_b128 v[194:197], v136 offset:5120
	ds_read_b128 v[198:201], v136 offset:6144
	ds_read_b128 v[202:205], v136 offset:7168
	global_load_lds_dwordx4 v[206:207], off
	v_lshl_add_u64 v[206:207], s[48:49], 0, v[130:131]
	s_mov_b32 m0, s41
	s_nop 0
	global_load_lds_dwordx4 v[206:207], off
	s_waitcnt vmcnt(8)
	s_waitcnt lgkmcnt(0)
	s_barrier
	s_setprio 1
	v_mfma_f32_16x16x32_bf16 v[124:127], v[140:143], v[172:175], v[124:127]
	v_mfma_f32_16x16x32_bf16 v[120:123], v[148:151], v[172:175], v[120:123]
	v_mfma_f32_16x16x32_bf16 v[108:111], v[140:143], v[182:185], v[108:111]
	v_mfma_f32_16x16x32_bf16 v[104:107], v[148:151], v[182:185], v[104:107]
	v_mfma_f32_16x16x32_bf16 v[92:95], v[140:143], v[190:193], v[92:95]
	v_mfma_f32_16x16x32_bf16 v[88:91], v[148:151], v[190:193], v[88:91]
	v_mfma_f32_16x16x32_bf16 v[76:79], v[140:143], v[198:201], v[76:79]
	v_mfma_f32_16x16x32_bf16 v[72:75], v[148:151], v[198:201], v[72:75]
	v_mfma_f32_16x16x32_bf16 v[124:127], v[144:147], v[176:179], v[124:127]
	v_mfma_f32_16x16x32_bf16 v[120:123], v[152:155], v[176:179], v[120:123]
	v_mfma_f32_16x16x32_bf16 v[108:111], v[144:147], v[186:189], v[108:111]
	v_mfma_f32_16x16x32_bf16 v[104:107], v[152:155], v[186:189], v[104:107]
	v_mfma_f32_16x16x32_bf16 v[92:95], v[144:147], v[194:197], v[92:95]
	v_mfma_f32_16x16x32_bf16 v[88:91], v[152:155], v[194:197], v[88:91]
	v_mfma_f32_16x16x32_bf16 v[76:79], v[144:147], v[202:205], v[76:79]
	v_mfma_f32_16x16x32_bf16 v[72:75], v[152:155], v[202:205], v[72:75]
	s_setprio 0
	s_setprio 1
	v_mfma_f32_16x16x32_bf16 v[116:119], v[156:159], v[172:175], v[116:119]
	v_mfma_f32_16x16x32_bf16 v[112:115], v[164:167], v[172:175], v[112:115]
	v_mfma_f32_16x16x32_bf16 v[100:103], v[156:159], v[182:185], v[100:103]
	v_mfma_f32_16x16x32_bf16 v[96:99], v[164:167], v[182:185], v[96:99]
	v_mfma_f32_16x16x32_bf16 v[84:87], v[156:159], v[190:193], v[84:87]
	v_mfma_f32_16x16x32_bf16 v[80:83], v[164:167], v[190:193], v[80:83]
	v_mfma_f32_16x16x32_bf16 v[68:71], v[156:159], v[198:201], v[68:71]
	v_mfma_f32_16x16x32_bf16 v[64:67], v[164:167], v[198:201], v[64:67]
	v_mfma_f32_16x16x32_bf16 v[116:119], v[160:163], v[176:179], v[116:119]
	v_mfma_f32_16x16x32_bf16 v[112:115], v[168:171], v[176:179], v[112:115]
	v_mfma_f32_16x16x32_bf16 v[100:103], v[160:163], v[186:189], v[100:103]
	v_mfma_f32_16x16x32_bf16 v[96:99], v[168:171], v[186:189], v[96:99]
	v_mfma_f32_16x16x32_bf16 v[84:87], v[160:163], v[194:197], v[84:87]
	v_mfma_f32_16x16x32_bf16 v[80:83], v[168:171], v[194:197], v[80:83]
	v_mfma_f32_16x16x32_bf16 v[68:71], v[160:163], v[202:205], v[68:71]
	v_mfma_f32_16x16x32_bf16 v[64:67], v[168:171], v[202:205], v[64:67]
	s_setprio 0
	s_barrier
	s_mov_b32 m0, s42
	v_lshl_add_u64 v[206:207], s[34:35], 0, v[128:129]
	s_add_u32 s48, s34, 0x100000
	ds_read_b128 v[172:175], v136 offset:16384
	ds_read_b128 v[176:179], v136 offset:17408
	ds_read_b128 v[182:185], v136 offset:18432
	ds_read_b128 v[186:189], v136 offset:19456
	ds_read_b128 v[190:193], v136 offset:20480
	ds_read_b128 v[194:197], v136 offset:21504
	ds_read_b128 v[198:201], v136 offset:22528
	ds_read_b128 v[202:205], v136 offset:23552
	global_load_lds_dwordx4 v[206:207], off
	v_lshl_add_u64 v[208:209], s[34:35], 0, v[130:131]
	s_mov_b32 m0, s43
	s_addc_u32 s49, s35, 0
	global_load_lds_dwordx4 v[208:209], off
	v_lshl_add_u64 v[210:211], s[48:49], 0, v[128:129]
	s_mov_b32 m0, s44
	v_lshl_add_u64 v[212:213], s[36:37], 0, v[130:131]
	global_load_lds_dwordx4 v[210:211], off
	v_lshl_add_u64 v[210:211], s[48:49], 0, v[130:131]
	s_mov_b32 m0, s45
	s_nop 0
	global_load_lds_dwordx4 v[210:211], off
	v_lshl_add_u64 v[210:211], s[36:37], 0, v[128:129]
	s_mov_b32 m0, s8
	s_nop 0
	global_load_lds_dwordx4 v[210:211], off
	s_mov_b32 m0, s9
	s_nop 0
	global_load_lds_dwordx4 v[212:213], off
	s_waitcnt vmcnt(8)
	s_waitcnt lgkmcnt(0)
	s_barrier
	s_setprio 1
	v_mfma_f32_16x16x32_bf16 v[60:63], v[140:143], v[172:175], v[60:63]
	v_mfma_f32_16x16x32_bf16 v[56:59], v[148:151], v[172:175], v[56:59]
	v_mfma_f32_16x16x32_bf16 v[44:47], v[140:143], v[182:185], v[44:47]
	v_mfma_f32_16x16x32_bf16 v[40:43], v[148:151], v[182:185], v[40:43]
	v_mfma_f32_16x16x32_bf16 v[28:31], v[140:143], v[190:193], v[28:31]
	v_mfma_f32_16x16x32_bf16 v[24:27], v[148:151], v[190:193], v[24:27]
	v_mfma_f32_16x16x32_bf16 v[12:15], v[140:143], v[198:201], v[12:15]
	v_mfma_f32_16x16x32_bf16 v[8:11], v[148:151], v[198:201], v[8:11]
	v_mfma_f32_16x16x32_bf16 v[60:63], v[144:147], v[176:179], v[60:63]
	v_mfma_f32_16x16x32_bf16 v[56:59], v[152:155], v[176:179], v[56:59]
	v_mfma_f32_16x16x32_bf16 v[44:47], v[144:147], v[186:189], v[44:47]
	v_mfma_f32_16x16x32_bf16 v[40:43], v[152:155], v[186:189], v[40:43]
	v_mfma_f32_16x16x32_bf16 v[28:31], v[144:147], v[194:197], v[28:31]
	v_mfma_f32_16x16x32_bf16 v[24:27], v[152:155], v[194:197], v[24:27]
	v_mfma_f32_16x16x32_bf16 v[12:15], v[144:147], v[202:205], v[12:15]
	v_mfma_f32_16x16x32_bf16 v[8:11], v[152:155], v[202:205], v[8:11]
	s_setprio 0
	s_setprio 1
	v_mfma_f32_16x16x32_bf16 v[52:55], v[156:159], v[172:175], v[52:55]
	v_mfma_f32_16x16x32_bf16 v[48:51], v[164:167], v[172:175], v[48:51]
	v_mfma_f32_16x16x32_bf16 v[36:39], v[156:159], v[182:185], v[36:39]
	v_mfma_f32_16x16x32_bf16 v[32:35], v[164:167], v[182:185], v[32:35]
	v_mfma_f32_16x16x32_bf16 v[20:23], v[156:159], v[190:193], v[20:23]
	v_mfma_f32_16x16x32_bf16 v[16:19], v[164:167], v[190:193], v[16:19]
	v_mfma_f32_16x16x32_bf16 v[4:7], v[156:159], v[198:201], v[4:7]
	v_mfma_f32_16x16x32_bf16 v[0:3], v[164:167], v[198:201], v[0:3]
	v_mfma_f32_16x16x32_bf16 v[52:55], v[160:163], v[176:179], v[52:55]
	v_mfma_f32_16x16x32_bf16 v[48:51], v[168:171], v[176:179], v[48:51]
	v_mfma_f32_16x16x32_bf16 v[36:39], v[160:163], v[186:189], v[36:39]
	v_mfma_f32_16x16x32_bf16 v[32:35], v[168:171], v[186:189], v[32:35]
	v_mfma_f32_16x16x32_bf16 v[20:23], v[160:163], v[194:197], v[20:23]
	v_mfma_f32_16x16x32_bf16 v[16:19], v[168:171], v[194:197], v[16:19]
	v_mfma_f32_16x16x32_bf16 v[4:7], v[160:163], v[202:205], v[4:7]
	v_mfma_f32_16x16x32_bf16 v[0:3], v[168:171], v[202:205], v[0:3]
	s_setprio 0
	s_barrier
	ds_read_b128 v[140:143], v137
	ds_read_b128 v[144:147], v137 offset:1024
	ds_read_b128 v[148:151], v137 offset:2048
	ds_read_b128 v[152:155], v137 offset:3072
	ds_read_b128 v[156:159], v138
	ds_read_b128 v[160:163], v138 offset:1024
	ds_read_b128 v[164:167], v138 offset:2048
	ds_read_b128 v[168:171], v138 offset:3072
	s_add_u32 s36, s36, 0x100000
	s_addc_u32 s37, s37, 0
	s_mov_b32 m0, s23
	v_lshl_add_u64 v[214:215], s[36:37], 0, v[128:129]
	ds_read_b128 v[172:175], v136 offset:32768
	ds_read_b128 v[176:179], v136 offset:33792
	ds_read_b128 v[182:185], v136 offset:34816
	ds_read_b128 v[186:189], v136 offset:35840
	ds_read_b128 v[190:193], v136 offset:36864
	ds_read_b128 v[194:197], v136 offset:37888
	ds_read_b128 v[198:201], v136 offset:38912
	ds_read_b128 v[202:205], v136 offset:39936
	global_load_lds_dwordx4 v[214:215], off
	v_lshl_add_u64 v[214:215], s[36:37], 0, v[130:131]
	s_mov_b32 m0, s28
	s_nop 0
	global_load_lds_dwordx4 v[214:215], off
	s_waitcnt vmcnt(8)
	s_waitcnt lgkmcnt(0)
	s_barrier
	s_setprio 1
	v_mfma_f32_16x16x32_bf16 v[124:127], v[140:143], v[172:175], v[124:127]
	v_mfma_f32_16x16x32_bf16 v[120:123], v[148:151], v[172:175], v[120:123]
	v_mfma_f32_16x16x32_bf16 v[108:111], v[140:143], v[182:185], v[108:111]
	v_mfma_f32_16x16x32_bf16 v[104:107], v[148:151], v[182:185], v[104:107]
	v_mfma_f32_16x16x32_bf16 v[92:95], v[140:143], v[190:193], v[92:95]
	v_mfma_f32_16x16x32_bf16 v[88:91], v[148:151], v[190:193], v[88:91]
	v_mfma_f32_16x16x32_bf16 v[76:79], v[140:143], v[198:201], v[76:79]
	v_mfma_f32_16x16x32_bf16 v[72:75], v[148:151], v[198:201], v[72:75]
	v_mfma_f32_16x16x32_bf16 v[124:127], v[144:147], v[176:179], v[124:127]
	v_mfma_f32_16x16x32_bf16 v[120:123], v[152:155], v[176:179], v[120:123]
	v_mfma_f32_16x16x32_bf16 v[108:111], v[144:147], v[186:189], v[108:111]
	v_mfma_f32_16x16x32_bf16 v[104:107], v[152:155], v[186:189], v[104:107]
	v_mfma_f32_16x16x32_bf16 v[92:95], v[144:147], v[194:197], v[92:95]
	v_mfma_f32_16x16x32_bf16 v[88:91], v[152:155], v[194:197], v[88:91]
	v_mfma_f32_16x16x32_bf16 v[76:79], v[144:147], v[202:205], v[76:79]
	v_mfma_f32_16x16x32_bf16 v[72:75], v[152:155], v[202:205], v[72:75]
	s_setprio 0
	s_setprio 1
	v_mfma_f32_16x16x32_bf16 v[116:119], v[156:159], v[172:175], v[116:119]
	v_mfma_f32_16x16x32_bf16 v[112:115], v[164:167], v[172:175], v[112:115]
	v_mfma_f32_16x16x32_bf16 v[100:103], v[156:159], v[182:185], v[100:103]
	v_mfma_f32_16x16x32_bf16 v[96:99], v[164:167], v[182:185], v[96:99]
	v_mfma_f32_16x16x32_bf16 v[84:87], v[156:159], v[190:193], v[84:87]
	v_mfma_f32_16x16x32_bf16 v[80:83], v[164:167], v[190:193], v[80:83]
	v_mfma_f32_16x16x32_bf16 v[68:71], v[156:159], v[198:201], v[68:71]
	v_mfma_f32_16x16x32_bf16 v[64:67], v[164:167], v[198:201], v[64:67]
	v_mfma_f32_16x16x32_bf16 v[116:119], v[160:163], v[176:179], v[116:119]
	v_mfma_f32_16x16x32_bf16 v[112:115], v[168:171], v[176:179], v[112:115]
	v_mfma_f32_16x16x32_bf16 v[100:103], v[160:163], v[186:189], v[100:103]
	v_mfma_f32_16x16x32_bf16 v[96:99], v[168:171], v[186:189], v[96:99]
	v_mfma_f32_16x16x32_bf16 v[84:87], v[160:163], v[194:197], v[84:87]
	v_mfma_f32_16x16x32_bf16 v[80:83], v[168:171], v[194:197], v[80:83]
	v_mfma_f32_16x16x32_bf16 v[68:71], v[160:163], v[202:205], v[68:71]
	v_mfma_f32_16x16x32_bf16 v[64:67], v[168:171], v[202:205], v[64:67]
	s_setprio 0
	s_barrier
	s_mov_b32 m0, s46
	v_lshl_add_u64 v[206:207], v[206:207], 0, s[10:11]
	s_add_u32 s34, s34, 0x100080
	ds_read_b128 v[172:175], v136 offset:49152
	ds_read_b128 v[176:179], v136 offset:50176
	ds_read_b128 v[182:185], v136 offset:51200
	ds_read_b128 v[186:189], v136 offset:52224
	ds_read_b128 v[190:193], v136 offset:53248
	ds_read_b128 v[194:197], v136 offset:54272
	ds_read_b128 v[198:201], v136 offset:55296
	ds_read_b128 v[202:205], v136 offset:56320
	global_load_lds_dwordx4 v[206:207], off
	v_lshl_add_u64 v[206:207], v[208:209], 0, s[10:11]
	s_mov_b32 m0, s47
	s_addc_u32 s35, s35, 0
	global_load_lds_dwordx4 v[206:207], off
	v_lshl_add_u64 v[206:207], s[34:35], 0, v[128:129]
	s_mov_b32 m0, s52
	s_nop 0
	global_load_lds_dwordx4 v[206:207], off
	v_lshl_add_u64 v[206:207], s[34:35], 0, v[130:131]
	s_mov_b32 m0, s53
	s_nop 0
	global_load_lds_dwordx4 v[206:207], off
	v_lshl_add_u64 v[206:207], v[210:211], 0, s[10:11]
	s_mov_b32 m0, s29
	s_nop 0
	global_load_lds_dwordx4 v[206:207], off
	v_lshl_add_u64 v[206:207], v[212:213], 0, s[10:11]
	s_mov_b32 m0, s30
	s_nop 0
	global_load_lds_dwordx4 v[206:207], off
	s_waitcnt vmcnt(8)
	s_waitcnt lgkmcnt(0)
	s_barrier
	s_setprio 1
	v_mfma_f32_16x16x32_bf16 v[60:63], v[140:143], v[172:175], v[60:63]
	v_mfma_f32_16x16x32_bf16 v[56:59], v[148:151], v[172:175], v[56:59]
	v_mfma_f32_16x16x32_bf16 v[44:47], v[140:143], v[182:185], v[44:47]
	v_mfma_f32_16x16x32_bf16 v[40:43], v[148:151], v[182:185], v[40:43]
	v_mfma_f32_16x16x32_bf16 v[28:31], v[140:143], v[190:193], v[28:31]
	v_mfma_f32_16x16x32_bf16 v[24:27], v[148:151], v[190:193], v[24:27]
	v_mfma_f32_16x16x32_bf16 v[12:15], v[140:143], v[198:201], v[12:15]
	v_mfma_f32_16x16x32_bf16 v[8:11], v[148:151], v[198:201], v[8:11]
	v_mfma_f32_16x16x32_bf16 v[60:63], v[144:147], v[176:179], v[60:63]
	v_mfma_f32_16x16x32_bf16 v[56:59], v[152:155], v[176:179], v[56:59]
	v_mfma_f32_16x16x32_bf16 v[44:47], v[144:147], v[186:189], v[44:47]
	v_mfma_f32_16x16x32_bf16 v[40:43], v[152:155], v[186:189], v[40:43]
	v_mfma_f32_16x16x32_bf16 v[28:31], v[144:147], v[194:197], v[28:31]
	v_mfma_f32_16x16x32_bf16 v[24:27], v[152:155], v[194:197], v[24:27]
	v_mfma_f32_16x16x32_bf16 v[12:15], v[144:147], v[202:205], v[12:15]
	v_mfma_f32_16x16x32_bf16 v[8:11], v[152:155], v[202:205], v[8:11]
	s_setprio 0
	s_setprio 1
	v_mfma_f32_16x16x32_bf16 v[52:55], v[156:159], v[172:175], v[52:55]
	v_mfma_f32_16x16x32_bf16 v[48:51], v[164:167], v[172:175], v[48:51]
	v_mfma_f32_16x16x32_bf16 v[36:39], v[156:159], v[182:185], v[36:39]
	v_mfma_f32_16x16x32_bf16 v[32:35], v[164:167], v[182:185], v[32:35]
	v_mfma_f32_16x16x32_bf16 v[20:23], v[156:159], v[190:193], v[20:23]
	v_mfma_f32_16x16x32_bf16 v[16:19], v[164:167], v[190:193], v[16:19]
	v_mfma_f32_16x16x32_bf16 v[4:7], v[156:159], v[198:201], v[4:7]
	v_mfma_f32_16x16x32_bf16 v[0:3], v[164:167], v[198:201], v[0:3]
	v_mfma_f32_16x16x32_bf16 v[52:55], v[160:163], v[176:179], v[52:55]
	v_mfma_f32_16x16x32_bf16 v[48:51], v[168:171], v[176:179], v[48:51]
	v_mfma_f32_16x16x32_bf16 v[36:39], v[160:163], v[186:189], v[36:39]
	v_mfma_f32_16x16x32_bf16 v[32:35], v[168:171], v[186:189], v[32:35]
	v_mfma_f32_16x16x32_bf16 v[20:23], v[160:163], v[194:197], v[20:23]
	v_mfma_f32_16x16x32_bf16 v[16:19], v[168:171], v[194:197], v[16:19]
	v_mfma_f32_16x16x32_bf16 v[4:7], v[160:163], v[202:205], v[4:7]
	v_mfma_f32_16x16x32_bf16 v[0:3], v[168:171], v[202:205], v[0:3]
	s_setprio 0
	s_barrier
	s_add_i32 s39, s39, 2
	s_add_u32 s16, s16, 0x100
	s_addc_u32 s17, s17, 0
	s_cmp_ge_i32 s39, s31
	s_cbranch_scc0 .LBB0_1511
	v_mov_b32_e32 v129, v127

.LBB0_1684:
	s_mov_b64 s[6:7], s[58:59]
	ds_read_b128 v[140:143], v147
	ds_read_b128 v[150:153], v147 offset:1024
	ds_read_b128 v[154:157], v147 offset:2048
	ds_read_b128 v[158:161], v147 offset:3072
	ds_read_b128 v[162:165], v148
	ds_read_b128 v[166:169], v148 offset:1024
	ds_read_b128 v[170:173], v148 offset:2048
	ds_read_b128 v[174:177], v148 offset:3072
	s_add_u32 s8, s54, s6
	s_addc_u32 s9, s55, s7
	s_add_u32 s28, s8, 0x100
	s_addc_u32 s29, s9, 0
	s_add_u32 s6, s56, s6
	s_addc_u32 s7, s57, s7
	s_add_u32 s6, s6, 0x100
	s_addc_u32 s7, s7, 0
	s_cmp_eq_u32 s71, s5
	s_cselect_b32 s63, s17, s29
	s_cselect_b32 s62, s16, s28
	s_cselect_b32 s61, s37, s7
	s_cselect_b32 s60, s36, s6
	s_add_u32 s6, s8, 0x80080
	s_addc_u32 s7, s9, 0
	v_lshl_add_u64 v[178:179], s[6:7], 0, v[134:135]
	s_add_i32 m0, s23, 0xc000
	ds_read_b128 v[182:185], v149
	ds_read_b128 v[186:189], v149 offset:1024
	ds_read_b128 v[190:193], v149 offset:2048
	ds_read_b128 v[194:197], v149 offset:3072
	ds_read_b128 v[198:201], v149 offset:4096
	ds_read_b128 v[202:205], v149 offset:5120
	ds_read_b128 v[206:209], v149 offset:6144
	ds_read_b128 v[210:213], v149 offset:7168
	global_load_lds_dwordx4 v[178:179], off
	v_lshl_add_u64 v[178:179], s[6:7], 0, v[130:131]
	s_add_i32 m0, s23, 0xe000
	s_nop 0
	global_load_lds_dwordx4 v[178:179], off
	s_waitcnt vmcnt(8)
	s_waitcnt lgkmcnt(0)
	s_barrier
	s_setprio 1
	v_mfma_f32_16x16x32_bf16 v[124:127], v[140:143], v[182:185], v[124:127]
	v_mfma_f32_16x16x32_bf16 v[116:119], v[154:157], v[182:185], v[116:119]
	v_mfma_f32_16x16x32_bf16 v[108:111], v[140:143], v[190:193], v[108:111]
	v_mfma_f32_16x16x32_bf16 v[100:103], v[154:157], v[190:193], v[100:103]
	v_mfma_f32_16x16x32_bf16 v[92:95], v[140:143], v[198:201], v[92:95]
	v_mfma_f32_16x16x32_bf16 v[84:87], v[154:157], v[198:201], v[84:87]
	v_mfma_f32_16x16x32_bf16 v[76:79], v[140:143], v[206:209], v[76:79]
	v_mfma_f32_16x16x32_bf16 v[68:71], v[154:157], v[206:209], v[68:71]
	v_mfma_f32_16x16x32_bf16 v[124:127], v[150:153], v[186:189], v[124:127]
	v_mfma_f32_16x16x32_bf16 v[116:119], v[158:161], v[186:189], v[116:119]
	v_mfma_f32_16x16x32_bf16 v[108:111], v[150:153], v[194:197], v[108:111]
	v_mfma_f32_16x16x32_bf16 v[100:103], v[158:161], v[194:197], v[100:103]
	v_mfma_f32_16x16x32_bf16 v[92:95], v[150:153], v[202:205], v[92:95]
	v_mfma_f32_16x16x32_bf16 v[84:87], v[158:161], v[202:205], v[84:87]
	v_mfma_f32_16x16x32_bf16 v[76:79], v[150:153], v[210:213], v[76:79]
	v_mfma_f32_16x16x32_bf16 v[68:71], v[158:161], v[210:213], v[68:71]
	s_setprio 0
	s_setprio 1
	v_mfma_f32_16x16x32_bf16 v[120:123], v[162:165], v[182:185], v[120:123]
	v_mfma_f32_16x16x32_bf16 v[112:115], v[170:173], v[182:185], v[112:115]
	v_mfma_f32_16x16x32_bf16 v[104:107], v[162:165], v[190:193], v[104:107]
	v_mfma_f32_16x16x32_bf16 v[96:99], v[170:173], v[190:193], v[96:99]
	v_mfma_f32_16x16x32_bf16 v[88:91], v[162:165], v[198:201], v[88:91]
	v_mfma_f32_16x16x32_bf16 v[80:83], v[170:173], v[198:201], v[80:83]
	v_mfma_f32_16x16x32_bf16 v[72:75], v[162:165], v[206:209], v[72:75]
	v_mfma_f32_16x16x32_bf16 v[64:67], v[170:173], v[206:209], v[64:67]
	v_mfma_f32_16x16x32_bf16 v[120:123], v[166:169], v[186:189], v[120:123]
	v_mfma_f32_16x16x32_bf16 v[112:115], v[174:177], v[186:189], v[112:115]
	v_mfma_f32_16x16x32_bf16 v[104:107], v[166:169], v[194:197], v[104:107]
	v_mfma_f32_16x16x32_bf16 v[96:99], v[174:177], v[194:197], v[96:99]
	v_mfma_f32_16x16x32_bf16 v[88:91], v[166:169], v[202:205], v[88:91]
	v_mfma_f32_16x16x32_bf16 v[80:83], v[174:177], v[202:205], v[80:83]
	v_mfma_f32_16x16x32_bf16 v[72:75], v[166:169], v[210:213], v[72:75]
	v_mfma_f32_16x16x32_bf16 v[64:67], v[174:177], v[210:213], v[64:67]
	s_setprio 0
	s_barrier
	s_add_i32 s6, s72, s18
	v_lshl_add_u64 v[178:179], s[60:61], 0, v[132:133]
	s_mov_b32 m0, s6
	ds_read_b128 v[182:185], v149 offset:16384
	ds_read_b128 v[186:189], v149 offset:17408
	ds_read_b128 v[190:193], v149 offset:18432
	ds_read_b128 v[194:197], v149 offset:19456
	ds_read_b128 v[198:201], v149 offset:20480
	ds_read_b128 v[202:205], v149 offset:21504
	ds_read_b128 v[206:209], v149 offset:22528
	ds_read_b128 v[210:213], v149 offset:23552
	global_load_lds_dwordx4 v[178:179], off
	s_add_i32 m0, s6, 0x2000
	s_add_u32 s6, s60, 0x80000
	v_lshl_add_u64 v[214:215], s[60:61], 0, v[128:129]
	s_addc_u32 s7, s61, 0
	s_add_i32 s8, s73, s18
	global_load_lds_dwordx4 v[214:215], off
	v_lshl_add_u64 v[216:217], s[6:7], 0, v[132:133]
	s_mov_b32 m0, s8
	v_lshl_add_u64 v[218:219], s[62:63], 0, v[130:131]
	global_load_lds_dwordx4 v[216:217], off
	v_lshl_add_u64 v[216:217], s[6:7], 0, v[128:129]
	s_add_i32 m0, s8, 0x2000
	s_nop 0
	global_load_lds_dwordx4 v[216:217], off
	v_lshl_add_u64 v[216:217], s[62:63], 0, v[134:135]
	s_mov_b32 m0, s23
	s_nop 0
	global_load_lds_dwordx4 v[216:217], off
	s_mov_b32 m0, s64
	s_nop 0
	global_load_lds_dwordx4 v[218:219], off
	s_waitcnt vmcnt(8)
	s_waitcnt lgkmcnt(0)
	s_barrier
	s_setprio 1
	v_mfma_f32_16x16x32_bf16 v[60:63], v[140:143], v[182:185], v[60:63]
	v_mfma_f32_16x16x32_bf16 v[52:55], v[154:157], v[182:185], v[52:55]
	v_mfma_f32_16x16x32_bf16 v[44:47], v[140:143], v[190:193], v[44:47]
	v_mfma_f32_16x16x32_bf16 v[36:39], v[154:157], v[190:193], v[36:39]
	v_mfma_f32_16x16x32_bf16 v[28:31], v[140:143], v[198:201], v[28:31]
	v_mfma_f32_16x16x32_bf16 v[20:23], v[154:157], v[198:201], v[20:23]
	v_mfma_f32_16x16x32_bf16 v[12:15], v[140:143], v[206:209], v[12:15]
	v_mfma_f32_16x16x32_bf16 v[4:7], v[154:157], v[206:209], v[4:7]
	v_mfma_f32_16x16x32_bf16 v[60:63], v[150:153], v[186:189], v[60:63]
	v_mfma_f32_16x16x32_bf16 v[52:55], v[158:161], v[186:189], v[52:55]
	v_mfma_f32_16x16x32_bf16 v[44:47], v[150:153], v[194:197], v[44:47]
	v_mfma_f32_16x16x32_bf16 v[36:39], v[158:161], v[194:197], v[36:39]
	v_mfma_f32_16x16x32_bf16 v[28:31], v[150:153], v[202:205], v[28:31]
	v_mfma_f32_16x16x32_bf16 v[20:23], v[158:161], v[202:205], v[20:23]
	v_mfma_f32_16x16x32_bf16 v[12:15], v[150:153], v[210:213], v[12:15]
	v_mfma_f32_16x16x32_bf16 v[4:7], v[158:161], v[210:213], v[4:7]
	s_setprio 0
	s_setprio 1
	v_mfma_f32_16x16x32_bf16 v[56:59], v[162:165], v[182:185], v[56:59]
	v_mfma_f32_16x16x32_bf16 v[48:51], v[170:173], v[182:185], v[48:51]
	v_mfma_f32_16x16x32_bf16 v[40:43], v[162:165], v[190:193], v[40:43]
	v_mfma_f32_16x16x32_bf16 v[32:35], v[170:173], v[190:193], v[32:35]
	v_mfma_f32_16x16x32_bf16 v[24:27], v[162:165], v[198:201], v[24:27]
	v_mfma_f32_16x16x32_bf16 v[16:19], v[170:173], v[198:201], v[16:19]
	v_mfma_f32_16x16x32_bf16 v[8:11], v[162:165], v[206:209], v[8:11]
	v_mfma_f32_16x16x32_bf16 v[0:3], v[170:173], v[206:209], v[0:3]
	v_mfma_f32_16x16x32_bf16 v[56:59], v[166:169], v[186:189], v[56:59]
	v_mfma_f32_16x16x32_bf16 v[48:51], v[174:177], v[186:189], v[48:51]
	v_mfma_f32_16x16x32_bf16 v[40:43], v[166:169], v[194:197], v[40:43]
	v_mfma_f32_16x16x32_bf16 v[32:35], v[174:177], v[194:197], v[32:35]
	v_mfma_f32_16x16x32_bf16 v[24:27], v[166:169], v[202:205], v[24:27]
	v_mfma_f32_16x16x32_bf16 v[16:19], v[174:177], v[202:205], v[16:19]
	v_mfma_f32_16x16x32_bf16 v[8:11], v[166:169], v[210:213], v[8:11]
	v_mfma_f32_16x16x32_bf16 v[0:3], v[174:177], v[210:213], v[0:3]
	s_setprio 0
	s_barrier
	s_add_i32 s8, 0, 0x18000
	s_add_i32 s9, 0, 0x1c000
	v_add_u32_e32 v158, s8, v146
	v_add_u32_e32 v174, s9, v146
	ds_read_b128 v[140:143], v158
	ds_read_b128 v[150:153], v158 offset:1024
	ds_read_b128 v[154:157], v158 offset:2048
	ds_read_b128 v[158:161], v158 offset:3072
	ds_read_b128 v[162:165], v174
	ds_read_b128 v[166:169], v174 offset:1024
	ds_read_b128 v[170:173], v174 offset:2048
	ds_read_b128 v[174:177], v174 offset:3072
	s_add_u32 s6, s62, 0x80000
	s_addc_u32 s7, s63, 0
	s_mov_b32 m0, s65
	v_lshl_add_u64 v[220:221], s[6:7], 0, v[134:135]
	ds_read_b128 v[182:185], v149 offset:32768
	ds_read_b128 v[186:189], v149 offset:33792
	ds_read_b128 v[190:193], v149 offset:34816
	ds_read_b128 v[194:197], v149 offset:35840
	ds_read_b128 v[198:201], v149 offset:36864
	ds_read_b128 v[202:205], v149 offset:37888
	ds_read_b128 v[206:209], v149 offset:38912
	ds_read_b128 v[210:213], v149 offset:39936
	global_load_lds_dwordx4 v[220:221], off
	v_lshl_add_u64 v[220:221], s[6:7], 0, v[130:131]
	s_mov_b32 m0, s66
	s_nop 0
	global_load_lds_dwordx4 v[220:221], off
	s_waitcnt vmcnt(8)
	s_waitcnt lgkmcnt(0)
	s_barrier
	s_setprio 1
	v_mfma_f32_16x16x32_bf16 v[124:127], v[140:143], v[182:185], v[124:127]
	v_mfma_f32_16x16x32_bf16 v[116:119], v[154:157], v[182:185], v[116:119]
	v_mfma_f32_16x16x32_bf16 v[108:111], v[140:143], v[190:193], v[108:111]
	v_mfma_f32_16x16x32_bf16 v[100:103], v[154:157], v[190:193], v[100:103]
	v_mfma_f32_16x16x32_bf16 v[92:95], v[140:143], v[198:201], v[92:95]
	v_mfma_f32_16x16x32_bf16 v[84:87], v[154:157], v[198:201], v[84:87]
	v_mfma_f32_16x16x32_bf16 v[76:79], v[140:143], v[206:209], v[76:79]
	v_mfma_f32_16x16x32_bf16 v[68:71], v[154:157], v[206:209], v[68:71]
	v_mfma_f32_16x16x32_bf16 v[124:127], v[150:153], v[186:189], v[124:127]
	v_mfma_f32_16x16x32_bf16 v[116:119], v[158:161], v[186:189], v[116:119]
	v_mfma_f32_16x16x32_bf16 v[108:111], v[150:153], v[194:197], v[108:111]
	v_mfma_f32_16x16x32_bf16 v[100:103], v[158:161], v[194:197], v[100:103]
	v_mfma_f32_16x16x32_bf16 v[92:95], v[150:153], v[202:205], v[92:95]
	v_mfma_f32_16x16x32_bf16 v[84:87], v[158:161], v[202:205], v[84:87]
	v_mfma_f32_16x16x32_bf16 v[76:79], v[150:153], v[210:213], v[76:79]
	v_mfma_f32_16x16x32_bf16 v[68:71], v[158:161], v[210:213], v[68:71]
	s_setprio 0
	s_setprio 1
	v_mfma_f32_16x16x32_bf16 v[120:123], v[162:165], v[182:185], v[120:123]
	v_mfma_f32_16x16x32_bf16 v[112:115], v[170:173], v[182:185], v[112:115]
	v_mfma_f32_16x16x32_bf16 v[104:107], v[162:165], v[190:193], v[104:107]
	v_mfma_f32_16x16x32_bf16 v[96:99], v[170:173], v[190:193], v[96:99]
	v_mfma_f32_16x16x32_bf16 v[88:91], v[162:165], v[198:201], v[88:91]
	v_mfma_f32_16x16x32_bf16 v[80:83], v[170:173], v[198:201], v[80:83]
	v_mfma_f32_16x16x32_bf16 v[72:75], v[162:165], v[206:209], v[72:75]
	v_mfma_f32_16x16x32_bf16 v[64:67], v[170:173], v[206:209], v[64:67]
	v_mfma_f32_16x16x32_bf16 v[120:123], v[166:169], v[186:189], v[120:123]
	v_mfma_f32_16x16x32_bf16 v[112:115], v[174:177], v[186:189], v[112:115]
	v_mfma_f32_16x16x32_bf16 v[104:107], v[166:169], v[194:197], v[104:107]
	v_mfma_f32_16x16x32_bf16 v[96:99], v[174:177], v[194:197], v[96:99]
	v_mfma_f32_16x16x32_bf16 v[88:91], v[166:169], v[202:205], v[88:91]
	v_mfma_f32_16x16x32_bf16 v[80:83], v[174:177], v[202:205], v[80:83]
	v_mfma_f32_16x16x32_bf16 v[72:75], v[166:169], v[210:213], v[72:75]
	v_mfma_f32_16x16x32_bf16 v[64:67], v[174:177], v[210:213], v[64:67]
	s_setprio 0
	s_barrier
	s_add_i32 s6, s8, s18
	v_lshl_add_u64 v[178:179], v[178:179], 0, s[34:35]
	s_mov_b32 m0, s6
	ds_read_b128 v[182:185], v149 offset:49152
	ds_read_b128 v[186:189], v149 offset:50176
	ds_read_b128 v[190:193], v149 offset:51200
	ds_read_b128 v[194:197], v149 offset:52224
	ds_read_b128 v[198:201], v149 offset:53248
	ds_read_b128 v[202:205], v149 offset:54272
	ds_read_b128 v[206:209], v149 offset:55296
	ds_read_b128 v[210:213], v149 offset:56320
	global_load_lds_dwordx4 v[178:179], off
	s_add_i32 m0, s6, 0x2000
	s_add_u32 s6, s60, 0x80080
	v_lshl_add_u64 v[178:179], v[214:215], 0, s[34:35]
	s_addc_u32 s7, s61, 0
	s_add_i32 s8, s9, s18
	global_load_lds_dwordx4 v[178:179], off
	v_lshl_add_u64 v[178:179], s[6:7], 0, v[132:133]
	s_mov_b32 m0, s8
	s_nop 0
	global_load_lds_dwordx4 v[178:179], off
	v_lshl_add_u64 v[178:179], s[6:7], 0, v[128:129]
	s_add_i32 m0, s8, 0x2000
	s_nop 0
	global_load_lds_dwordx4 v[178:179], off
	v_lshl_add_u64 v[178:179], v[216:217], 0, s[34:35]
	s_mov_b32 m0, s69
	s_nop 0
	global_load_lds_dwordx4 v[178:179], off
	v_lshl_add_u64 v[178:179], v[218:219], 0, s[34:35]
	s_mov_b32 m0, s70
	s_nop 0
	global_load_lds_dwordx4 v[178:179], off
	s_waitcnt vmcnt(8)
	s_waitcnt lgkmcnt(0)
	s_barrier
	s_setprio 1
	v_mfma_f32_16x16x32_bf16 v[60:63], v[140:143], v[182:185], v[60:63]
	v_mfma_f32_16x16x32_bf16 v[52:55], v[154:157], v[182:185], v[52:55]
	v_mfma_f32_16x16x32_bf16 v[44:47], v[140:143], v[190:193], v[44:47]
	v_mfma_f32_16x16x32_bf16 v[36:39], v[154:157], v[190:193], v[36:39]
	v_mfma_f32_16x16x32_bf16 v[28:31], v[140:143], v[198:201], v[28:31]
	v_mfma_f32_16x16x32_bf16 v[20:23], v[154:157], v[198:201], v[20:23]
	v_mfma_f32_16x16x32_bf16 v[12:15], v[140:143], v[206:209], v[12:15]
	v_mfma_f32_16x16x32_bf16 v[4:7], v[154:157], v[206:209], v[4:7]
	v_mfma_f32_16x16x32_bf16 v[60:63], v[150:153], v[186:189], v[60:63]
	v_mfma_f32_16x16x32_bf16 v[52:55], v[158:161], v[186:189], v[52:55]
	v_mfma_f32_16x16x32_bf16 v[44:47], v[150:153], v[194:197], v[44:47]
	v_mfma_f32_16x16x32_bf16 v[36:39], v[158:161], v[194:197], v[36:39]
	v_mfma_f32_16x16x32_bf16 v[28:31], v[150:153], v[202:205], v[28:31]
	v_mfma_f32_16x16x32_bf16 v[20:23], v[158:161], v[202:205], v[20:23]
	v_mfma_f32_16x16x32_bf16 v[12:15], v[150:153], v[210:213], v[12:15]
	v_mfma_f32_16x16x32_bf16 v[4:7], v[158:161], v[210:213], v[4:7]
	s_setprio 0
	s_setprio 1
	v_mfma_f32_16x16x32_bf16 v[56:59], v[162:165], v[182:185], v[56:59]
	v_mfma_f32_16x16x32_bf16 v[48:51], v[170:173], v[182:185], v[48:51]
	v_mfma_f32_16x16x32_bf16 v[40:43], v[162:165], v[190:193], v[40:43]
	v_mfma_f32_16x16x32_bf16 v[32:35], v[170:173], v[190:193], v[32:35]
	v_mfma_f32_16x16x32_bf16 v[24:27], v[162:165], v[198:201], v[24:27]
	v_mfma_f32_16x16x32_bf16 v[16:19], v[170:173], v[198:201], v[16:19]
	v_mfma_f32_16x16x32_bf16 v[8:11], v[162:165], v[206:209], v[8:11]
	v_mfma_f32_16x16x32_bf16 v[0:3], v[170:173], v[206:209], v[0:3]
	v_mfma_f32_16x16x32_bf16 v[56:59], v[166:169], v[186:189], v[56:59]
	v_mfma_f32_16x16x32_bf16 v[48:51], v[174:177], v[186:189], v[48:51]
	v_mfma_f32_16x16x32_bf16 v[40:43], v[166:169], v[194:197], v[40:43]
	v_mfma_f32_16x16x32_bf16 v[32:35], v[174:177], v[194:197], v[32:35]
	v_mfma_f32_16x16x32_bf16 v[24:27], v[166:169], v[202:205], v[24:27]
	v_mfma_f32_16x16x32_bf16 v[16:19], v[174:177], v[202:205], v[16:19]
	v_mfma_f32_16x16x32_bf16 v[8:11], v[166:169], v[210:213], v[8:11]
	v_mfma_f32_16x16x32_bf16 v[0:3], v[174:177], v[210:213], v[0:3]
	s_setprio 0
	s_barrier
	s_add_i32 s5, s5, 2
	s_add_u32 s58, s58, 0x100
	s_addc_u32 s59, s59, 0
	s_cmp_ge_i32 s5, s67
	s_cbranch_scc0 .LBB0_1684

.LBB0_1755:
	s_add_u32 s8, s12, s20
	s_addc_u32 s9, s13, s21
	s_and_b64 s[4:5], s[6:7], exec
	s_cselect_b32 s31, s9, s17
	s_cselect_b32 s30, s8, s16
	s_add_u32 s8, s0, s28
	s_addc_u32 s9, s1, s29
	s_and_b64 s[4:5], s[6:7], exec
	s_cselect_b32 s35, s9, s37
	s_cselect_b32 s34, s8, s36
	s_and_b64 vcc, exec, s[2:3]
	s_cbranch_vccnz .Lcoldzero_d3
	v_mov_b64_e32 v[0:1], 0
	s_mov_b32 s4, 0
	s_mov_b64 s[38:39], 0
	v_mov_b64_e32 v[2:3], 0
	v_mov_b64_e32 v[4:5], 0
	v_mov_b64_e32 v[6:7], 0
	v_mov_b64_e32 v[8:9], 0
	v_mov_b64_e32 v[10:11], 0
	v_mov_b64_e32 v[12:13], 0
	v_mov_b64_e32 v[14:15], 0
	v_mov_b64_e32 v[16:17], 0
	v_mov_b64_e32 v[18:19], 0
	v_mov_b64_e32 v[20:21], 0
	v_mov_b64_e32 v[22:23], 0
	v_mov_b64_e32 v[24:25], 0
	v_mov_b64_e32 v[26:27], 0
	v_mov_b64_e32 v[28:29], 0
	v_mov_b64_e32 v[30:31], 0
	v_mov_b64_e32 v[32:33], 0
	v_mov_b64_e32 v[34:35], 0
	v_mov_b64_e32 v[36:37], 0
	v_mov_b64_e32 v[38:39], 0
	v_mov_b64_e32 v[40:41], 0
	v_mov_b64_e32 v[42:43], 0
	v_mov_b64_e32 v[44:45], 0
	v_mov_b64_e32 v[46:47], 0
	v_mov_b64_e32 v[48:49], 0
	v_mov_b64_e32 v[50:51], 0
	v_mov_b64_e32 v[52:53], 0
	v_mov_b64_e32 v[54:55], 0
	v_mov_b64_e32 v[56:57], 0
	v_mov_b64_e32 v[58:59], 0
	v_mov_b64_e32 v[60:61], 0
	v_mov_b64_e32 v[62:63], 0
	v_mov_b64_e32 v[64:65], 0
	v_mov_b64_e32 v[66:67], 0
	v_mov_b64_e32 v[68:69], 0
	v_mov_b64_e32 v[70:71], 0
	v_mov_b64_e32 v[72:73], 0
	v_mov_b64_e32 v[74:75], 0
	v_mov_b64_e32 v[76:77], 0
	v_mov_b64_e32 v[78:79], 0
	v_mov_b64_e32 v[80:81], 0
	v_mov_b64_e32 v[82:83], 0
	v_mov_b64_e32 v[84:85], 0
	v_mov_b64_e32 v[86:87], 0
	v_mov_b64_e32 v[88:89], 0
	v_mov_b64_e32 v[90:91], 0
	v_mov_b64_e32 v[92:93], 0
	v_mov_b64_e32 v[94:95], 0
	v_mov_b64_e32 v[96:97], 0
	v_mov_b64_e32 v[98:99], 0
	v_mov_b64_e32 v[100:101], 0
	v_mov_b64_e32 v[102:103], 0
	v_mov_b64_e32 v[104:105], 0
	v_mov_b64_e32 v[106:107], 0
	v_mov_b64_e32 v[108:109], 0
	v_mov_b64_e32 v[110:111], 0
	v_mov_b64_e32 v[112:113], 0
	v_mov_b64_e32 v[114:115], 0
	v_mov_b64_e32 v[116:117], 0
	v_mov_b64_e32 v[118:119], 0
	v_mov_b64_e32 v[120:121], 0
	v_mov_b64_e32 v[122:123], 0
	v_mov_b64_e32 v[124:125], 0
	v_mov_b64_e32 v[126:127], 0
.LBB0_1757:
	s_mov_b64 s[8:9], s[38:39]
	ds_read_b128 v[136:139], v183
	ds_read_b128 v[140:143], v183 offset:1024
	ds_read_b128 v[144:147], v183 offset:2048
	ds_read_b128 v[148:151], v183 offset:3072
	ds_read_b128 v[152:155], v184
	ds_read_b128 v[156:159], v184 offset:1024
	ds_read_b128 v[160:163], v184 offset:2048
	ds_read_b128 v[164:167], v184 offset:3072
	s_add_u32 s5, s16, s8
	s_addc_u32 s48, s17, s9
	s_add_u32 s40, s5, 0x100
	s_addc_u32 s41, s48, 0
	s_add_u32 s8, s36, s8
	s_addc_u32 s9, s37, s9
	s_add_u32 s8, s8, 0x100
	s_addc_u32 s9, s9, 0
	s_cmp_eq_u32 s60, s4
	s_cselect_b32 s43, s31, s41
	s_cselect_b32 s42, s30, s40
	s_cselect_b32 s41, s35, s9
	s_cselect_b32 s40, s34, s8
	s_add_u32 s8, s5, 0x160080
	s_addc_u32 s9, s48, 0
	v_lshl_add_u64 v[176:177], s[8:9], 0, v[128:129]
	s_add_i32 m0, s45, 0xc000
	ds_read_b128 v[168:171], v185
	ds_read_b128 v[172:175], v185 offset:1024
	ds_read_b128 v[186:189], v185 offset:2048
	ds_read_b128 v[190:193], v185 offset:3072
	ds_read_b128 v[194:197], v185 offset:4096
	ds_read_b128 v[198:201], v185 offset:5120
	ds_read_b128 v[202:205], v185 offset:6144
	ds_read_b128 v[206:209], v185 offset:7168
	global_load_lds_dwordx4 v[176:177], off
	v_lshl_add_u64 v[176:177], s[8:9], 0, v[130:131]
	s_add_i32 m0, s45, 0xe000
	s_nop 0
	global_load_lds_dwordx4 v[176:177], off
	s_waitcnt vmcnt(8)
	s_waitcnt lgkmcnt(0)
	s_barrier
	s_setprio 1
	v_mfma_f32_16x16x32_bf16 v[124:127], v[136:139], v[168:171], v[124:127]
	v_mfma_f32_16x16x32_bf16 v[120:123], v[144:147], v[168:171], v[120:123]
	v_mfma_f32_16x16x32_bf16 v[116:119], v[136:139], v[186:189], v[116:119]
	v_mfma_f32_16x16x32_bf16 v[112:115], v[144:147], v[186:189], v[112:115]
	v_mfma_f32_16x16x32_bf16 v[104:107], v[136:139], v[194:197], v[104:107]
	v_mfma_f32_16x16x32_bf16 v[96:99], v[144:147], v[194:197], v[96:99]
	v_mfma_f32_16x16x32_bf16 v[88:91], v[136:139], v[202:205], v[88:91]
	v_mfma_f32_16x16x32_bf16 v[80:83], v[144:147], v[202:205], v[80:83]
	v_mfma_f32_16x16x32_bf16 v[124:127], v[140:143], v[172:175], v[124:127]
	v_mfma_f32_16x16x32_bf16 v[120:123], v[148:151], v[172:175], v[120:123]
	v_mfma_f32_16x16x32_bf16 v[116:119], v[140:143], v[190:193], v[116:119]
	v_mfma_f32_16x16x32_bf16 v[112:115], v[148:151], v[190:193], v[112:115]
	v_mfma_f32_16x16x32_bf16 v[104:107], v[140:143], v[198:201], v[104:107]
	v_mfma_f32_16x16x32_bf16 v[96:99], v[148:151], v[198:201], v[96:99]
	v_mfma_f32_16x16x32_bf16 v[88:91], v[140:143], v[206:209], v[88:91]
	v_mfma_f32_16x16x32_bf16 v[80:83], v[148:151], v[206:209], v[80:83]
	s_setprio 0
	s_setprio 1
	v_mfma_f32_16x16x32_bf16 v[108:111], v[152:155], v[168:171], v[108:111]
	v_mfma_f32_16x16x32_bf16 v[100:103], v[160:163], v[168:171], v[100:103]
	v_mfma_f32_16x16x32_bf16 v[92:95], v[152:155], v[186:189], v[92:95]
	v_mfma_f32_16x16x32_bf16 v[84:87], v[160:163], v[186:189], v[84:87]
	v_mfma_f32_16x16x32_bf16 v[76:79], v[152:155], v[194:197], v[76:79]
	v_mfma_f32_16x16x32_bf16 v[72:75], v[160:163], v[194:197], v[72:75]
	v_mfma_f32_16x16x32_bf16 v[68:71], v[152:155], v[202:205], v[68:71]
	v_mfma_f32_16x16x32_bf16 v[64:67], v[160:163], v[202:205], v[64:67]
	v_mfma_f32_16x16x32_bf16 v[108:111], v[156:159], v[172:175], v[108:111]
	v_mfma_f32_16x16x32_bf16 v[100:103], v[164:167], v[172:175], v[100:103]
	v_mfma_f32_16x16x32_bf16 v[92:95], v[156:159], v[190:193], v[92:95]
	v_mfma_f32_16x16x32_bf16 v[84:87], v[164:167], v[190:193], v[84:87]
	v_mfma_f32_16x16x32_bf16 v[76:79], v[156:159], v[198:201], v[76:79]
	v_mfma_f32_16x16x32_bf16 v[72:75], v[164:167], v[198:201], v[72:75]
	v_mfma_f32_16x16x32_bf16 v[68:71], v[156:159], v[206:209], v[68:71]
	v_mfma_f32_16x16x32_bf16 v[64:67], v[164:167], v[206:209], v[64:67]
	s_setprio 0
	s_barrier
	s_add_i32 s5, s61, s44
	v_lshl_add_u64 v[176:177], s[40:41], 0, v[128:129]
	s_mov_b32 m0, s5
	ds_read_b128 v[168:171], v185 offset:16384
	ds_read_b128 v[172:175], v185 offset:17408
	ds_read_b128 v[186:189], v185 offset:18432
	ds_read_b128 v[190:193], v185 offset:19456
	ds_read_b128 v[194:197], v185 offset:20480
	ds_read_b128 v[198:201], v185 offset:21504
	ds_read_b128 v[202:205], v185 offset:22528
	ds_read_b128 v[206:209], v185 offset:23552
	global_load_lds_dwordx4 v[176:177], off
	s_add_i32 m0, s5, 0x2000
	s_add_u32 s8, s40, 0x160000
	v_lshl_add_u64 v[210:211], s[40:41], 0, v[130:131]
	s_addc_u32 s9, s41, 0
	s_add_i32 s5, s62, s44
	global_load_lds_dwordx4 v[210:211], off
	v_lshl_add_u64 v[212:213], s[8:9], 0, v[128:129]
	s_mov_b32 m0, s5
	v_lshl_add_u64 v[214:215], s[42:43], 0, v[130:131]
	global_load_lds_dwordx4 v[212:213], off
	v_lshl_add_u64 v[212:213], s[8:9], 0, v[130:131]
	s_add_i32 m0, s5, 0x2000
	s_nop 0
	global_load_lds_dwordx4 v[212:213], off
	v_lshl_add_u64 v[212:213], s[42:43], 0, v[128:129]
	s_mov_b32 m0, s45
	s_nop 0
	global_load_lds_dwordx4 v[212:213], off
	s_mov_b32 m0, s46
	s_nop 0
	global_load_lds_dwordx4 v[214:215], off
	s_waitcnt vmcnt(8)
	s_waitcnt lgkmcnt(0)
	s_barrier
	s_setprio 1
	v_mfma_f32_16x16x32_bf16 v[60:63], v[136:139], v[168:171], v[60:63]
	v_mfma_f32_16x16x32_bf16 v[56:59], v[144:147], v[168:171], v[56:59]
	v_mfma_f32_16x16x32_bf16 v[52:55], v[136:139], v[186:189], v[52:55]
	v_mfma_f32_16x16x32_bf16 v[48:51], v[144:147], v[186:189], v[48:51]
	v_mfma_f32_16x16x32_bf16 v[40:43], v[136:139], v[194:197], v[40:43]
	v_mfma_f32_16x16x32_bf16 v[32:35], v[144:147], v[194:197], v[32:35]
	v_mfma_f32_16x16x32_bf16 v[24:27], v[136:139], v[202:205], v[24:27]
	v_mfma_f32_16x16x32_bf16 v[16:19], v[144:147], v[202:205], v[16:19]
	v_mfma_f32_16x16x32_bf16 v[60:63], v[140:143], v[172:175], v[60:63]
	v_mfma_f32_16x16x32_bf16 v[56:59], v[148:151], v[172:175], v[56:59]
	v_mfma_f32_16x16x32_bf16 v[52:55], v[140:143], v[190:193], v[52:55]
	v_mfma_f32_16x16x32_bf16 v[48:51], v[148:151], v[190:193], v[48:51]
	v_mfma_f32_16x16x32_bf16 v[40:43], v[140:143], v[198:201], v[40:43]
	v_mfma_f32_16x16x32_bf16 v[32:35], v[148:151], v[198:201], v[32:35]
	v_mfma_f32_16x16x32_bf16 v[24:27], v[140:143], v[206:209], v[24:27]
	v_mfma_f32_16x16x32_bf16 v[16:19], v[148:151], v[206:209], v[16:19]
	s_setprio 0
	s_setprio 1
	v_mfma_f32_16x16x32_bf16 v[44:47], v[152:155], v[168:171], v[44:47]
	v_mfma_f32_16x16x32_bf16 v[36:39], v[160:163], v[168:171], v[36:39]
	v_mfma_f32_16x16x32_bf16 v[28:31], v[152:155], v[186:189], v[28:31]
	v_mfma_f32_16x16x32_bf16 v[20:23], v[160:163], v[186:189], v[20:23]
	v_mfma_f32_16x16x32_bf16 v[12:15], v[152:155], v[194:197], v[12:15]
	v_mfma_f32_16x16x32_bf16 v[8:11], v[160:163], v[194:197], v[8:11]
	v_mfma_f32_16x16x32_bf16 v[4:7], v[152:155], v[202:205], v[4:7]
	v_mfma_f32_16x16x32_bf16 v[0:3], v[160:163], v[202:205], v[0:3]
	v_mfma_f32_16x16x32_bf16 v[44:47], v[156:159], v[172:175], v[44:47]
	v_mfma_f32_16x16x32_bf16 v[36:39], v[164:167], v[172:175], v[36:39]
	v_mfma_f32_16x16x32_bf16 v[28:31], v[156:159], v[190:193], v[28:31]
	v_mfma_f32_16x16x32_bf16 v[20:23], v[164:167], v[190:193], v[20:23]
	v_mfma_f32_16x16x32_bf16 v[12:15], v[156:159], v[198:201], v[12:15]
	v_mfma_f32_16x16x32_bf16 v[8:11], v[164:167], v[198:201], v[8:11]
	v_mfma_f32_16x16x32_bf16 v[4:7], v[156:159], v[206:209], v[4:7]
	v_mfma_f32_16x16x32_bf16 v[0:3], v[164:167], v[206:209], v[0:3]
	s_setprio 0
	s_barrier
	s_add_i32 s5, 0, 0x18000
	v_add_u32_e32 v132, s5, v182
	s_add_i32 s48, 0, 0x1c000
	ds_read_b128 v[136:139], v132
	ds_read_b128 v[140:143], v132 offset:1024
	ds_read_b128 v[144:147], v132 offset:2048
	ds_read_b128 v[148:151], v132 offset:3072
	v_add_u32_e32 v132, s48, v182
	ds_read_b128 v[152:155], v132
	ds_read_b128 v[156:159], v132 offset:1024
	ds_read_b128 v[160:163], v132 offset:2048
	ds_read_b128 v[164:167], v132 offset:3072
	s_add_u32 s8, s42, 0x160000
	s_addc_u32 s9, s43, 0
	s_mov_b32 m0, s47
	v_lshl_add_u64 v[216:217], s[8:9], 0, v[128:129]
	ds_read_b128 v[168:171], v185 offset:32768
	ds_read_b128 v[172:175], v185 offset:33792
	ds_read_b128 v[186:189], v185 offset:34816
	ds_read_b128 v[190:193], v185 offset:35840
	ds_read_b128 v[194:197], v185 offset:36864
	ds_read_b128 v[198:201], v185 offset:37888
	ds_read_b128 v[202:205], v185 offset:38912
	ds_read_b128 v[206:209], v185 offset:39936
	global_load_lds_dwordx4 v[216:217], off
	v_lshl_add_u64 v[216:217], s[8:9], 0, v[130:131]
	s_mov_b32 m0, s52
	s_nop 0
	global_load_lds_dwordx4 v[216:217], off
	s_waitcnt vmcnt(8)
	s_waitcnt lgkmcnt(0)
	s_barrier
	s_setprio 1
	v_mfma_f32_16x16x32_bf16 v[124:127], v[136:139], v[168:171], v[124:127]
	v_mfma_f32_16x16x32_bf16 v[120:123], v[144:147], v[168:171], v[120:123]
	v_mfma_f32_16x16x32_bf16 v[116:119], v[136:139], v[186:189], v[116:119]
	v_mfma_f32_16x16x32_bf16 v[112:115], v[144:147], v[186:189], v[112:115]
	v_mfma_f32_16x16x32_bf16 v[104:107], v[136:139], v[194:197], v[104:107]
	v_mfma_f32_16x16x32_bf16 v[96:99], v[144:147], v[194:197], v[96:99]
	v_mfma_f32_16x16x32_bf16 v[88:91], v[136:139], v[202:205], v[88:91]
	v_mfma_f32_16x16x32_bf16 v[80:83], v[144:147], v[202:205], v[80:83]
	v_mfma_f32_16x16x32_bf16 v[124:127], v[140:143], v[172:175], v[124:127]
	v_mfma_f32_16x16x32_bf16 v[120:123], v[148:151], v[172:175], v[120:123]
	v_mfma_f32_16x16x32_bf16 v[116:119], v[140:143], v[190:193], v[116:119]
	v_mfma_f32_16x16x32_bf16 v[112:115], v[148:151], v[190:193], v[112:115]
	v_mfma_f32_16x16x32_bf16 v[104:107], v[140:143], v[198:201], v[104:107]
	v_mfma_f32_16x16x32_bf16 v[96:99], v[148:151], v[198:201], v[96:99]
	v_mfma_f32_16x16x32_bf16 v[88:91], v[140:143], v[206:209], v[88:91]
	v_mfma_f32_16x16x32_bf16 v[80:83], v[148:151], v[206:209], v[80:83]
	s_setprio 0
	s_setprio 1
	v_mfma_f32_16x16x32_bf16 v[108:111], v[152:155], v[168:171], v[108:111]
	v_mfma_f32_16x16x32_bf16 v[100:103], v[160:163], v[168:171], v[100:103]
	v_mfma_f32_16x16x32_bf16 v[92:95], v[152:155], v[186:189], v[92:95]
	v_mfma_f32_16x16x32_bf16 v[84:87], v[160:163], v[186:189], v[84:87]
	v_mfma_f32_16x16x32_bf16 v[76:79], v[152:155], v[194:197], v[76:79]
	v_mfma_f32_16x16x32_bf16 v[72:75], v[160:163], v[194:197], v[72:75]
	v_mfma_f32_16x16x32_bf16 v[68:71], v[152:155], v[202:205], v[68:71]
	v_mfma_f32_16x16x32_bf16 v[64:67], v[160:163], v[202:205], v[64:67]
	v_mfma_f32_16x16x32_bf16 v[108:111], v[156:159], v[172:175], v[108:111]
	v_mfma_f32_16x16x32_bf16 v[100:103], v[164:167], v[172:175], v[100:103]
	v_mfma_f32_16x16x32_bf16 v[92:95], v[156:159], v[190:193], v[92:95]
	v_mfma_f32_16x16x32_bf16 v[84:87], v[164:167], v[190:193], v[84:87]
	v_mfma_f32_16x16x32_bf16 v[76:79], v[156:159], v[198:201], v[76:79]
	v_mfma_f32_16x16x32_bf16 v[72:75], v[164:167], v[198:201], v[72:75]
	v_mfma_f32_16x16x32_bf16 v[68:71], v[156:159], v[206:209], v[68:71]
	v_mfma_f32_16x16x32_bf16 v[64:67], v[164:167], v[206:209], v[64:67]
	s_setprio 0
	s_barrier
	s_add_i32 s5, s5, s44
	v_lshl_add_u64 v[176:177], v[176:177], 0, s[14:15]
	s_mov_b32 m0, s5
	ds_read_b128 v[168:171], v185 offset:49152
	ds_read_b128 v[172:175], v185 offset:50176
	ds_read_b128 v[186:189], v185 offset:51200
	ds_read_b128 v[190:193], v185 offset:52224
	ds_read_b128 v[194:197], v185 offset:53248
	ds_read_b128 v[198:201], v185 offset:54272
	ds_read_b128 v[202:205], v185 offset:55296
	ds_read_b128 v[206:209], v185 offset:56320
	global_load_lds_dwordx4 v[176:177], off
	s_add_i32 m0, s5, 0x2000
	s_add_u32 s8, s40, 0x160080
	v_lshl_add_u64 v[176:177], v[210:211], 0, s[14:15]
	s_addc_u32 s9, s41, 0
	s_add_i32 s5, s48, s44
	global_load_lds_dwordx4 v[176:177], off
	v_lshl_add_u64 v[176:177], s[8:9], 0, v[128:129]
	s_mov_b32 m0, s5
	s_nop 0
	global_load_lds_dwordx4 v[176:177], off
	v_lshl_add_u64 v[176:177], s[8:9], 0, v[130:131]
	s_add_i32 m0, s5, 0x2000
	s_nop 0
	global_load_lds_dwordx4 v[176:177], off
	v_lshl_add_u64 v[176:177], v[212:213], 0, s[14:15]
	s_mov_b32 m0, s58
	s_nop 0
	global_load_lds_dwordx4 v[176:177], off
	v_lshl_add_u64 v[176:177], v[214:215], 0, s[14:15]
	s_mov_b32 m0, s59
	s_nop 0
	global_load_lds_dwordx4 v[176:177], off
	s_waitcnt vmcnt(8)
	s_waitcnt lgkmcnt(0)
	s_barrier
	s_setprio 1
	v_mfma_f32_16x16x32_bf16 v[60:63], v[136:139], v[168:171], v[60:63]
	v_mfma_f32_16x16x32_bf16 v[56:59], v[144:147], v[168:171], v[56:59]
	v_mfma_f32_16x16x32_bf16 v[52:55], v[136:139], v[186:189], v[52:55]
	v_mfma_f32_16x16x32_bf16 v[48:51], v[144:147], v[186:189], v[48:51]
	v_mfma_f32_16x16x32_bf16 v[40:43], v[136:139], v[194:197], v[40:43]
	v_mfma_f32_16x16x32_bf16 v[32:35], v[144:147], v[194:197], v[32:35]
	v_mfma_f32_16x16x32_bf16 v[24:27], v[136:139], v[202:205], v[24:27]
	v_mfma_f32_16x16x32_bf16 v[16:19], v[144:147], v[202:205], v[16:19]
	v_mfma_f32_16x16x32_bf16 v[60:63], v[140:143], v[172:175], v[60:63]
	v_mfma_f32_16x16x32_bf16 v[56:59], v[148:151], v[172:175], v[56:59]
	v_mfma_f32_16x16x32_bf16 v[52:55], v[140:143], v[190:193], v[52:55]
	v_mfma_f32_16x16x32_bf16 v[48:51], v[148:151], v[190:193], v[48:51]
	v_mfma_f32_16x16x32_bf16 v[40:43], v[140:143], v[198:201], v[40:43]
	v_mfma_f32_16x16x32_bf16 v[32:35], v[148:151], v[198:201], v[32:35]
	v_mfma_f32_16x16x32_bf16 v[24:27], v[140:143], v[206:209], v[24:27]
	v_mfma_f32_16x16x32_bf16 v[16:19], v[148:151], v[206:209], v[16:19]
	s_setprio 0
	s_setprio 1
	v_mfma_f32_16x16x32_bf16 v[44:47], v[152:155], v[168:171], v[44:47]
	v_mfma_f32_16x16x32_bf16 v[36:39], v[160:163], v[168:171], v[36:39]
	v_mfma_f32_16x16x32_bf16 v[28:31], v[152:155], v[186:189], v[28:31]
	v_mfma_f32_16x16x32_bf16 v[20:23], v[160:163], v[186:189], v[20:23]
	v_mfma_f32_16x16x32_bf16 v[12:15], v[152:155], v[194:197], v[12:15]
	v_mfma_f32_16x16x32_bf16 v[8:11], v[160:163], v[194:197], v[8:11]
	v_mfma_f32_16x16x32_bf16 v[4:7], v[152:155], v[202:205], v[4:7]
	v_mfma_f32_16x16x32_bf16 v[0:3], v[160:163], v[202:205], v[0:3]
	v_mfma_f32_16x16x32_bf16 v[44:47], v[156:159], v[172:175], v[44:47]
	v_mfma_f32_16x16x32_bf16 v[36:39], v[164:167], v[172:175], v[36:39]
	v_mfma_f32_16x16x32_bf16 v[28:31], v[156:159], v[190:193], v[28:31]
	v_mfma_f32_16x16x32_bf16 v[20:23], v[164:167], v[190:193], v[20:23]
	v_mfma_f32_16x16x32_bf16 v[12:15], v[156:159], v[198:201], v[12:15]
	v_mfma_f32_16x16x32_bf16 v[8:11], v[164:167], v[198:201], v[8:11]
	v_mfma_f32_16x16x32_bf16 v[4:7], v[156:159], v[206:209], v[4:7]
	v_mfma_f32_16x16x32_bf16 v[0:3], v[164:167], v[206:209], v[0:3]
	s_setprio 0
	s_barrier
	s_add_i32 s4, s4, 2
	s_add_u32 s38, s38, 0x100
	s_addc_u32 s39, s39, 0
	s_cmp_ge_i32 s4, s53
	s_cbranch_scc0 .LBB0_1757
	v_pk_add_f32 v[160:161], v[126:127], 0 op_sel_hi:[1,0]
	v_pk_add_f32 v[162:163], v[124:125], 0 op_sel_hi:[1,0]
	v_pk_add_f32 v[158:159], v[122:123], 0 op_sel_hi:[1,0]
	v_pk_add_f32 v[156:157], v[120:121], 0 op_sel_hi:[1,0]
	v_pk_add_f32 v[170:171], v[110:111], 0 op_sel_hi:[1,0]
	v_pk_add_f32 v[168:169], v[108:109], 0 op_sel_hi:[1,0]
	v_pk_add_f32 v[166:167], v[102:103], 0 op_sel_hi:[1,0]
	v_pk_add_f32 v[164:165], v[100:101], 0 op_sel_hi:[1,0]
	v_pk_add_f32 v[138:139], v[118:119], 0 op_sel_hi:[1,0]
	v_pk_add_f32 v[140:141], v[116:117], 0 op_sel_hi:[1,0]
	v_pk_add_f32 v[142:143], v[114:115], 0 op_sel_hi:[1,0]
	v_pk_add_f32 v[144:145], v[112:113], 0 op_sel_hi:[1,0]
	v_pk_add_f32 v[146:147], v[94:95], 0 op_sel_hi:[1,0]
	v_pk_add_f32 v[148:149], v[92:93], 0 op_sel_hi:[1,0]
	v_pk_add_f32 v[150:151], v[86:87], 0 op_sel_hi:[1,0]
	v_pk_add_f32 v[152:153], v[84:85], 0 op_sel_hi:[1,0]
	v_pk_add_f32 v[120:121], v[106:107], 0 op_sel_hi:[1,0]
	v_pk_add_f32 v[118:119], v[104:105], 0 op_sel_hi:[1,0]
	v_pk_add_f32 v[114:115], v[98:99], 0 op_sel_hi:[1,0]
	v_pk_add_f32 v[112:113], v[96:97], 0 op_sel_hi:[1,0]
	v_pk_add_f32 v[136:137], v[78:79], 0 op_sel_hi:[1,0]
	v_pk_add_f32 v[126:127], v[76:77], 0 op_sel_hi:[1,0]
	v_pk_add_f32 v[124:125], v[74:75], 0 op_sel_hi:[1,0]
	v_pk_add_f32 v[122:123], v[72:73], 0 op_sel_hi:[1,0]
	v_pk_add_f32 v[96:97], v[90:91], 0 op_sel_hi:[1,0]
	v_pk_add_f32 v[98:99], v[88:89], 0 op_sel_hi:[1,0]
	v_pk_add_f32 v[100:101], v[82:83], 0 op_sel_hi:[1,0]
	v_pk_add_f32 v[102:103], v[80:81], 0 op_sel_hi:[1,0]
	v_pk_add_f32 v[104:105], v[70:71], 0 op_sel_hi:[1,0]
	v_pk_add_f32 v[106:107], v[68:69], 0 op_sel_hi:[1,0]
	v_pk_add_f32 v[108:109], v[66:67], 0 op_sel_hi:[1,0]
	v_pk_add_f32 v[110:111], v[64:65], 0 op_sel_hi:[1,0]
	v_pk_add_f32 v[86:87], v[62:63], 0 op_sel_hi:[1,0]
	v_pk_add_f32 v[84:85], v[60:61], 0 op_sel_hi:[1,0]
	v_pk_add_f32 v[82:83], v[58:59], 0 op_sel_hi:[1,0]
	v_pk_add_f32 v[80:81], v[56:57], 0 op_sel_hi:[1,0]
	v_pk_add_f32 v[94:95], v[46:47], 0 op_sel_hi:[1,0]
	v_pk_add_f32 v[92:93], v[44:45], 0 op_sel_hi:[1,0]
	v_pk_add_f32 v[90:91], v[38:39], 0 op_sel_hi:[1,0]
	v_pk_add_f32 v[88:89], v[36:37], 0 op_sel_hi:[1,0]
	v_pk_add_f32 v[64:65], v[54:55], 0 op_sel_hi:[1,0]
	v_pk_add_f32 v[66:67], v[52:53], 0 op_sel_hi:[1,0]
	v_pk_add_f32 v[68:69], v[50:51], 0 op_sel_hi:[1,0]
	v_pk_add_f32 v[70:71], v[48:49], 0 op_sel_hi:[1,0]
	v_pk_add_f32 v[72:73], v[30:31], 0 op_sel_hi:[1,0]
	v_pk_add_f32 v[74:75], v[28:29], 0 op_sel_hi:[1,0]
	v_pk_add_f32 v[76:77], v[22:23], 0 op_sel_hi:[1,0]
	v_pk_add_f32 v[78:79], v[20:21], 0 op_sel_hi:[1,0]
	v_pk_add_f32 v[54:55], v[42:43], 0 op_sel_hi:[1,0]
	v_pk_add_f32 v[52:53], v[40:41], 0 op_sel_hi:[1,0]
	v_pk_add_f32 v[50:51], v[34:35], 0 op_sel_hi:[1,0]
	v_pk_add_f32 v[48:49], v[32:33], 0 op_sel_hi:[1,0]
	v_pk_add_f32 v[62:63], v[14:15], 0 op_sel_hi:[1,0]
	v_pk_add_f32 v[60:61], v[12:13], 0 op_sel_hi:[1,0]
	v_pk_add_f32 v[58:59], v[10:11], 0 op_sel_hi:[1,0]
	v_pk_add_f32 v[56:57], v[8:9], 0 op_sel_hi:[1,0]
	v_pk_add_f32 v[32:33], v[26:27], 0 op_sel_hi:[1,0]
	v_pk_add_f32 v[34:35], v[24:25], 0 op_sel_hi:[1,0]
	v_pk_add_f32 v[36:37], v[18:19], 0 op_sel_hi:[1,0]
	v_pk_add_f32 v[38:39], v[16:17], 0 op_sel_hi:[1,0]
	v_pk_add_f32 v[40:41], v[6:7], 0 op_sel_hi:[1,0]
	v_pk_add_f32 v[42:43], v[4:5], 0 op_sel_hi:[1,0]
	v_pk_add_f32 v[44:45], v[2:3], 0 op_sel_hi:[1,0]
	v_pk_add_f32 v[46:47], v[0:1], 0 op_sel_hi:[1,0]

.LBB0_1789:
	s_mov_b64 s[14:15], s[12:13]
	ds_read_b128 v[140:143], v134
	ds_read_b128 v[144:147], v134 offset:1024
	ds_read_b128 v[148:151], v134 offset:2048
	ds_read_b128 v[152:155], v134 offset:3072
	ds_read_b128 v[156:159], v135
	ds_read_b128 v[160:163], v135 offset:1024
	ds_read_b128 v[164:167], v135 offset:2048
	ds_read_b128 v[168:171], v135 offset:3072
	s_add_u32 s44, s2, s14
	s_addc_u32 s45, s3, s15
	s_add_u32 s16, s44, 0x100
	s_addc_u32 s17, s45, 0
	s_add_u32 s14, s0, s14
	s_addc_u32 s15, s1, s15
	s_add_u32 s14, s14, 0x100
	s_addc_u32 s15, s15, 0
	s_cmp_eq_u32 s31, s33
	s_cselect_b32 s17, s9, s17
	s_cselect_b32 s16, s8, s16
	s_cselect_b32 s15, s11, s15
	s_cselect_b32 s14, s10, s14
	s_add_u32 s44, s44, 0x160080
	s_addc_u32 s45, s45, 0
	s_mov_b32 m0, s34
	v_lshl_add_u64 v[206:207], s[44:45], 0, v[128:129]
	ds_read_b128 v[172:175], v136
	ds_read_b128 v[176:179], v136 offset:1024
	ds_read_b128 v[182:185], v136 offset:2048
	ds_read_b128 v[186:189], v136 offset:3072
	ds_read_b128 v[190:193], v136 offset:4096
	ds_read_b128 v[194:197], v136 offset:5120
	ds_read_b128 v[198:201], v136 offset:6144
	ds_read_b128 v[202:205], v136 offset:7168
	global_load_lds_dwordx4 v[206:207], off
	v_lshl_add_u64 v[206:207], s[44:45], 0, v[130:131]
	s_mov_b32 m0, s35
	s_nop 0
	global_load_lds_dwordx4 v[206:207], off
	s_waitcnt vmcnt(8)
	s_waitcnt lgkmcnt(0)
	s_barrier
	s_setprio 1
	v_mfma_f32_16x16x32_bf16 v[124:127], v[140:143], v[172:175], v[124:127]
	v_mfma_f32_16x16x32_bf16 v[120:123], v[148:151], v[172:175], v[120:123]
	v_mfma_f32_16x16x32_bf16 v[108:111], v[140:143], v[182:185], v[108:111]
	v_mfma_f32_16x16x32_bf16 v[104:107], v[148:151], v[182:185], v[104:107]
	v_mfma_f32_16x16x32_bf16 v[92:95], v[140:143], v[190:193], v[92:95]
	v_mfma_f32_16x16x32_bf16 v[88:91], v[148:151], v[190:193], v[88:91]
	v_mfma_f32_16x16x32_bf16 v[76:79], v[140:143], v[198:201], v[76:79]
	v_mfma_f32_16x16x32_bf16 v[72:75], v[148:151], v[198:201], v[72:75]
	v_mfma_f32_16x16x32_bf16 v[124:127], v[144:147], v[176:179], v[124:127]
	v_mfma_f32_16x16x32_bf16 v[120:123], v[152:155], v[176:179], v[120:123]
	v_mfma_f32_16x16x32_bf16 v[108:111], v[144:147], v[186:189], v[108:111]
	v_mfma_f32_16x16x32_bf16 v[104:107], v[152:155], v[186:189], v[104:107]
	v_mfma_f32_16x16x32_bf16 v[92:95], v[144:147], v[194:197], v[92:95]
	v_mfma_f32_16x16x32_bf16 v[88:91], v[152:155], v[194:197], v[88:91]
	v_mfma_f32_16x16x32_bf16 v[76:79], v[144:147], v[202:205], v[76:79]
	v_mfma_f32_16x16x32_bf16 v[72:75], v[152:155], v[202:205], v[72:75]
	s_setprio 0
	s_setprio 1
	v_mfma_f32_16x16x32_bf16 v[116:119], v[156:159], v[172:175], v[116:119]
	v_mfma_f32_16x16x32_bf16 v[112:115], v[164:167], v[172:175], v[112:115]
	v_mfma_f32_16x16x32_bf16 v[100:103], v[156:159], v[182:185], v[100:103]
	v_mfma_f32_16x16x32_bf16 v[96:99], v[164:167], v[182:185], v[96:99]
	v_mfma_f32_16x16x32_bf16 v[84:87], v[156:159], v[190:193], v[84:87]
	v_mfma_f32_16x16x32_bf16 v[80:83], v[164:167], v[190:193], v[80:83]
	v_mfma_f32_16x16x32_bf16 v[68:71], v[156:159], v[198:201], v[68:71]
	v_mfma_f32_16x16x32_bf16 v[64:67], v[164:167], v[198:201], v[64:67]
	v_mfma_f32_16x16x32_bf16 v[116:119], v[160:163], v[176:179], v[116:119]
	v_mfma_f32_16x16x32_bf16 v[112:115], v[168:171], v[176:179], v[112:115]
	v_mfma_f32_16x16x32_bf16 v[100:103], v[160:163], v[186:189], v[100:103]
	v_mfma_f32_16x16x32_bf16 v[96:99], v[168:171], v[186:189], v[96:99]
	v_mfma_f32_16x16x32_bf16 v[84:87], v[160:163], v[194:197], v[84:87]
	v_mfma_f32_16x16x32_bf16 v[80:83], v[168:171], v[194:197], v[80:83]
	v_mfma_f32_16x16x32_bf16 v[68:71], v[160:163], v[202:205], v[68:71]
	v_mfma_f32_16x16x32_bf16 v[64:67], v[168:171], v[202:205], v[64:67]
	s_setprio 0
	s_barrier
	s_mov_b32 m0, s36
	v_lshl_add_u64 v[206:207], s[14:15], 0, v[128:129]
	s_add_u32 s44, s14, 0x160000
	ds_read_b128 v[172:175], v136 offset:16384
	ds_read_b128 v[176:179], v136 offset:17408
	ds_read_b128 v[182:185], v136 offset:18432
	ds_read_b128 v[186:189], v136 offset:19456
	ds_read_b128 v[190:193], v136 offset:20480
	ds_read_b128 v[194:197], v136 offset:21504
	ds_read_b128 v[198:201], v136 offset:22528
	ds_read_b128 v[202:205], v136 offset:23552
	global_load_lds_dwordx4 v[206:207], off
	v_lshl_add_u64 v[208:209], s[14:15], 0, v[130:131]
	s_mov_b32 m0, s37
	s_addc_u32 s45, s15, 0
	global_load_lds_dwordx4 v[208:209], off
	v_lshl_add_u64 v[210:211], s[44:45], 0, v[128:129]
	s_mov_b32 m0, s38
	v_lshl_add_u64 v[212:213], s[16:17], 0, v[130:131]
	global_load_lds_dwordx4 v[210:211], off
	v_lshl_add_u64 v[210:211], s[44:45], 0, v[130:131]
	s_mov_b32 m0, s39
	s_nop 0
	global_load_lds_dwordx4 v[210:211], off
	v_lshl_add_u64 v[210:211], s[16:17], 0, v[128:129]
	s_mov_b32 m0, s20
	s_nop 0
	global_load_lds_dwordx4 v[210:211], off
	s_mov_b32 m0, s21
	s_nop 0
	global_load_lds_dwordx4 v[212:213], off
	s_waitcnt vmcnt(8)
	s_waitcnt lgkmcnt(0)
	s_barrier
	s_setprio 1
	v_mfma_f32_16x16x32_bf16 v[60:63], v[140:143], v[172:175], v[60:63]
	v_mfma_f32_16x16x32_bf16 v[56:59], v[148:151], v[172:175], v[56:59]
	v_mfma_f32_16x16x32_bf16 v[44:47], v[140:143], v[182:185], v[44:47]
	v_mfma_f32_16x16x32_bf16 v[40:43], v[148:151], v[182:185], v[40:43]
	v_mfma_f32_16x16x32_bf16 v[28:31], v[140:143], v[190:193], v[28:31]
	v_mfma_f32_16x16x32_bf16 v[24:27], v[148:151], v[190:193], v[24:27]
	v_mfma_f32_16x16x32_bf16 v[12:15], v[140:143], v[198:201], v[12:15]
	v_mfma_f32_16x16x32_bf16 v[8:11], v[148:151], v[198:201], v[8:11]
	v_mfma_f32_16x16x32_bf16 v[60:63], v[144:147], v[176:179], v[60:63]
	v_mfma_f32_16x16x32_bf16 v[56:59], v[152:155], v[176:179], v[56:59]
	v_mfma_f32_16x16x32_bf16 v[44:47], v[144:147], v[186:189], v[44:47]
	v_mfma_f32_16x16x32_bf16 v[40:43], v[152:155], v[186:189], v[40:43]
	v_mfma_f32_16x16x32_bf16 v[28:31], v[144:147], v[194:197], v[28:31]
	v_mfma_f32_16x16x32_bf16 v[24:27], v[152:155], v[194:197], v[24:27]
	v_mfma_f32_16x16x32_bf16 v[12:15], v[144:147], v[202:205], v[12:15]
	v_mfma_f32_16x16x32_bf16 v[8:11], v[152:155], v[202:205], v[8:11]
	s_setprio 0
	s_setprio 1
	v_mfma_f32_16x16x32_bf16 v[52:55], v[156:159], v[172:175], v[52:55]
	v_mfma_f32_16x16x32_bf16 v[48:51], v[164:167], v[172:175], v[48:51]
	v_mfma_f32_16x16x32_bf16 v[36:39], v[156:159], v[182:185], v[36:39]
	v_mfma_f32_16x16x32_bf16 v[32:35], v[164:167], v[182:185], v[32:35]
	v_mfma_f32_16x16x32_bf16 v[20:23], v[156:159], v[190:193], v[20:23]
	v_mfma_f32_16x16x32_bf16 v[16:19], v[164:167], v[190:193], v[16:19]
	v_mfma_f32_16x16x32_bf16 v[4:7], v[156:159], v[198:201], v[4:7]
	v_mfma_f32_16x16x32_bf16 v[0:3], v[164:167], v[198:201], v[0:3]
	v_mfma_f32_16x16x32_bf16 v[52:55], v[160:163], v[176:179], v[52:55]
	v_mfma_f32_16x16x32_bf16 v[48:51], v[168:171], v[176:179], v[48:51]
	v_mfma_f32_16x16x32_bf16 v[36:39], v[160:163], v[186:189], v[36:39]
	v_mfma_f32_16x16x32_bf16 v[32:35], v[168:171], v[186:189], v[32:35]
	v_mfma_f32_16x16x32_bf16 v[20:23], v[160:163], v[194:197], v[20:23]
	v_mfma_f32_16x16x32_bf16 v[16:19], v[168:171], v[194:197], v[16:19]
	v_mfma_f32_16x16x32_bf16 v[4:7], v[160:163], v[202:205], v[4:7]
	v_mfma_f32_16x16x32_bf16 v[0:3], v[168:171], v[202:205], v[0:3]
	s_setprio 0
	s_barrier
	ds_read_b128 v[140:143], v137
	ds_read_b128 v[144:147], v137 offset:1024
	ds_read_b128 v[148:151], v137 offset:2048
	ds_read_b128 v[152:155], v137 offset:3072
	ds_read_b128 v[156:159], v138
	ds_read_b128 v[160:163], v138 offset:1024
	ds_read_b128 v[164:167], v138 offset:2048
	ds_read_b128 v[168:171], v138 offset:3072
	s_add_u32 s16, s16, 0x160000
	s_addc_u32 s17, s17, 0
	s_mov_b32 m0, s22
	v_lshl_add_u64 v[214:215], s[16:17], 0, v[128:129]
	ds_read_b128 v[172:175], v136 offset:32768
	ds_read_b128 v[176:179], v136 offset:33792
	ds_read_b128 v[182:185], v136 offset:34816
	ds_read_b128 v[186:189], v136 offset:35840
	ds_read_b128 v[190:193], v136 offset:36864
	ds_read_b128 v[194:197], v136 offset:37888
	ds_read_b128 v[198:201], v136 offset:38912
	ds_read_b128 v[202:205], v136 offset:39936
	global_load_lds_dwordx4 v[214:215], off
	v_lshl_add_u64 v[214:215], s[16:17], 0, v[130:131]
	s_mov_b32 m0, s23
	s_nop 0
	global_load_lds_dwordx4 v[214:215], off
	s_waitcnt vmcnt(8)
	s_waitcnt lgkmcnt(0)
	s_barrier
	s_setprio 1
	v_mfma_f32_16x16x32_bf16 v[124:127], v[140:143], v[172:175], v[124:127]
	v_mfma_f32_16x16x32_bf16 v[120:123], v[148:151], v[172:175], v[120:123]
	v_mfma_f32_16x16x32_bf16 v[108:111], v[140:143], v[182:185], v[108:111]
	v_mfma_f32_16x16x32_bf16 v[104:107], v[148:151], v[182:185], v[104:107]
	v_mfma_f32_16x16x32_bf16 v[92:95], v[140:143], v[190:193], v[92:95]
	v_mfma_f32_16x16x32_bf16 v[88:91], v[148:151], v[190:193], v[88:91]
	v_mfma_f32_16x16x32_bf16 v[76:79], v[140:143], v[198:201], v[76:79]
	v_mfma_f32_16x16x32_bf16 v[72:75], v[148:151], v[198:201], v[72:75]
	v_mfma_f32_16x16x32_bf16 v[124:127], v[144:147], v[176:179], v[124:127]
	v_mfma_f32_16x16x32_bf16 v[120:123], v[152:155], v[176:179], v[120:123]
	v_mfma_f32_16x16x32_bf16 v[108:111], v[144:147], v[186:189], v[108:111]
	v_mfma_f32_16x16x32_bf16 v[104:107], v[152:155], v[186:189], v[104:107]
	v_mfma_f32_16x16x32_bf16 v[92:95], v[144:147], v[194:197], v[92:95]
	v_mfma_f32_16x16x32_bf16 v[88:91], v[152:155], v[194:197], v[88:91]
	v_mfma_f32_16x16x32_bf16 v[76:79], v[144:147], v[202:205], v[76:79]
	v_mfma_f32_16x16x32_bf16 v[72:75], v[152:155], v[202:205], v[72:75]
	s_setprio 0
	s_setprio 1
	v_mfma_f32_16x16x32_bf16 v[116:119], v[156:159], v[172:175], v[116:119]
	v_mfma_f32_16x16x32_bf16 v[112:115], v[164:167], v[172:175], v[112:115]
	v_mfma_f32_16x16x32_bf16 v[100:103], v[156:159], v[182:185], v[100:103]
	v_mfma_f32_16x16x32_bf16 v[96:99], v[164:167], v[182:185], v[96:99]
	v_mfma_f32_16x16x32_bf16 v[84:87], v[156:159], v[190:193], v[84:87]
	v_mfma_f32_16x16x32_bf16 v[80:83], v[164:167], v[190:193], v[80:83]
	v_mfma_f32_16x16x32_bf16 v[68:71], v[156:159], v[198:201], v[68:71]
	v_mfma_f32_16x16x32_bf16 v[64:67], v[164:167], v[198:201], v[64:67]
	v_mfma_f32_16x16x32_bf16 v[116:119], v[160:163], v[176:179], v[116:119]
	v_mfma_f32_16x16x32_bf16 v[112:115], v[168:171], v[176:179], v[112:115]
	v_mfma_f32_16x16x32_bf16 v[100:103], v[160:163], v[186:189], v[100:103]
	v_mfma_f32_16x16x32_bf16 v[96:99], v[168:171], v[186:189], v[96:99]
	v_mfma_f32_16x16x32_bf16 v[84:87], v[160:163], v[194:197], v[84:87]
	v_mfma_f32_16x16x32_bf16 v[80:83], v[168:171], v[194:197], v[80:83]
	v_mfma_f32_16x16x32_bf16 v[68:71], v[160:163], v[202:205], v[68:71]
	v_mfma_f32_16x16x32_bf16 v[64:67], v[168:171], v[202:205], v[64:67]
	s_setprio 0
	s_barrier
	s_mov_b32 m0, s40
	v_lshl_add_u64 v[206:207], v[206:207], 0, s[6:7]
	s_add_u32 s14, s14, 0x160080
	ds_read_b128 v[172:175], v136 offset:49152
	ds_read_b128 v[176:179], v136 offset:50176
	ds_read_b128 v[182:185], v136 offset:51200
	ds_read_b128 v[186:189], v136 offset:52224
	ds_read_b128 v[190:193], v136 offset:53248
	ds_read_b128 v[194:197], v136 offset:54272
	ds_read_b128 v[198:201], v136 offset:55296
	ds_read_b128 v[202:205], v136 offset:56320
	global_load_lds_dwordx4 v[206:207], off
	v_lshl_add_u64 v[206:207], v[208:209], 0, s[6:7]
	s_mov_b32 m0, s41
	s_addc_u32 s15, s15, 0
	global_load_lds_dwordx4 v[206:207], off
	v_lshl_add_u64 v[206:207], s[14:15], 0, v[128:129]
	s_mov_b32 m0, s42
	s_nop 0
	global_load_lds_dwordx4 v[206:207], off
	v_lshl_add_u64 v[206:207], s[14:15], 0, v[130:131]
	s_mov_b32 m0, s43
	s_nop 0
	global_load_lds_dwordx4 v[206:207], off
	v_lshl_add_u64 v[206:207], v[210:211], 0, s[6:7]
	s_mov_b32 m0, s28
	s_nop 0
	global_load_lds_dwordx4 v[206:207], off
	v_lshl_add_u64 v[206:207], v[212:213], 0, s[6:7]
	s_mov_b32 m0, s29
	s_nop 0
	global_load_lds_dwordx4 v[206:207], off
	s_waitcnt vmcnt(8)
	s_waitcnt lgkmcnt(0)
	s_barrier
	s_setprio 1
	v_mfma_f32_16x16x32_bf16 v[60:63], v[140:143], v[172:175], v[60:63]
	v_mfma_f32_16x16x32_bf16 v[56:59], v[148:151], v[172:175], v[56:59]
	v_mfma_f32_16x16x32_bf16 v[44:47], v[140:143], v[182:185], v[44:47]
	v_mfma_f32_16x16x32_bf16 v[40:43], v[148:151], v[182:185], v[40:43]
	v_mfma_f32_16x16x32_bf16 v[28:31], v[140:143], v[190:193], v[28:31]
	v_mfma_f32_16x16x32_bf16 v[24:27], v[148:151], v[190:193], v[24:27]
	v_mfma_f32_16x16x32_bf16 v[12:15], v[140:143], v[198:201], v[12:15]
	v_mfma_f32_16x16x32_bf16 v[8:11], v[148:151], v[198:201], v[8:11]
	v_mfma_f32_16x16x32_bf16 v[60:63], v[144:147], v[176:179], v[60:63]
	v_mfma_f32_16x16x32_bf16 v[56:59], v[152:155], v[176:179], v[56:59]
	v_mfma_f32_16x16x32_bf16 v[44:47], v[144:147], v[186:189], v[44:47]
	v_mfma_f32_16x16x32_bf16 v[40:43], v[152:155], v[186:189], v[40:43]
	v_mfma_f32_16x16x32_bf16 v[28:31], v[144:147], v[194:197], v[28:31]
	v_mfma_f32_16x16x32_bf16 v[24:27], v[152:155], v[194:197], v[24:27]
	v_mfma_f32_16x16x32_bf16 v[12:15], v[144:147], v[202:205], v[12:15]
	v_mfma_f32_16x16x32_bf16 v[8:11], v[152:155], v[202:205], v[8:11]
	s_setprio 0
	s_setprio 1
	v_mfma_f32_16x16x32_bf16 v[52:55], v[156:159], v[172:175], v[52:55]
	v_mfma_f32_16x16x32_bf16 v[48:51], v[164:167], v[172:175], v[48:51]
	v_mfma_f32_16x16x32_bf16 v[36:39], v[156:159], v[182:185], v[36:39]
	v_mfma_f32_16x16x32_bf16 v[32:35], v[164:167], v[182:185], v[32:35]
	v_mfma_f32_16x16x32_bf16 v[20:23], v[156:159], v[190:193], v[20:23]
	v_mfma_f32_16x16x32_bf16 v[16:19], v[164:167], v[190:193], v[16:19]
	v_mfma_f32_16x16x32_bf16 v[4:7], v[156:159], v[198:201], v[4:7]
	v_mfma_f32_16x16x32_bf16 v[0:3], v[164:167], v[198:201], v[0:3]
	v_mfma_f32_16x16x32_bf16 v[52:55], v[160:163], v[176:179], v[52:55]
	v_mfma_f32_16x16x32_bf16 v[48:51], v[168:171], v[176:179], v[48:51]
	v_mfma_f32_16x16x32_bf16 v[36:39], v[160:163], v[186:189], v[36:39]
	v_mfma_f32_16x16x32_bf16 v[32:35], v[168:171], v[186:189], v[32:35]
	v_mfma_f32_16x16x32_bf16 v[20:23], v[160:163], v[194:197], v[20:23]
	v_mfma_f32_16x16x32_bf16 v[16:19], v[168:171], v[194:197], v[16:19]
	v_mfma_f32_16x16x32_bf16 v[4:7], v[160:163], v[202:205], v[4:7]
	v_mfma_f32_16x16x32_bf16 v[0:3], v[168:171], v[202:205], v[0:3]
	s_setprio 0
	s_barrier
	s_add_i32 s33, s33, 2
	s_add_u32 s12, s12, 0x100
	s_addc_u32 s13, s13, 0
	s_cmp_ge_i32 s33, s30
	s_cbranch_scc0 .LBB0_1789
	v_mov_b32_e32 v129, v127
